# private intermediate blocks laid out step-major (unit, step, wave, lane): each workgroup touches one contiguous 16/32 KiB span per row-step
# baseline (speedup 1.0000x reference)
;     __device__ __forceinline__ void operator()(const i32x4 (&acc)[2][2][4][2], const Unit& uu, int wr, int wc, int fr, int fq) const {
;         Unit u = uu; u.pn += pn0;
;         const int row0 = u.pm * BM + wr * 64 + fr, cl = wc * 32 + 8 * fq;
;         bf16_t* base; int ldc, colt; bool sg = false;
;         if (u.pn < 18) { base = QKV; ldc = 4608; colt = u.pn * 256; }
;         else if (u.pn < 44) { base = Z; ldc = 6656; colt = (u.pn - 18) * 256; }
;         else { base = GT; ldc = 8192; colt = (u.pn - 44) * 256; sg = true; }
;         const int col0 = colt + cl;
.LBB0_610:
	s_lshl_b32 s98, s6, 5
	s_add_i32 s98, s98, s30
	s_lshl_b32 s98, s98, 17
	v_and_b32_e32 v248, 63, v0
	v_lshlrev_b32_e32 v248, 4, v248
	v_lshrrev_b32_e32 v249, 6, v0
	v_lshl_add_u32 v248, v249, 11, v248
	v_add_u32_e32 v248, s98, v248
	v_mov_b32_e32 v249, 0
	v_lshl_add_u64 v[248:249], s[12:13], 0, v[248:249]
	s_add_i32 s7, s30, 44
	v_mov_b32_e32 v58, v0
	s_cmpk_gt_i32 s30, 0xffe5
	s_mov_b64 s[40:41], -1
	s_cbranch_scc0 .LBB0_616
	s_lshl_b32 s38, s7, 8
	s_cmp_lt_u32 s30, 0xffffffd4
	s_mov_b64 s[36:37], -1
	s_mov_b64 s[30:31], -1
	s_cbranch_scc0 .LBB0_613
	s_add_i32 s9, s38, 0xffffd400
	s_mov_b64 s[30:31], 0

; __device__ __forceinline__ u32x4 pack8(const f32x4 v0, const f32x4 v1) { u32x4 w; w.x = cvt_pk_bf16(v0[0], v0[1]); w.y = cvt_pk_bf16(v0[2], v0[3]); w.z = cvt_pk_bf16(v1[0], v1[1]); w.w = cvt_pk_bf16(v1[2], v1[3]); return w; }
; __device__ __forceinline__ f32x4 sig4(const f32x4 v) { return (f32x4){sigmoidf_(v[0]), sigmoidf_(v[1]), sigmoidf_(v[2]), sigmoidf_(v[3])}; }
; __device__ __forceinline__ float sigmoidf_(float x) { return __builtin_amdgcn_rcpf(1.0f + __builtin_amdgcn_exp2f(-1.4426950408889634f * x)); }
;     __device__ __forceinline__ void operator()(const i32x4 (&acc)[2][2][4][2], const Unit& uu, int wr, int wc, int fr, int fq) const {
;     ...
;         for (int ai = 0; ai < 2; ++ai)
; #pragma unroll
;             for (int m = 0; m < 4; ++m) { const int r = row0 + ai * HALF + m * 16; const float rs = rsv[ai][m]; bf16_t* rowp = base + (size_t)r * ldc + col0;
; #pragma unroll
;                 for (int bj = 0; bj < 2; ++bj) { f32x4 v0 = __builtin_convertvector(acc[ai][bj][m][0], f32x4) * rs * sv[bj][0], v1 = __builtin_convertvector(acc[ai][bj][m][1], f32x4) * rs * sv[bj][1];
;                     if (sg) { v0 = sig4(v0); v1 = sig4(v1); }
;                     *(u32x4*)(rowp + bj * HALF) = pack8(v0, v1); } }
.LBB0_624:
	v_cvt_f32_i32_e32 v119, v119
	v_cvt_f32_i32_e32 v121, v121
	v_cvt_f32_i32_e32 v120, v120
	v_cvt_f32_i32_e32 v118, v118
	v_cvt_f32_i32_e32 v115, v115
	v_cvt_f32_i32_e32 v117, v117
	v_cvt_f32_i32_e32 v116, v116
	v_cvt_f32_i32_e32 v114, v114
	v_mul_lo_u32 v134, s3, v168
	v_mul_lo_u32 v135, s2, v169
	v_mad_u64_u32 v[122:123], s[30:31], s2, v168, 0
	v_mov_b32_e32 v131, v130
	v_add3_u32 v123, v123, v135, v134
	s_nop 0
	v_cvt_pk_bf16_f32 v134, v126, v127
	s_nop 0
	v_cvt_pk_bf16_f32 v135, v124, v125
	v_mov_b32_e32 v124, v130
	v_mov_b32_e32 v125, v130
	v_pk_mul_f32 v[120:121], v[124:125], v[120:121]
	v_pk_mul_f32 v[126:127], v[130:131], v[118:119]
	v_pk_mul_f32 v[116:117], v[124:125], v[116:117]
	v_pk_mul_f32 v[114:115], v[130:131], v[114:115]
	s_mov_b64 s[98:99], 0x4000
	v_lshl_add_u64 v[122:123], v[248:249], 0, s[98:99]
	v_pk_mul_f32 v[118:119], v[64:65], v[120:121]
	v_pk_mul_f32 v[120:121], v[62:63], v[126:127]
	v_pk_mul_f32 v[116:117], v[60:61], v[116:117]
	s_and_b64 vcc, exec, s[6:7]
	v_pk_mul_f32 v[124:125], v[58:59], v[114:115]
	s_nop 0
	v_cvt_pk_bf16_f32 v136, v132, v133
	s_nop 0
	v_cvt_pk_bf16_f32 v137, v128, v129
	global_store_dwordx4 v[122:123], v[134:137], off
	s_cbranch_vccnz .LBB0_626
	v_mul_f32_e32 v114, 0xbfb8aa3b, v120
	v_exp_f32_e32 v114, v114
	v_mul_f32_e32 v115, 0xbfb8aa3b, v121
	v_exp_f32_e32 v115, v115
	v_add_f32_e32 v114, 1.0, v114
	v_rcp_f32_e32 v120, v114
	v_mul_f32_e32 v114, 0xbfb8aa3b, v118
	v_add_f32_e32 v115, 1.0, v115
	v_exp_f32_e32 v114, v114
	v_mul_f32_e32 v118, 0xbfb8aa3b, v119
	v_exp_f32_e32 v119, v118
	v_rcp_f32_e32 v121, v115
	v_mul_f32_e32 v115, 0xbfb8aa3b, v124
	v_exp_f32_e32 v115, v115
	v_add_f32_e32 v114, 1.0, v114
	v_rcp_f32_e32 v118, v114
	v_add_f32_e32 v114, 1.0, v119
	v_mul_f32_e32 v119, 0xbfb8aa3b, v125
	v_exp_f32_e32 v125, v119
	v_rcp_f32_e32 v119, v114
	v_add_f32_e32 v114, 1.0, v115
	v_mul_f32_e32 v115, 0xbfb8aa3b, v116
	v_exp_f32_e32 v115, v115
	v_mul_f32_e32 v116, 0xbfb8aa3b, v117
	v_exp_f32_e32 v117, v116
	v_rcp_f32_e32 v124, v114
	v_add_f32_e32 v114, 1.0, v125
	v_rcp_f32_e32 v125, v114
	v_add_f32_e32 v114, 1.0, v115
	v_rcp_f32_e32 v116, v114
	v_add_f32_e32 v114, 1.0, v117
	v_rcp_f32_e32 v117, v114

; __device__ __forceinline__ u32x4 pack8(const f32x4 v0, const f32x4 v1) { u32x4 w; w.x = cvt_pk_bf16(v0[0], v0[1]); w.y = cvt_pk_bf16(v0[2], v0[3]); w.z = cvt_pk_bf16(v1[0], v1[1]); w.w = cvt_pk_bf16(v1[2], v1[3]); return w; }
; __device__ __forceinline__ f32x4 sig4(const f32x4 v) { return (f32x4){sigmoidf_(v[0]), sigmoidf_(v[1]), sigmoidf_(v[2]), sigmoidf_(v[3])}; }
; __device__ __forceinline__ float sigmoidf_(float x) { return __builtin_amdgcn_rcpf(1.0f + __builtin_amdgcn_exp2f(-1.4426950408889634f * x)); }
;     __device__ __forceinline__ void operator()(const i32x4 (&acc)[2][2][4][2], const Unit& uu, int wr, int wc, int fr, int fq) const {
;     ...
;         for (int ai = 0; ai < 2; ++ai)
; #pragma unroll
;             for (int m = 0; m < 4; ++m) { const int r = row0 + ai * HALF + m * 16; const float rs = rsv[ai][m]; bf16_t* rowp = base + (size_t)r * ldc + col0;
; #pragma unroll
;                 for (int bj = 0; bj < 2; ++bj) { f32x4 v0 = __builtin_convertvector(acc[ai][bj][m][0], f32x4) * rs * sv[bj][0], v1 = __builtin_convertvector(acc[ai][bj][m][1], f32x4) * rs * sv[bj][1];
;                     if (sg) { v0 = sig4(v0); v1 = sig4(v1); }
;                     *(u32x4*)(rowp + bj * HALF) = pack8(v0, v1); } }
.LBB0_628:
	v_cvt_f32_i32_e32 v103, v103
	v_cvt_f32_i32_e32 v105, v105
	v_cvt_f32_i32_e32 v104, v104
	v_cvt_f32_i32_e32 v102, v102
	v_cvt_f32_i32_e32 v99, v99
	v_cvt_f32_i32_e32 v101, v101
	v_cvt_f32_i32_e32 v100, v100
	v_cvt_f32_i32_e32 v98, v98
	v_mul_lo_u32 v118, s3, v166
	v_mul_lo_u32 v119, s2, v167
	v_mad_u64_u32 v[106:107], s[30:31], s2, v166, 0
	v_mov_b32_e32 v115, v114
	v_add3_u32 v107, v107, v119, v118
	s_nop 0
	v_cvt_pk_bf16_f32 v118, v110, v111
	s_nop 0
	v_cvt_pk_bf16_f32 v119, v108, v109
	v_mov_b32_e32 v108, v114
	v_mov_b32_e32 v109, v114
	v_pk_mul_f32 v[104:105], v[108:109], v[104:105]
	v_pk_mul_f32 v[110:111], v[114:115], v[102:103]
	v_pk_mul_f32 v[100:101], v[108:109], v[100:101]
	v_pk_mul_f32 v[98:99], v[114:115], v[98:99]
	s_mov_b64 s[98:99], 0x8000
	v_lshl_add_u64 v[106:107], v[248:249], 0, s[98:99]
	v_pk_mul_f32 v[102:103], v[64:65], v[104:105]
	v_pk_mul_f32 v[104:105], v[62:63], v[110:111]
	v_pk_mul_f32 v[100:101], v[60:61], v[100:101]
	s_and_b64 vcc, exec, s[6:7]
	v_pk_mul_f32 v[108:109], v[58:59], v[98:99]
	s_nop 0
	v_cvt_pk_bf16_f32 v120, v116, v117
	s_nop 0
	v_cvt_pk_bf16_f32 v121, v112, v113
	global_store_dwordx4 v[106:107], v[118:121], off
	s_cbranch_vccnz .LBB0_630
	v_mul_f32_e32 v98, 0xbfb8aa3b, v104
	v_exp_f32_e32 v98, v98
	v_mul_f32_e32 v99, 0xbfb8aa3b, v105
	v_exp_f32_e32 v99, v99
	v_add_f32_e32 v98, 1.0, v98
	v_rcp_f32_e32 v104, v98
	v_mul_f32_e32 v98, 0xbfb8aa3b, v102
	v_add_f32_e32 v99, 1.0, v99
	v_exp_f32_e32 v98, v98
	v_mul_f32_e32 v102, 0xbfb8aa3b, v103
	v_exp_f32_e32 v103, v102
	v_rcp_f32_e32 v105, v99
	v_mul_f32_e32 v99, 0xbfb8aa3b, v108
	v_exp_f32_e32 v99, v99
	v_add_f32_e32 v98, 1.0, v98
	v_rcp_f32_e32 v102, v98
	v_add_f32_e32 v98, 1.0, v103
	v_mul_f32_e32 v103, 0xbfb8aa3b, v109
	v_exp_f32_e32 v109, v103
	v_rcp_f32_e32 v103, v98
	v_add_f32_e32 v98, 1.0, v99
	v_mul_f32_e32 v99, 0xbfb8aa3b, v100
	v_exp_f32_e32 v99, v99
	v_mul_f32_e32 v100, 0xbfb8aa3b, v101
	v_exp_f32_e32 v101, v100
	v_rcp_f32_e32 v108, v98
	v_add_f32_e32 v98, 1.0, v109
	v_rcp_f32_e32 v109, v98
	v_add_f32_e32 v98, 1.0, v99
	v_rcp_f32_e32 v100, v98
	v_add_f32_e32 v98, 1.0, v101
	v_rcp_f32_e32 v101, v98

; __device__ __forceinline__ u32x4 pack8(const f32x4 v0, const f32x4 v1) { u32x4 w; w.x = cvt_pk_bf16(v0[0], v0[1]); w.y = cvt_pk_bf16(v0[2], v0[3]); w.z = cvt_pk_bf16(v1[0], v1[1]); w.w = cvt_pk_bf16(v1[2], v1[3]); return w; }
; __device__ __forceinline__ f32x4 sig4(const f32x4 v) { return (f32x4){sigmoidf_(v[0]), sigmoidf_(v[1]), sigmoidf_(v[2]), sigmoidf_(v[3])}; }
; __device__ __forceinline__ float sigmoidf_(float x) { return __builtin_amdgcn_rcpf(1.0f + __builtin_amdgcn_exp2f(-1.4426950408889634f * x)); }
;     __device__ __forceinline__ void operator()(const i32x4 (&acc)[2][2][4][2], const Unit& uu, int wr, int wc, int fr, int fq) const {
;     ...
;         for (int ai = 0; ai < 2; ++ai)
; #pragma unroll
;             for (int m = 0; m < 4; ++m) { const int r = row0 + ai * HALF + m * 16; const float rs = rsv[ai][m]; bf16_t* rowp = base + (size_t)r * ldc + col0;
; #pragma unroll
;                 for (int bj = 0; bj < 2; ++bj) { f32x4 v0 = __builtin_convertvector(acc[ai][bj][m][0], f32x4) * rs * sv[bj][0], v1 = __builtin_convertvector(acc[ai][bj][m][1], f32x4) * rs * sv[bj][1];
;                     if (sg) { v0 = sig4(v0); v1 = sig4(v1); }
;                     *(u32x4*)(rowp + bj * HALF) = pack8(v0, v1); } }
.LBB0_632:
	v_cvt_f32_i32_e32 v87, v87
	v_cvt_f32_i32_e32 v89, v89
	v_cvt_f32_i32_e32 v88, v88
	v_cvt_f32_i32_e32 v86, v86
	v_cvt_f32_i32_e32 v83, v83
	v_cvt_f32_i32_e32 v85, v85
	v_cvt_f32_i32_e32 v84, v84
	v_cvt_f32_i32_e32 v82, v82
	v_mul_lo_u32 v102, s3, v164
	v_mul_lo_u32 v103, s2, v165
	v_mad_u64_u32 v[90:91], s[30:31], s2, v164, 0
	v_mov_b32_e32 v99, v98
	v_add3_u32 v91, v91, v103, v102
	s_nop 0
	v_cvt_pk_bf16_f32 v102, v94, v95
	s_nop 0
	v_cvt_pk_bf16_f32 v103, v92, v93
	v_mov_b32_e32 v92, v98
	v_mov_b32_e32 v93, v98
	v_pk_mul_f32 v[88:89], v[92:93], v[88:89]
	v_pk_mul_f32 v[94:95], v[98:99], v[86:87]
	v_pk_mul_f32 v[84:85], v[92:93], v[84:85]
	v_pk_mul_f32 v[82:83], v[98:99], v[82:83]
	s_mov_b64 s[98:99], 0xc000
	v_lshl_add_u64 v[90:91], v[248:249], 0, s[98:99]
	v_pk_mul_f32 v[86:87], v[64:65], v[88:89]
	v_pk_mul_f32 v[88:89], v[62:63], v[94:95]
	v_pk_mul_f32 v[84:85], v[60:61], v[84:85]
	s_and_b64 vcc, exec, s[6:7]
	v_pk_mul_f32 v[92:93], v[58:59], v[82:83]
	s_nop 0
	v_cvt_pk_bf16_f32 v104, v100, v101
	s_nop 0
	v_cvt_pk_bf16_f32 v105, v96, v97
	global_store_dwordx4 v[90:91], v[102:105], off
	s_cbranch_vccnz .LBB0_634
	v_mul_f32_e32 v82, 0xbfb8aa3b, v88
	v_exp_f32_e32 v82, v82
	v_mul_f32_e32 v83, 0xbfb8aa3b, v89
	v_exp_f32_e32 v83, v83
	v_add_f32_e32 v82, 1.0, v82
	v_rcp_f32_e32 v88, v82
	v_mul_f32_e32 v82, 0xbfb8aa3b, v86
	v_add_f32_e32 v83, 1.0, v83
	v_exp_f32_e32 v82, v82
	v_mul_f32_e32 v86, 0xbfb8aa3b, v87
	v_exp_f32_e32 v87, v86
	v_rcp_f32_e32 v89, v83
	v_mul_f32_e32 v83, 0xbfb8aa3b, v92
	v_exp_f32_e32 v83, v83
	v_add_f32_e32 v82, 1.0, v82
	v_rcp_f32_e32 v86, v82
	v_add_f32_e32 v82, 1.0, v87
	v_mul_f32_e32 v87, 0xbfb8aa3b, v93
	v_exp_f32_e32 v93, v87
	v_rcp_f32_e32 v87, v82
	v_add_f32_e32 v82, 1.0, v83
	v_mul_f32_e32 v83, 0xbfb8aa3b, v84
	v_exp_f32_e32 v83, v83
	v_mul_f32_e32 v84, 0xbfb8aa3b, v85
	v_exp_f32_e32 v85, v84
	v_rcp_f32_e32 v92, v82
	v_add_f32_e32 v82, 1.0, v93
	v_rcp_f32_e32 v93, v82
	v_add_f32_e32 v82, 1.0, v83
	v_rcp_f32_e32 v84, v82
	v_add_f32_e32 v82, 1.0, v85
	v_rcp_f32_e32 v85, v82

; __device__ __forceinline__ u32x4 pack8(const f32x4 v0, const f32x4 v1) { u32x4 w; w.x = cvt_pk_bf16(v0[0], v0[1]); w.y = cvt_pk_bf16(v0[2], v0[3]); w.z = cvt_pk_bf16(v1[0], v1[1]); w.w = cvt_pk_bf16(v1[2], v1[3]); return w; }
; __device__ __forceinline__ f32x4 sig4(const f32x4 v) { return (f32x4){sigmoidf_(v[0]), sigmoidf_(v[1]), sigmoidf_(v[2]), sigmoidf_(v[3])}; }
; __device__ __forceinline__ float sigmoidf_(float x) { return __builtin_amdgcn_rcpf(1.0f + __builtin_amdgcn_exp2f(-1.4426950408889634f * x)); }
;     __device__ __forceinline__ void operator()(const i32x4 (&acc)[2][2][4][2], const Unit& uu, int wr, int wc, int fr, int fq) const {
;     ...
;         for (int ai = 0; ai < 2; ++ai)
; #pragma unroll
;             for (int m = 0; m < 4; ++m) { const int r = row0 + ai * HALF + m * 16; const float rs = rsv[ai][m]; bf16_t* rowp = base + (size_t)r * ldc + col0;
; #pragma unroll
;                 for (int bj = 0; bj < 2; ++bj) { f32x4 v0 = __builtin_convertvector(acc[ai][bj][m][0], f32x4) * rs * sv[bj][0], v1 = __builtin_convertvector(acc[ai][bj][m][1], f32x4) * rs * sv[bj][1];
;                     if (sg) { v0 = sig4(v0); v1 = sig4(v1); }
;                     *(u32x4*)(rowp + bj * HALF) = pack8(v0, v1); } }
.LBB0_636:
	v_add_u32_e32 v66, 0x80, v162
	v_cvt_f32_i32_e32 v55, v55
	v_cvt_f32_i32_e32 v57, v57
	v_cvt_f32_i32_e32 v56, v56
	v_cvt_f32_i32_e32 v54, v54
	v_cvt_f32_i32_e32 v51, v51
	v_cvt_f32_i32_e32 v53, v53
	v_cvt_f32_i32_e32 v52, v52
	v_cvt_f32_i32_e32 v50, v50
	v_ashrrev_i32_e32 v67, 31, v66
	v_mul_lo_u32 v86, s2, v67
	v_mul_lo_u32 v87, s3, v66
	v_mad_u64_u32 v[66:67], s[30:31], s2, v66, 0
	v_mov_b32_e32 v83, v82
	v_add3_u32 v67, v67, v86, v87
	s_nop 0
	v_cvt_pk_bf16_f32 v86, v70, v71
	s_nop 0
	v_cvt_pk_bf16_f32 v87, v68, v69
	v_mov_b32_e32 v68, v82
	v_mov_b32_e32 v69, v82
	v_pk_mul_f32 v[56:57], v[68:69], v[56:57]
	v_pk_mul_f32 v[70:71], v[82:83], v[54:55]
	v_pk_mul_f32 v[52:53], v[68:69], v[52:53]
	v_pk_mul_f32 v[50:51], v[82:83], v[50:51]
	s_mov_b64 s[98:99], 0x10000
	v_lshl_add_u64 v[66:67], v[248:249], 0, s[98:99]
	v_pk_mul_f32 v[54:55], v[64:65], v[56:57]
	v_pk_mul_f32 v[56:57], v[62:63], v[70:71]
	v_pk_mul_f32 v[52:53], v[60:61], v[52:53]
	s_and_b64 vcc, exec, s[6:7]
	v_pk_mul_f32 v[68:69], v[58:59], v[50:51]
	s_nop 0
	v_cvt_pk_bf16_f32 v88, v84, v85
	s_nop 0
	v_cvt_pk_bf16_f32 v89, v72, v73
	global_store_dwordx4 v[66:67], v[86:89], off
	s_cbranch_vccnz .LBB0_638
	v_mul_f32_e32 v50, 0xbfb8aa3b, v56
	v_exp_f32_e32 v50, v50
	v_mul_f32_e32 v51, 0xbfb8aa3b, v57
	v_exp_f32_e32 v51, v51
	v_add_f32_e32 v50, 1.0, v50
	v_rcp_f32_e32 v56, v50
	v_mul_f32_e32 v50, 0xbfb8aa3b, v54
	v_add_f32_e32 v51, 1.0, v51
	v_exp_f32_e32 v50, v50
	v_mul_f32_e32 v54, 0xbfb8aa3b, v55
	v_exp_f32_e32 v55, v54
	v_rcp_f32_e32 v57, v51
	v_mul_f32_e32 v51, 0xbfb8aa3b, v68
	v_exp_f32_e32 v51, v51
	v_add_f32_e32 v50, 1.0, v50
	v_rcp_f32_e32 v54, v50
	v_add_f32_e32 v50, 1.0, v55
	v_mul_f32_e32 v55, 0xbfb8aa3b, v69
	v_exp_f32_e32 v69, v55
	v_rcp_f32_e32 v55, v50
	v_add_f32_e32 v50, 1.0, v51
	v_mul_f32_e32 v51, 0xbfb8aa3b, v52
	v_exp_f32_e32 v51, v51
	v_mul_f32_e32 v52, 0xbfb8aa3b, v53
	v_exp_f32_e32 v53, v52
	v_rcp_f32_e32 v68, v50
	v_add_f32_e32 v50, 1.0, v69
	v_rcp_f32_e32 v69, v50
	v_add_f32_e32 v50, 1.0, v51
	v_rcp_f32_e32 v52, v50
	v_add_f32_e32 v50, 1.0, v53
	v_rcp_f32_e32 v53, v50

; __device__ __forceinline__ u32x4 pack8(const f32x4 v0, const f32x4 v1) { u32x4 w; w.x = cvt_pk_bf16(v0[0], v0[1]); w.y = cvt_pk_bf16(v0[2], v0[3]); w.z = cvt_pk_bf16(v1[0], v1[1]); w.w = cvt_pk_bf16(v1[2], v1[3]); return w; }
; __device__ __forceinline__ f32x4 sig4(const f32x4 v) { return (f32x4){sigmoidf_(v[0]), sigmoidf_(v[1]), sigmoidf_(v[2]), sigmoidf_(v[3])}; }
; __device__ __forceinline__ float sigmoidf_(float x) { return __builtin_amdgcn_rcpf(1.0f + __builtin_amdgcn_exp2f(-1.4426950408889634f * x)); }
;     __device__ __forceinline__ void operator()(const i32x4 (&acc)[2][2][4][2], const Unit& uu, int wr, int wc, int fr, int fq) const {
;     ...
;         for (int ai = 0; ai < 2; ++ai)
; #pragma unroll
;             for (int m = 0; m < 4; ++m) { const int r = row0 + ai * HALF + m * 16; const float rs = rsv[ai][m]; bf16_t* rowp = base + (size_t)r * ldc + col0;
; #pragma unroll
;                 for (int bj = 0; bj < 2; ++bj) { f32x4 v0 = __builtin_convertvector(acc[ai][bj][m][0], f32x4) * rs * sv[bj][0], v1 = __builtin_convertvector(acc[ai][bj][m][1], f32x4) * rs * sv[bj][1];
;                     if (sg) { v0 = sig4(v0); v1 = sig4(v1); }
;                     *(u32x4*)(rowp + bj * HALF) = pack8(v0, v1); } }
.LBB0_640:
	v_add_u32_e32 v42, 0x90, v162
	v_cvt_f32_i32_e32 v39, v39
	v_cvt_f32_i32_e32 v41, v41
	v_cvt_f32_i32_e32 v40, v40
	v_cvt_f32_i32_e32 v38, v38
	v_cvt_f32_i32_e32 v35, v35
	v_cvt_f32_i32_e32 v37, v37
	v_cvt_f32_i32_e32 v36, v36
	v_cvt_f32_i32_e32 v34, v34
	v_ashrrev_i32_e32 v43, 31, v42
	v_mul_lo_u32 v54, s2, v43
	v_mul_lo_u32 v55, s3, v42
	v_mad_u64_u32 v[42:43], s[30:31], s2, v42, 0
	v_mov_b32_e32 v51, v50
	v_add3_u32 v43, v43, v54, v55
	s_nop 0
	v_cvt_pk_bf16_f32 v54, v46, v47
	s_nop 0
	v_cvt_pk_bf16_f32 v55, v44, v45
	v_mov_b32_e32 v44, v50
	v_mov_b32_e32 v45, v50
	v_pk_mul_f32 v[40:41], v[44:45], v[40:41]
	v_pk_mul_f32 v[46:47], v[50:51], v[38:39]
	v_pk_mul_f32 v[36:37], v[44:45], v[36:37]
	v_pk_mul_f32 v[34:35], v[50:51], v[34:35]
	s_mov_b64 s[98:99], 0x14000
	v_lshl_add_u64 v[42:43], v[248:249], 0, s[98:99]
	v_pk_mul_f32 v[38:39], v[64:65], v[40:41]
	v_pk_mul_f32 v[40:41], v[62:63], v[46:47]
	v_pk_mul_f32 v[36:37], v[60:61], v[36:37]
	s_and_b64 vcc, exec, s[6:7]
	v_pk_mul_f32 v[44:45], v[58:59], v[34:35]
	s_nop 0
	v_cvt_pk_bf16_f32 v56, v52, v53
	s_nop 0
	v_cvt_pk_bf16_f32 v57, v48, v49
	global_store_dwordx4 v[42:43], v[54:57], off
	s_cbranch_vccnz .LBB0_642
	v_mul_f32_e32 v34, 0xbfb8aa3b, v40
	v_exp_f32_e32 v34, v34
	v_mul_f32_e32 v35, 0xbfb8aa3b, v41
	v_exp_f32_e32 v35, v35
	v_add_f32_e32 v34, 1.0, v34
	v_rcp_f32_e32 v40, v34
	v_mul_f32_e32 v34, 0xbfb8aa3b, v38
	v_add_f32_e32 v35, 1.0, v35
	v_exp_f32_e32 v34, v34
	v_mul_f32_e32 v38, 0xbfb8aa3b, v39
	v_exp_f32_e32 v39, v38
	v_rcp_f32_e32 v41, v35
	v_mul_f32_e32 v35, 0xbfb8aa3b, v44
	v_exp_f32_e32 v35, v35
	v_add_f32_e32 v34, 1.0, v34
	v_rcp_f32_e32 v38, v34
	v_add_f32_e32 v34, 1.0, v39
	v_mul_f32_e32 v39, 0xbfb8aa3b, v45
	v_exp_f32_e32 v45, v39
	v_rcp_f32_e32 v39, v34
	v_add_f32_e32 v34, 1.0, v35
	v_mul_f32_e32 v35, 0xbfb8aa3b, v36
	v_exp_f32_e32 v35, v35
	v_mul_f32_e32 v36, 0xbfb8aa3b, v37
	v_exp_f32_e32 v37, v36
	v_rcp_f32_e32 v44, v34
	v_add_f32_e32 v34, 1.0, v45
	v_rcp_f32_e32 v45, v34
	v_add_f32_e32 v34, 1.0, v35
	v_rcp_f32_e32 v36, v34
	v_add_f32_e32 v34, 1.0, v37
	v_rcp_f32_e32 v37, v34

; __device__ __forceinline__ u32x4 pack8(const f32x4 v0, const f32x4 v1) { u32x4 w; w.x = cvt_pk_bf16(v0[0], v0[1]); w.y = cvt_pk_bf16(v0[2], v0[3]); w.z = cvt_pk_bf16(v1[0], v1[1]); w.w = cvt_pk_bf16(v1[2], v1[3]); return w; }
; __device__ __forceinline__ f32x4 sig4(const f32x4 v) { return (f32x4){sigmoidf_(v[0]), sigmoidf_(v[1]), sigmoidf_(v[2]), sigmoidf_(v[3])}; }
; __device__ __forceinline__ float sigmoidf_(float x) { return __builtin_amdgcn_rcpf(1.0f + __builtin_amdgcn_exp2f(-1.4426950408889634f * x)); }
;     __device__ __forceinline__ void operator()(const i32x4 (&acc)[2][2][4][2], const Unit& uu, int wr, int wc, int fr, int fq) const {
;     ...
;         for (int ai = 0; ai < 2; ++ai)
; #pragma unroll
;             for (int m = 0; m < 4; ++m) { const int r = row0 + ai * HALF + m * 16; const float rs = rsv[ai][m]; bf16_t* rowp = base + (size_t)r * ldc + col0;
; #pragma unroll
;                 for (int bj = 0; bj < 2; ++bj) { f32x4 v0 = __builtin_convertvector(acc[ai][bj][m][0], f32x4) * rs * sv[bj][0], v1 = __builtin_convertvector(acc[ai][bj][m][1], f32x4) * rs * sv[bj][1];
;                     if (sg) { v0 = sig4(v0); v1 = sig4(v1); }
;                     *(u32x4*)(rowp + bj * HALF) = pack8(v0, v1); } }
.LBB0_644:
	v_add_u32_e32 v26, 0xa0, v162
	v_cvt_f32_i32_e32 v23, v23
	v_cvt_f32_i32_e32 v25, v25
	v_cvt_f32_i32_e32 v24, v24
	v_cvt_f32_i32_e32 v22, v22
	v_cvt_f32_i32_e32 v19, v19
	v_cvt_f32_i32_e32 v21, v21
	v_cvt_f32_i32_e32 v20, v20
	v_cvt_f32_i32_e32 v18, v18
	v_ashrrev_i32_e32 v27, 31, v26
	v_mul_lo_u32 v38, s2, v27
	v_mul_lo_u32 v39, s3, v26
	v_mad_u64_u32 v[26:27], s[30:31], s2, v26, 0
	v_mov_b32_e32 v35, v34
	v_add3_u32 v27, v27, v38, v39
	s_nop 0
	v_cvt_pk_bf16_f32 v38, v30, v31
	s_nop 0
	v_cvt_pk_bf16_f32 v39, v28, v29
	v_mov_b32_e32 v28, v34
	v_mov_b32_e32 v29, v34
	v_pk_mul_f32 v[24:25], v[28:29], v[24:25]
	v_pk_mul_f32 v[30:31], v[34:35], v[22:23]
	v_pk_mul_f32 v[20:21], v[28:29], v[20:21]
	v_pk_mul_f32 v[18:19], v[34:35], v[18:19]
	s_mov_b64 s[98:99], 0x18000
	v_lshl_add_u64 v[26:27], v[248:249], 0, s[98:99]
	v_pk_mul_f32 v[22:23], v[64:65], v[24:25]
	v_pk_mul_f32 v[24:25], v[62:63], v[30:31]
	v_pk_mul_f32 v[20:21], v[60:61], v[20:21]
	s_and_b64 vcc, exec, s[6:7]
	v_pk_mul_f32 v[28:29], v[58:59], v[18:19]
	s_nop 0
	v_cvt_pk_bf16_f32 v40, v36, v37
	s_nop 0
	v_cvt_pk_bf16_f32 v41, v32, v33
	global_store_dwordx4 v[26:27], v[38:41], off
	s_cbranch_vccnz .LBB0_646
	v_mul_f32_e32 v18, 0xbfb8aa3b, v24
	v_exp_f32_e32 v18, v18
	v_mul_f32_e32 v19, 0xbfb8aa3b, v25
	v_exp_f32_e32 v19, v19
	v_add_f32_e32 v18, 1.0, v18
	v_rcp_f32_e32 v24, v18
	v_mul_f32_e32 v18, 0xbfb8aa3b, v22
	v_add_f32_e32 v19, 1.0, v19
	v_exp_f32_e32 v18, v18
	v_mul_f32_e32 v22, 0xbfb8aa3b, v23
	v_exp_f32_e32 v23, v22
	v_rcp_f32_e32 v25, v19
	v_mul_f32_e32 v19, 0xbfb8aa3b, v28
	v_exp_f32_e32 v19, v19
	v_add_f32_e32 v18, 1.0, v18
	v_rcp_f32_e32 v22, v18
	v_add_f32_e32 v18, 1.0, v23
	v_mul_f32_e32 v23, 0xbfb8aa3b, v29
	v_exp_f32_e32 v29, v23
	v_rcp_f32_e32 v23, v18
	v_add_f32_e32 v18, 1.0, v19
	v_mul_f32_e32 v19, 0xbfb8aa3b, v20
	v_exp_f32_e32 v19, v19
	v_mul_f32_e32 v20, 0xbfb8aa3b, v21
	v_exp_f32_e32 v21, v20
	v_rcp_f32_e32 v28, v18
	v_add_f32_e32 v18, 1.0, v29
	v_rcp_f32_e32 v29, v18
	v_add_f32_e32 v18, 1.0, v19
	v_rcp_f32_e32 v20, v18
	v_add_f32_e32 v18, 1.0, v21
	v_rcp_f32_e32 v21, v18

; __device__ __forceinline__ u32x4 pack8(const f32x4 v0, const f32x4 v1) { u32x4 w; w.x = cvt_pk_bf16(v0[0], v0[1]); w.y = cvt_pk_bf16(v0[2], v0[3]); w.z = cvt_pk_bf16(v1[0], v1[1]); w.w = cvt_pk_bf16(v1[2], v1[3]); return w; }
; __device__ __forceinline__ f32x4 sig4(const f32x4 v) { return (f32x4){sigmoidf_(v[0]), sigmoidf_(v[1]), sigmoidf_(v[2]), sigmoidf_(v[3])}; }
; __device__ __forceinline__ float sigmoidf_(float x) { return __builtin_amdgcn_rcpf(1.0f + __builtin_amdgcn_exp2f(-1.4426950408889634f * x)); }
;     __device__ __forceinline__ void operator()(const i32x4 (&acc)[2][2][4][2], const Unit& uu, int wr, int wc, int fr, int fq) const {
;     ...
;         for (int ai = 0; ai < 2; ++ai)
; #pragma unroll
;             for (int m = 0; m < 4; ++m) { const int r = row0 + ai * HALF + m * 16; const float rs = rsv[ai][m]; bf16_t* rowp = base + (size_t)r * ldc + col0;
; #pragma unroll
;                 for (int bj = 0; bj < 2; ++bj) { f32x4 v0 = __builtin_convertvector(acc[ai][bj][m][0], f32x4) * rs * sv[bj][0], v1 = __builtin_convertvector(acc[ai][bj][m][1], f32x4) * rs * sv[bj][1];
;                     if (sg) { v0 = sig4(v0); v1 = sig4(v1); }
;                     *(u32x4*)(rowp + bj * HALF) = pack8(v0, v1); } }
.LBB0_648:
	v_add_u32_e32 v10, 0xb0, v162
	v_ashrrev_i32_e32 v11, 31, v10
	v_mul_lo_u32 v22, s2, v11
	v_mul_lo_u32 v23, s3, v10
	v_mad_u64_u32 v[10:11], s[2:3], s2, v10, 0
	v_cvt_f32_i32_e32 v7, v7
	v_cvt_f32_i32_e32 v9, v9
	v_cvt_f32_i32_e32 v8, v8
	v_cvt_f32_i32_e32 v6, v6
	v_add3_u32 v11, v11, v22, v23
	s_nop 0
	v_cvt_pk_bf16_f32 v22, v14, v15
	s_nop 0
	v_cvt_pk_bf16_f32 v23, v12, v13
	s_nop 0
	v_cvt_pk_bf16_f32 v24, v20, v21
	s_nop 0
	v_cvt_pk_bf16_f32 v25, v16, v17
	v_cvt_f32_i32_e32 v15, v3
	v_cvt_f32_i32_e32 v17, v5
	v_cvt_f32_i32_e32 v16, v4
	v_cvt_f32_i32_e32 v14, v2
	v_mov_b32_e32 v19, v18
	v_mov_b32_e32 v12, v18
	v_mov_b32_e32 v13, v18
	v_pk_mul_f32 v[8:9], v[12:13], v[8:9]
	v_pk_mul_f32 v[6:7], v[18:19], v[6:7]
	v_pk_mul_f32 v[2:3], v[64:65], v[8:9]
	v_pk_mul_f32 v[4:5], v[62:63], v[6:7]
	v_pk_mul_f32 v[6:7], v[12:13], v[16:17]
	v_pk_mul_f32 v[8:9], v[18:19], v[14:15]
	s_mov_b64 s[98:99], 0x1c000
	v_lshl_add_u64 v[10:11], v[248:249], 0, s[98:99]
	v_pk_mul_f32 v[6:7], v[60:61], v[6:7]
	s_and_b64 vcc, exec, s[6:7]
	v_pk_mul_f32 v[8:9], v[58:59], v[8:9]
	global_store_dwordx4 v[10:11], v[22:25], off
	s_cbranch_vccnz .LBB0_650
	v_mul_f32_e32 v4, 0xbfb8aa3b, v4
	v_mul_f32_e32 v5, 0xbfb8aa3b, v5
	v_mul_f32_e32 v2, 0xbfb8aa3b, v2
	v_mul_f32_e32 v3, 0xbfb8aa3b, v3
	v_mul_f32_e32 v8, 0xbfb8aa3b, v8
	v_mul_f32_e32 v9, 0xbfb8aa3b, v9
	v_mul_f32_e32 v6, 0xbfb8aa3b, v6
	v_mul_f32_e32 v7, 0xbfb8aa3b, v7
	v_exp_f32_e32 v4, v4
	v_exp_f32_e32 v5, v5
	v_exp_f32_e32 v2, v2
	v_exp_f32_e32 v3, v3
	v_exp_f32_e32 v8, v8
	v_exp_f32_e32 v9, v9
	v_exp_f32_e32 v6, v6
	v_exp_f32_e32 v7, v7
	v_add_f32_e32 v4, 1.0, v4
	v_add_f32_e32 v5, 1.0, v5
	v_add_f32_e32 v2, 1.0, v2
	v_add_f32_e32 v3, 1.0, v3
	v_add_f32_e32 v8, 1.0, v8
	v_add_f32_e32 v9, 1.0, v9
	v_add_f32_e32 v6, 1.0, v6
	v_add_f32_e32 v7, 1.0, v7
	v_rcp_f32_e32 v4, v4
	v_rcp_f32_e32 v5, v5
	v_rcp_f32_e32 v2, v2
	v_rcp_f32_e32 v3, v3
	v_rcp_f32_e32 v8, v8
	v_rcp_f32_e32 v9, v9
	v_rcp_f32_e32 v6, v6
	v_rcp_f32_e32 v7, v7

;     __device__ __forceinline__ void load_row(RowIn& R, int r, int col0) const {
; #pragma unroll
;         for (int bj = 0; bj < 2; ++bj) {
;             if (MODE == 2) R.g[bj] = *(const u32x4*)(GT + (size_t)r * 8192 + col0 + bj * HALF);
;             if (MODE == 3) { R.g[bj] = *(const u32x4*)(GT + (size_t)r * 8192 + 4096 + col0 + bj * HALF); R.a[bj] = *(const u32x4*)(AD + (size_t)r * 4096 + col0 + bj * HALF); } }
;     }
;     __device__ __forceinline__ void operator()(AccRef acc, const Unit& u, int wr, int wc, int fr, int fq) const {
;         const int row0 = u.pm * BM + wr * 64 + fr, col0 = u.pn * BM + wc * 32 + 8 * fq;
;         RowIn cur, nxt;
;         if (MODE >= 2) load_row(cur, row0, col0);
; #pragma unroll
;         for (int s = 0; s < 8; ++s) { const int ai = s >> 2, m = s & 3; const int r = row0 + ai * HALF + m * 16; bf16_t* rowp = O + (size_t)r * ldc + col0;
;                 if (MODE >= 2 && s + 1 < 8) load_row(nxt, row0 + ((s + 1) >> 2) * HALF + ((s + 1) & 3) * 16, col0);
;                 float rs = 1.f; if (MODE == 1) rs = __builtin_amdgcn_rsqf(rstd[r] * (1.0f / 4096.0f) + 1e-6f);
;                 float mx = 0.f;
; #pragma unroll
;                 for (int bj = 0; bj < 2; ++bj) { f32x4 v0 = acc[ai][bj][m][0], v1 = acc[ai][bj][m][1];
;                     if (MODE == 1) { v0 = v0 * rs; v1 = v1 * rs;
; #pragma unroll
;                         for (int j = 0; j < 4; ++j) { const float a = v0[j] > 0.f ? v0[j] : 0.f, b = v1[j] > 0.f ? v1[j] : 0.f; v0[j] = a * a; v1[j] = b * b; } }
;                     if (MODE == 2) { f32x4 g0, g1; unpack8(cur.g[bj], g0, g1); v0 = v0 * g0; v1 = v1 * g1; }
;                     if (MODE == 3) { f32x4 g0, g1, a0, a1; unpack8(cur.g[bj], g0, g1); unpack8(cur.a[bj], a0, a1);
;                         v0 = a0 + v0 * g0; v1 = a1 + v1 * g1;
; #pragma unroll
;                         for (int j = 0; j < 4; ++j) mx = fmaxf(mx, fmaxf(fabsf(v0[j]), fabsf(v1[j]))); }
;                     *(u32x4*)(rowp + bj * HALF) = pack8(v0, v1); }
;                 if (MODE == 3) { mx = fmaxf(mx, __shfl_xor(mx, 16)); mx = fmaxf(mx, __shfl_xor(mx, 32)); if (fq == 0) atomicMax(RM + r, __builtin_bit_cast(unsigned, mx)); }
;                 if (MODE >= 2) cur = nxt; }
.LBB0_1541:
	s_lshl_b32 s98, s20, 5
	s_add_i32 s98, s98, s44
	s_lshl_b32 s98, s98, 17
	v_and_b32_e32 v248, 63, v0
	v_lshlrev_b32_e32 v248, 4, v248
	v_lshrrev_b32_e32 v249, 6, v0
	v_lshl_add_u32 v248, v249, 11, v248
	v_add_u32_e32 v248, s98, v248
	v_mov_b32_e32 v249, 0
	v_lshl_add_u64 v[248:249], s[6:7], 0, v[248:249]
	s_lshl_b32 s98, s20, 4
	s_add_i32 s98, s98, s44
	s_lshl_b32 s98, s98, 17
	v_and_b32_e32 v250, 63, v0
	v_lshlrev_b32_e32 v250, 4, v250
	v_lshrrev_b32_e32 v251, 6, v0
	v_lshl_add_u32 v250, v251, 11, v250
	v_add_u32_e32 v250, s98, v250
	v_mov_b32_e32 v251, 0
	v_lshl_add_u64 v[250:251], s[2:3], 0, v[250:251]
	v_mov_b32_e32 v146, v0
	s_andn2_b64 vcc, exec, s[4:5]
	v_ashrrev_i32_e32 v147, 2, v146
	v_and_b32_e32 v147, 0xffffffc0, v147
	v_lshl_add_u32 v147, s20, 8, v147
	v_and_or_b32 v148, v146, 15, v147
	v_lshrrev_b32_e32 v146, 1, v146
	v_and_b32_e32 v146, 0x78, v146
	v_lshl_or_b32 v146, s44, 8, v146
	v_ashrrev_i32_e32 v149, 31, v148
	v_lshlrev_b64 v[150:151], 14, v[148:149]
	v_ashrrev_i32_e32 v147, 31, v146
	v_lshl_add_u64 v[150:151], s[6:7], 0, v[150:151]
	v_lshlrev_b64 v[146:147], 1, v[146:147]
	v_or_b32_e32 v174, 16, v148
	s_mov_b64 s[98:99], 0x0
	v_lshl_add_u64 v[150:151], v[248:249], 0, s[98:99]
	v_ashrrev_i32_e32 v175, 31, v174
	global_load_dwordx4 v[158:161], v[150:151], off
	global_load_dwordx4 v[162:165], v[150:151], off offset:1024
	v_lshlrev_b64 v[150:151], 14, v[174:175]
	v_lshl_add_u64 v[150:151], s[6:7], 0, v[150:151]
	s_mov_b64 s[98:99], 0x4000
	v_lshl_add_u64 v[150:151], v[248:249], 0, s[98:99]
	global_load_dwordx4 v[166:169], v[150:151], off
	global_load_dwordx4 v[170:173], v[150:151], off offset:1024
	v_or_b32_e32 v150, 32, v148
	v_ashrrev_i32_e32 v151, 31, v150
	v_lshlrev_b64 v[176:177], 13, v[148:149]
	v_lshlrev_b64 v[178:179], 14, v[150:151]
	v_lshl_add_u64 v[176:177], s[2:3], 0, v[176:177]
	v_lshl_add_u64 v[178:179], s[6:7], 0, v[178:179]
	s_mov_b64 s[98:99], 0x0
	v_lshl_add_u64 v[176:177], v[250:251], 0, s[98:99]
	s_mov_b64 s[98:99], 0x8000
	v_lshl_add_u64 v[178:179], v[248:249], 0, s[98:99]
	v_or_b32_e32 v152, 48, v148
	v_ashrrev_i32_e32 v153, 31, v152
	v_lshlrev_b64 v[174:175], 13, v[174:175]
	v_lshlrev_b64 v[180:181], 14, v[152:153]
	v_lshl_add_u64 v[174:175], s[2:3], 0, v[174:175]
	v_lshl_add_u64 v[180:181], s[6:7], 0, v[180:181]
	s_mov_b64 s[98:99], 0x4000
	v_lshl_add_u64 v[174:175], v[250:251], 0, s[98:99]
	s_mov_b64 s[98:99], 0xc000
	v_lshl_add_u64 v[180:181], v[248:249], 0, s[98:99]
	s_mov_b64 s[4:5], -1
	s_waitcnt vmcnt(0)
	v_lshlrev_b32_e32 v182, 16, v158
	v_and_b32_e32 v183, 0xffff0000, v158
	v_lshlrev_b32_e32 v158, 16, v159
	v_and_b32_e32 v159, 0xffff0000, v159
	v_lshlrev_b32_e32 v184, 16, v160
	v_and_b32_e32 v185, 0xffff0000, v160
	v_lshlrev_b32_e32 v160, 16, v161
	v_and_b32_e32 v161, 0xffff0000, v161
	v_lshlrev_b32_e32 v186, 16, v162
	v_and_b32_e32 v187, 0xffff0000, v162
	v_lshlrev_b32_e32 v162, 16, v163
	v_and_b32_e32 v163, 0xffff0000, v163
	v_lshlrev_b32_e32 v188, 16, v164
	v_and_b32_e32 v189, 0xffff0000, v164
	v_lshlrev_b32_e32 v164, 16, v165
	v_and_b32_e32 v165, 0xffff0000, v165
	v_pk_mul_f32 v[128:129], v[128:129], v[158:159]
	v_pk_mul_f32 v[126:127], v[126:127], v[182:183]
	v_pk_mul_f32 v[124:125], v[124:125], v[160:161]
	v_pk_mul_f32 v[122:123], v[122:123], v[184:185]
	v_pk_mul_f32 v[120:121], v[120:121], v[162:163]
	v_pk_mul_f32 v[118:119], v[118:119], v[186:187]
	v_pk_mul_f32 v[158:159], v[112:113], v[164:165]
	v_pk_mul_f32 v[160:161], v[110:111], v[188:189]
	s_nop 0
	v_cvt_pk_bf16_f32 v110, v126, v127
	s_nop 0
	v_cvt_pk_bf16_f32 v111, v128, v129
	s_nop 0
	v_cvt_pk_bf16_f32 v112, v122, v123
	s_nop 0
	v_cvt_pk_bf16_f32 v113, v124, v125
	global_store_dwordx4 v[176:177], v[110:113], off
	v_lshlrev_b32_e32 v162, 16, v166
	v_and_b32_e32 v163, 0xffff0000, v166
	s_nop 0
	v_cvt_pk_bf16_f32 v110, v118, v119
	s_nop 0
	v_cvt_pk_bf16_f32 v111, v120, v121
	s_nop 0
	v_cvt_pk_bf16_f32 v112, v160, v161
	s_nop 0
	v_cvt_pk_bf16_f32 v113, v158, v159
	global_load_dwordx4 v[118:121], v[178:179], off
	v_lshlrev_b32_e32 v164, 16, v167
	v_and_b32_e32 v165, 0xffff0000, v167
	v_lshlrev_b32_e32 v166, 16, v168
	v_and_b32_e32 v167, 0xffff0000, v168
	v_lshlrev_b32_e32 v124, 16, v171
	v_and_b32_e32 v125, 0xffff0000, v171
	global_store_dwordx4 v[176:177], v[110:113], off offset:1024
	v_pk_mul_f32 v[158:159], v[106:107], v[166:167]
	v_pk_mul_f32 v[124:125], v[104:105], v[124:125]
	global_load_dwordx4 v[104:107], v[178:179], off offset:1024
	v_lshlrev_b32_e32 v168, 16, v169
	v_and_b32_e32 v169, 0xffff0000, v169
	v_lshlrev_b32_e32 v126, 16, v172
	v_and_b32_e32 v127, 0xffff0000, v172
	v_lshlrev_b32_e32 v128, 16, v173
	v_and_b32_e32 v129, 0xffff0000, v173
	v_lshlrev_b32_e32 v122, 16, v170
	v_and_b32_e32 v123, 0xffff0000, v170
	v_pk_mul_f32 v[116:117], v[116:117], v[164:165]
	v_pk_mul_f32 v[114:115], v[114:115], v[162:163]
	v_pk_mul_f32 v[108:109], v[108:109], v[168:169]
	v_pk_mul_f32 v[110:111], v[100:101], v[128:129]
	v_pk_mul_f32 v[112:113], v[98:99], v[126:127]
	s_nop 0
	v_cvt_pk_bf16_f32 v98, v114, v115
	s_nop 0
	v_cvt_pk_bf16_f32 v99, v116, v117
	s_nop 0
	v_cvt_pk_bf16_f32 v100, v158, v159
	s_nop 0
	v_cvt_pk_bf16_f32 v101, v108, v109
	v_pk_mul_f32 v[102:103], v[102:103], v[122:123]
	global_store_dwordx4 v[174:175], v[98:101], off
	v_lshlrev_b64 v[116:117], 13, v[152:153]
	v_lshl_add_u64 v[116:117], s[2:3], 0, v[116:117]
	s_nop 0
	v_cvt_pk_bf16_f32 v98, v102, v103
	s_nop 0
	v_cvt_pk_bf16_f32 v99, v124, v125
	s_nop 0
	v_cvt_pk_bf16_f32 v100, v112, v113
	s_nop 0
	v_cvt_pk_bf16_f32 v101, v110, v111
	global_load_dwordx4 v[108:111], v[180:181], off
	v_lshlrev_b64 v[102:103], 13, v[150:151]
	global_store_dwordx4 v[174:175], v[98:101], off offset:1024
	global_load_dwordx4 v[112:115], v[180:181], off offset:1024
	v_lshl_add_u64 v[102:103], s[2:3], 0, v[102:103]
	v_add_u32_e32 v98, 0x80, v148
	v_ashrrev_i32_e32 v99, 31, v98
	v_lshlrev_b64 v[122:123], 14, v[98:99]
	v_lshl_add_u64 v[122:123], s[6:7], 0, v[122:123]
	s_mov_b64 s[98:99], 0x8000
	v_lshl_add_u64 v[102:103], v[250:251], 0, s[98:99]
	v_add_u32_e32 v100, 0x90, v148
	s_mov_b64 s[98:99], 0x10000
	v_lshl_add_u64 v[122:123], v[248:249], 0, s[98:99]
	v_ashrrev_i32_e32 v101, 31, v100
	v_lshlrev_b64 v[124:125], 14, v[100:101]
	v_lshl_add_u64 v[124:125], s[6:7], 0, v[124:125]
	s_mov_b64 s[98:99], 0xc000
	v_lshl_add_u64 v[116:117], v[250:251], 0, s[98:99]
	s_mov_b64 s[98:99], 0x14000
	v_lshl_add_u64 v[124:125], v[248:249], 0, s[98:99]
	s_waitcnt vmcnt(6)
; __device__ __forceinline__ u32x4 pack8(const f32x4 v0, const f32x4 v1) { u32x4 w; w.x = cvt_pk_bf16(v0[0], v0[1]); w.y = cvt_pk_bf16(v0[2], v0[3]); w.z = cvt_pk_bf16(v1[0], v1[1]); w.w = cvt_pk_bf16(v1[2], v1[3]); return w; }
; __device__ __forceinline__ void unpack8(const u32x4 w, f32x4& v0, f32x4& v1) { v0 = (f32x4){bf_lo(w.x), bf_hi(w.x), bf_lo(w.y), bf_hi(w.y)}; v1 = (f32x4){bf_lo(w.z), bf_hi(w.z), bf_lo(w.w), bf_hi(w.w)}; }
;     __device__ __forceinline__ void operator()(AccRef acc, const Unit& u, int wr, int wc, int fr, int fq) const {
;     ...
;         for (int s = 0; s < 8; ++s) { const int ai = s >> 2, m = s & 3; const int r = row0 + ai * HALF + m * 16; bf16_t* rowp = O + (size_t)r * ldc + col0;
;                 if (MODE >= 2 && s + 1 < 8) load_row(nxt, row0 + ((s + 1) >> 2) * HALF + ((s + 1) & 3) * 16, col0);
;                 float rs = 1.f; if (MODE == 1) rs = __builtin_amdgcn_rsqf(rstd[r] * (1.0f / 4096.0f) + 1e-6f);
;                 float mx = 0.f;
; #pragma unroll
;                 for (int bj = 0; bj < 2; ++bj) { f32x4 v0 = acc[ai][bj][m][0], v1 = acc[ai][bj][m][1];
;                     if (MODE == 1) { v0 = v0 * rs; v1 = v1 * rs;
; #pragma unroll
;                         for (int j = 0; j < 4; ++j) { const float a = v0[j] > 0.f ? v0[j] : 0.f, b = v1[j] > 0.f ? v1[j] : 0.f; v0[j] = a * a; v1[j] = b * b; } }
;                     if (MODE == 2) { f32x4 g0, g1; unpack8(cur.g[bj], g0, g1); v0 = v0 * g0; v1 = v1 * g1; }
;                     if (MODE == 3) { f32x4 g0, g1, a0, a1; unpack8(cur.g[bj], g0, g1); unpack8(cur.a[bj], a0, a1);
;                         v0 = a0 + v0 * g0; v1 = a1 + v1 * g1;
; #pragma unroll
;                         for (int j = 0; j < 4; ++j) mx = fmaxf(mx, fmaxf(fabsf(v0[j]), fabsf(v1[j]))); }
;                     *(u32x4*)(rowp + bj * HALF) = pack8(v0, v1); }
;                 if (MODE == 3) { mx = fmaxf(mx, __shfl_xor(mx, 16)); mx = fmaxf(mx, __shfl_xor(mx, 32)); if (fq == 0) atomicMax(RM + r, __builtin_bit_cast(unsigned, mx)); }
;                 if (MODE >= 2) cur = nxt; }
	v_lshlrev_b32_e32 v126, 16, v118
	v_and_b32_e32 v127, 0xffff0000, v118
	v_lshlrev_b32_e32 v118, 16, v119
	v_and_b32_e32 v119, 0xffff0000, v119
	v_lshlrev_b32_e32 v128, 16, v120
	v_and_b32_e32 v129, 0xffff0000, v120
	v_lshlrev_b32_e32 v120, 16, v121
	v_and_b32_e32 v121, 0xffff0000, v121
	v_pk_mul_f32 v[96:97], v[96:97], v[118:119]
	v_pk_mul_f32 v[94:95], v[94:95], v[126:127]
	v_pk_mul_f32 v[118:119], v[92:93], v[120:121]
	v_pk_mul_f32 v[92:93], v[90:91], v[128:129]
	s_nop 0
	v_cvt_pk_bf16_f32 v90, v94, v95
	s_nop 0
	v_cvt_pk_bf16_f32 v91, v96, v97
	s_waitcnt vmcnt(4)
	v_lshlrev_b32_e32 v94, 16, v104
	v_and_b32_e32 v95, 0xffff0000, v104
	v_lshlrev_b32_e32 v96, 16, v105
	v_and_b32_e32 v97, 0xffff0000, v105
	v_lshlrev_b32_e32 v104, 16, v106
	v_and_b32_e32 v105, 0xffff0000, v106
	v_lshlrev_b32_e32 v106, 16, v107
	v_and_b32_e32 v107, 0xffff0000, v107
	s_nop 0
	v_cvt_pk_bf16_f32 v92, v92, v93
	s_nop 0
	v_cvt_pk_bf16_f32 v93, v118, v119
	global_store_dwordx4 v[102:103], v[90:93], off
	v_pk_mul_f32 v[80:81], v[80:81], v[96:97]
	v_pk_mul_f32 v[78:79], v[78:79], v[94:95]
	v_pk_mul_f32 v[90:91], v[76:77], v[106:107]
	v_pk_mul_f32 v[76:77], v[74:75], v[104:105]
	s_nop 0
	v_cvt_pk_bf16_f32 v74, v78, v79
	s_nop 0
	v_cvt_pk_bf16_f32 v75, v80, v81
	s_waitcnt vmcnt(3)
	v_lshlrev_b32_e32 v92, 16, v108
	s_nop 0
	v_cvt_pk_bf16_f32 v76, v76, v77
	s_nop 0
	v_cvt_pk_bf16_f32 v77, v90, v91
	global_load_dwordx4 v[78:81], v[122:123], off
	v_and_b32_e32 v93, 0xffff0000, v108
	v_lshlrev_b32_e32 v94, 16, v109
	v_and_b32_e32 v95, 0xffff0000, v109
	v_lshlrev_b32_e32 v96, 16, v110
	v_and_b32_e32 v97, 0xffff0000, v110
	v_lshlrev_b32_e32 v104, 16, v111
	v_and_b32_e32 v105, 0xffff0000, v111
	global_store_dwordx4 v[102:103], v[74:77], off offset:1024
	v_pk_mul_f32 v[88:89], v[88:89], v[94:95]
	v_pk_mul_f32 v[86:87], v[86:87], v[92:93]
	v_pk_mul_f32 v[90:91], v[84:85], v[104:105]
	v_pk_mul_f32 v[84:85], v[82:83], v[96:97]
	s_waitcnt vmcnt(3)
	v_lshlrev_b32_e32 v92, 16, v112
	v_and_b32_e32 v93, 0xffff0000, v112
	v_lshlrev_b32_e32 v94, 16, v113
	v_and_b32_e32 v95, 0xffff0000, v113
	v_lshlrev_b32_e32 v96, 16, v114
	v_and_b32_e32 v97, 0xffff0000, v114
	v_lshlrev_b32_e32 v102, 16, v115
	v_and_b32_e32 v103, 0xffff0000, v115
	global_load_dwordx4 v[74:77], v[122:123], off offset:1024
	s_nop 0
	v_cvt_pk_bf16_f32 v82, v86, v87
	v_pk_mul_f32 v[72:73], v[72:73], v[94:95]
	v_pk_mul_f32 v[70:71], v[70:71], v[92:93]
	v_pk_mul_f32 v[86:87], v[68:69], v[102:103]
	v_pk_mul_f32 v[68:69], v[66:67], v[96:97]
	s_nop 0
	v_cvt_pk_bf16_f32 v83, v88, v89
	s_nop 0
	v_cvt_pk_bf16_f32 v84, v84, v85
	s_nop 0
	v_cvt_pk_bf16_f32 v85, v90, v91
	global_store_dwordx4 v[116:117], v[82:85], off
	s_nop 0
	v_cvt_pk_bf16_f32 v66, v70, v71
	s_nop 0
	v_cvt_pk_bf16_f32 v67, v72, v73
	s_nop 0
	v_cvt_pk_bf16_f32 v68, v68, v69
	s_nop 0
	v_cvt_pk_bf16_f32 v69, v86, v87
	global_load_dwordx4 v[70:73], v[124:125], off
	s_nop 0
	v_add_u32_e32 v82, 0xa0, v148
	global_store_dwordx4 v[116:117], v[66:69], off offset:1024
	global_load_dwordx4 v[66:69], v[124:125], off offset:1024
	v_ashrrev_i32_e32 v83, 31, v82
	v_lshlrev_b64 v[86:87], 13, v[98:99]
	v_lshlrev_b64 v[90:91], 14, v[82:83]
	v_lshl_add_u64 v[86:87], s[2:3], 0, v[86:87]
	v_add_u32_e32 v84, 0xb0, v148
	v_lshl_add_u64 v[90:91], s[6:7], 0, v[90:91]
	s_mov_b64 s[98:99], 0x10000
	v_lshl_add_u64 v[86:87], v[250:251], 0, s[98:99]
	v_ashrrev_i32_e32 v85, 31, v84
	s_mov_b64 s[98:99], 0x18000
	v_lshl_add_u64 v[90:91], v[248:249], 0, s[98:99]
	v_lshlrev_b64 v[88:89], 13, v[100:101]
	v_lshlrev_b64 v[92:93], 14, v[84:85]
	v_lshl_add_u64 v[88:89], s[2:3], 0, v[88:89]
	v_lshl_add_u64 v[92:93], s[6:7], 0, v[92:93]
	s_mov_b64 s[98:99], 0x14000
	v_lshl_add_u64 v[88:89], v[250:251], 0, s[98:99]
	s_mov_b64 s[98:99], 0x1c000
	v_lshl_add_u64 v[92:93], v[248:249], 0, s[98:99]
	s_waitcnt vmcnt(6)
	v_lshlrev_b32_e32 v94, 16, v78
	v_and_b32_e32 v95, 0xffff0000, v78
	v_lshlrev_b32_e32 v78, 16, v79
	v_and_b32_e32 v79, 0xffff0000, v79
	v_lshlrev_b32_e32 v96, 16, v80
	v_and_b32_e32 v97, 0xffff0000, v80
	v_lshlrev_b32_e32 v80, 16, v81
	v_and_b32_e32 v81, 0xffff0000, v81
	v_pk_mul_f32 v[64:65], v[64:65], v[78:79]
	v_pk_mul_f32 v[62:63], v[62:63], v[94:95]
	v_pk_mul_f32 v[78:79], v[60:61], v[80:81]
	v_pk_mul_f32 v[60:61], v[58:59], v[96:97]
	s_nop 0
	v_cvt_pk_bf16_f32 v58, v62, v63
	s_nop 0
	v_cvt_pk_bf16_f32 v59, v64, v65
	s_waitcnt vmcnt(4)
	v_lshlrev_b32_e32 v62, 16, v74
	v_and_b32_e32 v63, 0xffff0000, v74
	v_lshlrev_b32_e32 v64, 16, v75
	v_and_b32_e32 v65, 0xffff0000, v75
	v_lshlrev_b32_e32 v74, 16, v76
	v_and_b32_e32 v75, 0xffff0000, v76
	v_lshlrev_b32_e32 v76, 16, v77
	v_and_b32_e32 v77, 0xffff0000, v77
	s_nop 0
	v_cvt_pk_bf16_f32 v60, v60, v61
	s_nop 0
	v_cvt_pk_bf16_f32 v61, v78, v79
	global_store_dwordx4 v[86:87], v[58:61], off
	v_pk_mul_f32 v[48:49], v[48:49], v[64:65]
	v_pk_mul_f32 v[46:47], v[46:47], v[62:63]
	v_pk_mul_f32 v[58:59], v[44:45], v[76:77]
	v_pk_mul_f32 v[44:45], v[42:43], v[74:75]
	s_waitcnt vmcnt(3)
; __device__ __forceinline__ u32x4 pack8(const f32x4 v0, const f32x4 v1) { u32x4 w; w.x = cvt_pk_bf16(v0[0], v0[1]); w.y = cvt_pk_bf16(v0[2], v0[3]); w.z = cvt_pk_bf16(v1[0], v1[1]); w.w = cvt_pk_bf16(v1[2], v1[3]); return w; }
; __device__ __forceinline__ void unpack8(const u32x4 w, f32x4& v0, f32x4& v1) { v0 = (f32x4){bf_lo(w.x), bf_hi(w.x), bf_lo(w.y), bf_hi(w.y)}; v1 = (f32x4){bf_lo(w.z), bf_hi(w.z), bf_lo(w.w), bf_hi(w.w)}; }
;     __device__ __forceinline__ void operator()(AccRef acc, const Unit& u, int wr, int wc, int fr, int fq) const {
;     ...
;         for (int s = 0; s < 8; ++s) { const int ai = s >> 2, m = s & 3; const int r = row0 + ai * HALF + m * 16; bf16_t* rowp = O + (size_t)r * ldc + col0;
;                 if (MODE >= 2 && s + 1 < 8) load_row(nxt, row0 + ((s + 1) >> 2) * HALF + ((s + 1) & 3) * 16, col0);
;                 float rs = 1.f; if (MODE == 1) rs = __builtin_amdgcn_rsqf(rstd[r] * (1.0f / 4096.0f) + 1e-6f);
;                 float mx = 0.f;
; #pragma unroll
;                 for (int bj = 0; bj < 2; ++bj) { f32x4 v0 = acc[ai][bj][m][0], v1 = acc[ai][bj][m][1];
;                     if (MODE == 1) { v0 = v0 * rs; v1 = v1 * rs;
; #pragma unroll
;                         for (int j = 0; j < 4; ++j) { const float a = v0[j] > 0.f ? v0[j] : 0.f, b = v1[j] > 0.f ? v1[j] : 0.f; v0[j] = a * a; v1[j] = b * b; } }
;                     if (MODE == 2) { f32x4 g0, g1; unpack8(cur.g[bj], g0, g1); v0 = v0 * g0; v1 = v1 * g1; }
;                     if (MODE == 3) { f32x4 g0, g1, a0, a1; unpack8(cur.g[bj], g0, g1); unpack8(cur.a[bj], a0, a1);
;                         v0 = a0 + v0 * g0; v1 = a1 + v1 * g1;
; #pragma unroll
;                         for (int j = 0; j < 4; ++j) mx = fmaxf(mx, fmaxf(fabsf(v0[j]), fabsf(v1[j]))); }
;                     *(u32x4*)(rowp + bj * HALF) = pack8(v0, v1); }
;                 if (MODE == 3) { mx = fmaxf(mx, __shfl_xor(mx, 16)); mx = fmaxf(mx, __shfl_xor(mx, 32)); if (fq == 0) atomicMax(RM + r, __builtin_bit_cast(unsigned, mx)); }
;                 if (MODE >= 2) cur = nxt; }
	v_lshlrev_b32_e32 v60, 16, v70
	v_and_b32_e32 v61, 0xffff0000, v70
	v_lshlrev_b32_e32 v62, 16, v71
	v_and_b32_e32 v63, 0xffff0000, v71
	v_lshlrev_b32_e32 v64, 16, v72
	v_and_b32_e32 v65, 0xffff0000, v72
	v_lshlrev_b32_e32 v70, 16, v73
	s_nop 0
	v_cvt_pk_bf16_f32 v42, v46, v47
	s_nop 0
	v_cvt_pk_bf16_f32 v43, v48, v49
	s_nop 0
	v_cvt_pk_bf16_f32 v44, v44, v45
	s_nop 0
	v_cvt_pk_bf16_f32 v45, v58, v59
	global_load_dwordx4 v[46:49], v[90:91], off
	v_and_b32_e32 v71, 0xffff0000, v73
	v_pk_mul_f32 v[56:57], v[56:57], v[62:63]
	v_pk_mul_f32 v[54:55], v[54:55], v[60:61]
	v_pk_mul_f32 v[58:59], v[52:53], v[70:71]
	v_pk_mul_f32 v[52:53], v[50:51], v[64:65]
	global_store_dwordx4 v[86:87], v[42:45], off offset:1024
	s_waitcnt vmcnt(3)
	v_lshlrev_b32_e32 v60, 16, v66
	v_and_b32_e32 v61, 0xffff0000, v66
	v_lshlrev_b32_e32 v62, 16, v67
	v_and_b32_e32 v63, 0xffff0000, v67
	v_lshlrev_b32_e32 v64, 16, v68
	v_and_b32_e32 v65, 0xffff0000, v68
	v_lshlrev_b32_e32 v66, 16, v69
	v_and_b32_e32 v67, 0xffff0000, v69
	global_load_dwordx4 v[42:45], v[90:91], off offset:1024
	s_nop 0
	v_cvt_pk_bf16_f32 v50, v54, v55
	v_pk_mul_f32 v[40:41], v[40:41], v[62:63]
	v_pk_mul_f32 v[38:39], v[38:39], v[60:61]
	v_pk_mul_f32 v[54:55], v[36:37], v[66:67]
	v_pk_mul_f32 v[36:37], v[34:35], v[64:65]
	s_nop 0
	v_cvt_pk_bf16_f32 v51, v56, v57
	s_nop 0
	v_cvt_pk_bf16_f32 v52, v52, v53
	s_nop 0
	v_cvt_pk_bf16_f32 v53, v58, v59
	global_store_dwordx4 v[88:89], v[50:53], off
	s_nop 0
	v_cvt_pk_bf16_f32 v34, v38, v39
	s_nop 0
	v_cvt_pk_bf16_f32 v35, v40, v41
	s_nop 0
	v_cvt_pk_bf16_f32 v36, v36, v37
	s_nop 0
	v_cvt_pk_bf16_f32 v37, v54, v55
	global_load_dwordx4 v[38:41], v[92:93], off
	s_nop 0
	v_lshlrev_b64 v[50:51], 13, v[82:83]
	global_store_dwordx4 v[88:89], v[34:37], off offset:1024
	global_load_dwordx4 v[34:37], v[92:93], off offset:1024
	v_lshl_add_u64 v[50:51], s[2:3], 0, v[50:51]
	s_mov_b64 s[98:99], 0x18000
	v_lshl_add_u64 v[50:51], v[250:251], 0, s[98:99]
	v_lshlrev_b64 v[52:53], 13, v[84:85]
	v_lshl_add_u64 v[52:53], s[2:3], 0, v[52:53]
	s_mov_b64 s[98:99], 0x1c000
	v_lshl_add_u64 v[52:53], v[250:251], 0, s[98:99]
	s_waitcnt vmcnt(6)
	v_lshlrev_b32_e32 v54, 16, v46
	v_and_b32_e32 v55, 0xffff0000, v46
	v_lshlrev_b32_e32 v46, 16, v47
	v_and_b32_e32 v47, 0xffff0000, v47
	v_lshlrev_b32_e32 v56, 16, v48
	v_and_b32_e32 v57, 0xffff0000, v48
	v_lshlrev_b32_e32 v48, 16, v49
	v_and_b32_e32 v49, 0xffff0000, v49
	v_pk_mul_f32 v[32:33], v[32:33], v[46:47]
	v_pk_mul_f32 v[30:31], v[30:31], v[54:55]
	v_pk_mul_f32 v[46:47], v[28:29], v[48:49]
	v_pk_mul_f32 v[28:29], v[26:27], v[56:57]
	s_nop 0
	v_cvt_pk_bf16_f32 v26, v30, v31
	s_nop 0
	v_cvt_pk_bf16_f32 v27, v32, v33
	s_waitcnt vmcnt(4)
	v_lshlrev_b32_e32 v30, 16, v42
	s_nop 0
	v_cvt_pk_bf16_f32 v28, v28, v29
	s_nop 0
	v_cvt_pk_bf16_f32 v29, v46, v47
	v_and_b32_e32 v31, 0xffff0000, v42
	v_lshlrev_b32_e32 v32, 16, v43
	v_and_b32_e32 v33, 0xffff0000, v43
	v_lshlrev_b32_e32 v42, 16, v44
	v_and_b32_e32 v43, 0xffff0000, v44
	v_lshlrev_b32_e32 v44, 16, v45
	v_and_b32_e32 v45, 0xffff0000, v45
	global_store_dwordx4 v[50:51], v[26:29], off
	v_pk_mul_f32 v[20:21], v[20:21], v[32:33]
	v_pk_mul_f32 v[18:19], v[18:19], v[30:31]
	v_pk_mul_f32 v[26:27], v[16:17], v[44:45]
	s_waitcnt vmcnt(3)
	v_lshlrev_b32_e32 v28, 16, v38
	v_and_b32_e32 v29, 0xffff0000, v38
	v_lshlrev_b32_e32 v30, 16, v39
	v_and_b32_e32 v31, 0xffff0000, v39
	v_lshlrev_b32_e32 v32, 16, v40
	v_and_b32_e32 v33, 0xffff0000, v40
	v_lshlrev_b32_e32 v38, 16, v41
	v_and_b32_e32 v39, 0xffff0000, v41
	v_pk_mul_f32 v[16:17], v[14:15], v[42:43]
	s_nop 0
	v_cvt_pk_bf16_f32 v14, v18, v19
	s_nop 0
	v_cvt_pk_bf16_f32 v15, v20, v21
	v_pk_mul_f32 v[20:21], v[22:23], v[28:29]
	v_pk_mul_f32 v[22:23], v[12:13], v[38:39]
	v_pk_mul_f32 v[12:13], v[10:11], v[32:33]
	s_nop 0
	v_cvt_pk_bf16_f32 v16, v16, v17
	s_nop 0
	v_cvt_pk_bf16_f32 v17, v26, v27
	v_pk_mul_f32 v[18:19], v[24:25], v[30:31]
	global_store_dwordx4 v[50:51], v[14:17], off offset:1024
	s_nop 0
	v_cvt_pk_bf16_f32 v10, v20, v21
	s_nop 0
	v_cvt_pk_bf16_f32 v11, v18, v19
	s_nop 0
	v_cvt_pk_bf16_f32 v12, v12, v13
	s_nop 0
	v_cvt_pk_bf16_f32 v13, v22, v23
	global_store_dwordx4 v[52:53], v[10:13], off
	s_waitcnt vmcnt(3)
	v_lshlrev_b32_e32 v14, 16, v34
	v_and_b32_e32 v15, 0xffff0000, v34
	v_lshlrev_b32_e32 v10, 16, v36
	v_and_b32_e32 v11, 0xffff0000, v36
	v_lshlrev_b32_e32 v12, 16, v37
	v_and_b32_e32 v13, 0xffff0000, v37
	v_lshlrev_b32_e32 v16, 16, v35
	v_and_b32_e32 v17, 0xffff0000, v35
	v_pk_mul_f32 v[12:13], v[4:5], v[12:13]
	v_pk_mul_f32 v[4:5], v[2:3], v[10:11]
	v_pk_mul_f32 v[8:9], v[8:9], v[16:17]
	v_pk_mul_f32 v[6:7], v[6:7], v[14:15]
	s_nop 0
	s_nop 0
	v_cvt_pk_bf16_f32 v2, v6, v7
	s_nop 0
	v_cvt_pk_bf16_f32 v3, v8, v9
	s_nop 0
	v_cvt_pk_bf16_f32 v4, v4, v5
	s_nop 0
	v_cvt_pk_bf16_f32 v5, v12, v13
	global_store_dwordx4 v[52:53], v[2:5], off offset:1024
	s_cbranch_vccnz .LBB0_1530
	s_andn2_b64 vcc, exec, s[0:1]
	s_cbranch_vccnz .LBB0_1529
	s_barrier
	s_branch .LBB0_1529

; __device__ __forceinline__ u32x4 pack8(const f32x4 v0, const f32x4 v1) { u32x4 w; w.x = cvt_pk_bf16(v0[0], v0[1]); w.y = cvt_pk_bf16(v0[2], v0[3]); w.z = cvt_pk_bf16(v1[0], v1[1]); w.w = cvt_pk_bf16(v1[2], v1[3]); return w; }
; __device__ __forceinline__ void unpack8(const u32x4 w, f32x4& v0, f32x4& v1) { v0 = (f32x4){bf_lo(w.x), bf_hi(w.x), bf_lo(w.y), bf_hi(w.y)}; v1 = (f32x4){bf_lo(w.z), bf_hi(w.z), bf_lo(w.w), bf_hi(w.w)}; }
;     __device__ __forceinline__ void operator()(AccRef acc, const Unit& u, int wr, int wc, int fr, int fq) const {
;     ...
;         for (int s = 0; s < 8; ++s) { const int ai = s >> 2, m = s & 3; const int r = row0 + ai * HALF + m * 16; bf16_t* rowp = O + (size_t)r * ldc + col0;
;                 if (MODE >= 2 && s + 1 < 8) load_row(nxt, row0 + ((s + 1) >> 2) * HALF + ((s + 1) & 3) * 16, col0);
;                 float rs = 1.f; if (MODE == 1) rs = __builtin_amdgcn_rsqf(rstd[r] * (1.0f / 4096.0f) + 1e-6f);
;                 float mx = 0.f;
; #pragma unroll
;                 for (int bj = 0; bj < 2; ++bj) { f32x4 v0 = acc[ai][bj][m][0], v1 = acc[ai][bj][m][1];
;                     if (MODE == 1) { v0 = v0 * rs; v1 = v1 * rs;
; #pragma unroll
;                         for (int j = 0; j < 4; ++j) { const float a = v0[j] > 0.f ? v0[j] : 0.f, b = v1[j] > 0.f ? v1[j] : 0.f; v0[j] = a * a; v1[j] = b * b; } }
;                     if (MODE == 2) { f32x4 g0, g1; unpack8(cur.g[bj], g0, g1); v0 = v0 * g0; v1 = v1 * g1; }
;                     if (MODE == 3) { f32x4 g0, g1, a0, a1; unpack8(cur.g[bj], g0, g1); unpack8(cur.a[bj], a0, a1);
;                         v0 = a0 + v0 * g0; v1 = a1 + v1 * g1;
; #pragma unroll
;                         for (int j = 0; j < 4; ++j) mx = fmaxf(mx, fmaxf(fabsf(v0[j]), fabsf(v1[j]))); }
;                     *(u32x4*)(rowp + bj * HALF) = pack8(v0, v1); }
;                 if (MODE == 3) { mx = fmaxf(mx, __shfl_xor(mx, 16)); mx = fmaxf(mx, __shfl_xor(mx, 32)); if (fq == 0) atomicMax(RM + r, __builtin_bit_cast(unsigned, mx)); }
;                 if (MODE >= 2) cur = nxt; }
.LBB0_1568:
	s_lshl_b32 s98, s26, 5
	s_add_i32 s98, s98, s6
	s_add_i32 s98, s98, 16
	s_lshl_b32 s98, s98, 17
	v_and_b32_e32 v248, 63, v0
	v_lshlrev_b32_e32 v248, 4, v248
	v_lshrrev_b32_e32 v249, 6, v0
	v_lshl_add_u32 v248, v249, 11, v248
	v_add_u32_e32 v248, s98, v248
	v_mov_b32_e32 v249, 0
	v_lshl_add_u64 v[248:249], s[8:9], 0, v[248:249]
	s_lshl_b32 s98, s26, 4
	s_add_i32 s98, s98, s6
	s_lshl_b32 s98, s98, 17
	v_and_b32_e32 v250, 63, v0
	v_lshlrev_b32_e32 v250, 4, v250
	v_lshrrev_b32_e32 v251, 6, v0
	v_lshl_add_u32 v250, v251, 11, v250
	v_add_u32_e32 v250, s98, v250
	v_mov_b32_e32 v251, 0
	v_lshl_add_u64 v[250:251], s[10:11], 0, v[250:251]
	v_mov_b32_e32 v130, v0
	s_nop 0
	v_ashrrev_i32_e32 v131, 2, v130
	v_and_b32_e32 v131, 0xffffffc0, v131
	v_lshl_add_u32 v131, s26, 8, v131
	v_bfe_u32 v174, v130, 4, 2
	v_and_or_b32 v166, v130, 15, v131
	v_lshrrev_b32_e32 v130, 1, v130
	v_and_b32_e32 v130, 0x60, v130
	v_lshl_or_b32 v130, s6, 8, v130
	v_lshl_or_b32 v162, v174, 3, v130
	v_ashrrev_i32_e32 v167, 31, v166
	v_ashrrev_i32_e32 v163, 31, v162
	v_lshlrev_b64 v[170:171], 13, v[166:167]
	v_lshlrev_b64 v[164:165], 1, v[162:163]
	v_lshl_add_u64 v[130:131], s[10:11], 0, v[170:171]
	v_lshl_add_u64 v[130:131], v[130:131], 0, v[164:165]
	s_mov_b64 s[98:99], 0x0
	v_lshl_add_u64 v[252:253], v[250:251], 0, s[98:99]
	global_load_dwordx4 v[180:183], v[252:253], off
	global_load_dwordx4 v[184:187], v[252:253], off offset:1024
	v_lshlrev_b64 v[130:131], 14, v[166:167]
	v_lshl_add_u64 v[130:131], s[8:9], 0, v[130:131]
	v_lshl_add_u64 v[130:131], v[130:131], 0, v[164:165]
	v_add_co_u32_e32 v130, vcc, s44, v130
	v_or_b32_e32 v168, 16, v166
	s_nop 0
	v_addc_co_u32_e32 v131, vcc, 0, v131, vcc
	s_mov_b64 s[98:99], 0x0
	v_lshl_add_u64 v[246:247], v[248:249], 0, s[98:99]
	global_load_dwordx4 v[188:191], v[246:247], off
	global_load_dwordx4 v[192:195], v[246:247], off offset:1024
	v_ashrrev_i32_e32 v169, 31, v168
	v_lshlrev_b64 v[130:131], 14, v[168:169]
	v_lshl_add_u64 v[130:131], s[8:9], 0, v[130:131]
	v_lshlrev_b64 v[172:173], 13, v[168:169]
	v_lshl_add_u64 v[130:131], v[130:131], 0, v[164:165]
	v_lshl_add_u64 v[132:133], s[10:11], 0, v[172:173]
	v_add_co_u32_e32 v134, vcc, s44, v130
	v_lshl_add_u64 v[132:133], v[132:133], 0, v[164:165]
	s_nop 0
	v_addc_co_u32_e32 v135, vcc, 0, v131, vcc
	s_mov_b64 s[98:99], 0x4000
	v_lshl_add_u64 v[252:253], v[250:251], 0, s[98:99]
	global_load_dwordx4 v[138:141], v[252:253], off
	s_nop 0
	global_load_dwordx4 v[130:133], v[252:253], off offset:1024
	s_nop 0
	s_mov_b64 s[98:99], 0x4000
	v_lshl_add_u64 v[246:247], v[248:249], 0, s[98:99]
	global_load_dwordx4 v[142:145], v[246:247], off
	s_nop 0
	global_load_dwordx4 v[134:137], v[246:247], off offset:1024
	v_cmp_eq_u32_e64 s[6:7], 0, v174
	v_lshl_add_u64 v[170:171], s[2:3], 0, v[170:171]
	v_lshl_add_u64 v[170:171], v[170:171], 0, v[164:165]
	s_waitcnt vmcnt(0)
	v_lshlrev_b32_e32 v174, 16, v180
	v_and_b32_e32 v175, 0xffff0000, v180
	v_lshlrev_b32_e32 v196, 16, v182
	v_and_b32_e32 v197, 0xffff0000, v182
	v_lshlrev_b32_e32 v180, 16, v181
	v_and_b32_e32 v181, 0xffff0000, v181
	v_lshlrev_b32_e32 v182, 16, v183
	v_and_b32_e32 v183, 0xffff0000, v183
	v_lshlrev_b32_e32 v200, 16, v186
	v_lshlrev_b32_e32 v202, 16, v188
	v_and_b32_e32 v203, 0xffff0000, v188
	v_lshlrev_b32_e32 v204, 16, v190
	v_and_b32_e32 v205, 0xffff0000, v190
	v_and_b32_e32 v201, 0xffff0000, v186
	v_lshlrev_b32_e32 v186, 16, v187
	v_and_b32_e32 v187, 0xffff0000, v187
	v_lshlrev_b32_e32 v188, 16, v189
	v_and_b32_e32 v189, 0xffff0000, v189
	v_lshlrev_b32_e32 v190, 16, v191
	v_and_b32_e32 v191, 0xffff0000, v191
	v_lshlrev_b32_e32 v208, 16, v194
	v_and_b32_e32 v209, 0xffff0000, v194
	v_lshlrev_b32_e32 v194, 16, v195
	v_and_b32_e32 v195, 0xffff0000, v195
	v_pk_fma_f32 v[126:127], v[126:127], v[202:203], v[174:175]
	v_pk_fma_f32 v[122:123], v[122:123], v[204:205], v[196:197]
	v_lshlrev_b32_e32 v198, 16, v184
	v_and_b32_e32 v199, 0xffff0000, v184
	v_lshlrev_b32_e32 v206, 16, v192
	v_and_b32_e32 v207, 0xffff0000, v192
	v_pk_fma_f32 v[128:129], v[128:129], v[188:189], v[180:181]
	v_pk_fma_f32 v[124:125], v[124:125], v[190:191], v[182:183]
	v_pk_fma_f32 v[174:175], v[116:117], v[194:195], v[186:187]
	v_max_f32_e64 v116, |v126|, |v122|
	v_max_f32_e64 v117, |v127|, |v123|
	v_lshlrev_b32_e32 v184, 16, v185
	v_and_b32_e32 v185, 0xffff0000, v185
	v_lshlrev_b32_e32 v192, 16, v193
	v_and_b32_e32 v193, 0xffff0000, v193
	v_pk_fma_f32 v[118:119], v[118:119], v[206:207], v[198:199]
	v_pk_fma_f32 v[182:183], v[114:115], v[208:209], v[200:201]
	v_max_f32_e64 v180, |v128|, |v124|
	v_max_f32_e64 v181, |v129|, |v125|
	v_max3_f32 v116, v116, 0, v117
	v_pk_fma_f32 v[120:121], v[120:121], v[192:193], v[184:185]
	s_nop 0
	v_cvt_pk_bf16_f32 v114, v126, v127
	v_max_f32_e64 v126, |v118|, |v182|
	v_max3_f32 v116, v116, v180, v181
	v_max_f32_e64 v117, |v119|, |v183|
	v_max3_f32 v116, v116, v126, v117
	v_max_f32_e64 v117, |v120|, |v174|
	v_max_f32_e64 v126, |v121|, |v175|
	v_max3_f32 v126, v116, v117, v126
	v_and_b32_e32 v117, 64, v179
	v_xor_b32_e32 v116, 16, v179
	v_add_u32_e32 v127, 64, v117
	v_cmp_lt_i32_e32 vcc, v116, v127
	s_nop 0
	v_cvt_pk_bf16_f32 v115, v128, v129
	s_nop 1
	v_cndmask_b32_e32 v116, v179, v116, vcc
	v_lshlrev_b32_e32 v180, 2, v116
	ds_bpermute_b32 v128, v180, v126
	s_nop 0
	v_cvt_pk_bf16_f32 v116, v122, v123
	s_nop 0
	v_cvt_pk_bf16_f32 v117, v124, v125
	global_store_dwordx4 v[170:171], v[114:117], off
	s_nop 1
	v_xor_b32_e32 v115, 32, v179
	v_cmp_lt_i32_e32 vcc, v115, v127
	s_waitcnt lgkmcnt(0)
	v_max_f32_e32 v114, v128, v128
	v_max_f32_e32 v114, v126, v114
	v_cndmask_b32_e32 v115, v179, v115, vcc
	v_lshlrev_b32_e32 v181, 2, v115
	ds_bpermute_b32 v115, v181, v114
	s_nop 0
	v_cvt_pk_bf16_f32 v116, v118, v119
	s_nop 0
	v_cvt_pk_bf16_f32 v117, v120, v121
	s_nop 0
	v_cvt_pk_bf16_f32 v118, v182, v183
	s_nop 0
	v_cvt_pk_bf16_f32 v119, v174, v175
	global_store_dwordx4 v[170:171], v[116:119], off offset:256
	s_and_saveexec_b64 s[26:27], s[6:7]
	s_cbranch_execz .LBB0_1570
	s_waitcnt lgkmcnt(0)
	v_max_f32_e32 v115, v115, v115
	v_max_f32_e32 v114, v114, v114
	v_lshl_add_u64 v[116:117], v[166:167], 2, s[12:13]
	v_max_f32_e32 v114, v114, v115
	global_atomic_umax v[116:117], v114, off
; __device__ __forceinline__ u32x4 pack8(const f32x4 v0, const f32x4 v1) { u32x4 w; w.x = cvt_pk_bf16(v0[0], v0[1]); w.y = cvt_pk_bf16(v0[2], v0[3]); w.z = cvt_pk_bf16(v1[0], v1[1]); w.w = cvt_pk_bf16(v1[2], v1[3]); return w; }
; __device__ __forceinline__ void unpack8(const u32x4 w, f32x4& v0, f32x4& v1) { v0 = (f32x4){bf_lo(w.x), bf_hi(w.x), bf_lo(w.y), bf_hi(w.y)}; v1 = (f32x4){bf_lo(w.z), bf_hi(w.z), bf_lo(w.w), bf_hi(w.w)}; }
;     __device__ __forceinline__ void operator()(AccRef acc, const Unit& u, int wr, int wc, int fr, int fq) const {
;     ...
;         for (int s = 0; s < 8; ++s) { const int ai = s >> 2, m = s & 3; const int r = row0 + ai * HALF + m * 16; bf16_t* rowp = O + (size_t)r * ldc + col0;
;                 if (MODE >= 2 && s + 1 < 8) load_row(nxt, row0 + ((s + 1) >> 2) * HALF + ((s + 1) & 3) * 16, col0);
;                 float rs = 1.f; if (MODE == 1) rs = __builtin_amdgcn_rsqf(rstd[r] * (1.0f / 4096.0f) + 1e-6f);
;                 float mx = 0.f;
; #pragma unroll
;                 for (int bj = 0; bj < 2; ++bj) { f32x4 v0 = acc[ai][bj][m][0], v1 = acc[ai][bj][m][1];
;                     if (MODE == 1) { v0 = v0 * rs; v1 = v1 * rs;
; #pragma unroll
;                         for (int j = 0; j < 4; ++j) { const float a = v0[j] > 0.f ? v0[j] : 0.f, b = v1[j] > 0.f ? v1[j] : 0.f; v0[j] = a * a; v1[j] = b * b; } }
;                     if (MODE == 2) { f32x4 g0, g1; unpack8(cur.g[bj], g0, g1); v0 = v0 * g0; v1 = v1 * g1; }
;                     if (MODE == 3) { f32x4 g0, g1, a0, a1; unpack8(cur.g[bj], g0, g1); unpack8(cur.a[bj], a0, a1);
;                         v0 = a0 + v0 * g0; v1 = a1 + v1 * g1;
; #pragma unroll
;                         for (int j = 0; j < 4; ++j) mx = fmaxf(mx, fmaxf(fabsf(v0[j]), fabsf(v1[j]))); }
;                     *(u32x4*)(rowp + bj * HALF) = pack8(v0, v1); }
;                 if (MODE == 3) { mx = fmaxf(mx, __shfl_xor(mx, 16)); mx = fmaxf(mx, __shfl_xor(mx, 32)); if (fq == 0) atomicMax(RM + r, __builtin_bit_cast(unsigned, mx)); }
;                 if (MODE >= 2) cur = nxt; }
.LBB0_1570:
	s_or_b64 exec, exec, s[26:27]
	v_or_b32_e32 v170, 32, v166
	v_ashrrev_i32_e32 v171, 31, v170
	s_waitcnt lgkmcnt(0)
	v_lshlrev_b64 v[114:115], 14, v[170:171]
	v_lshl_add_u64 v[114:115], s[8:9], 0, v[114:115]
	v_lshlrev_b64 v[174:175], 13, v[170:171]
	v_lshl_add_u64 v[114:115], v[114:115], 0, v[164:165]
	v_add_co_u32_e32 v114, vcc, 0x2000, v114
	v_lshl_add_u64 v[116:117], s[10:11], 0, v[174:175]
	s_nop 0
	v_addc_co_u32_e32 v115, vcc, 0, v115, vcc
	v_lshl_add_u64 v[116:117], v[116:117], 0, v[164:165]
	s_mov_b64 s[98:99], 0x8000
	v_lshl_add_u64 v[246:247], v[248:249], 0, s[98:99]
	global_load_dwordx4 v[126:129], v[246:247], off
	global_load_dwordx4 v[118:121], v[246:247], off offset:1024
	s_mov_b64 s[98:99], 0x8000
	v_lshl_add_u64 v[252:253], v[250:251], 0, s[98:99]
	global_load_dwordx4 v[122:125], v[252:253], off
	s_nop 0
	global_load_dwordx4 v[114:117], v[252:253], off offset:1024
	v_lshlrev_b32_e32 v182, 16, v142
	v_and_b32_e32 v183, 0xffff0000, v142
	v_lshlrev_b32_e32 v142, 16, v143
	v_and_b32_e32 v143, 0xffff0000, v143
	v_lshlrev_b32_e32 v184, 16, v144
	v_and_b32_e32 v185, 0xffff0000, v144
	v_lshlrev_b32_e32 v144, 16, v145
	v_and_b32_e32 v145, 0xffff0000, v145
	v_lshlrev_b32_e32 v186, 16, v138
	v_and_b32_e32 v187, 0xffff0000, v138
	v_lshlrev_b32_e32 v138, 16, v139
	v_and_b32_e32 v139, 0xffff0000, v139
	v_lshlrev_b32_e32 v188, 16, v140
	v_and_b32_e32 v189, 0xffff0000, v140
	v_lshlrev_b32_e32 v140, 16, v141
	v_and_b32_e32 v141, 0xffff0000, v141
	v_pk_fma_f32 v[112:113], v[112:113], v[142:143], v[138:139]
	v_pk_fma_f32 v[110:111], v[110:111], v[182:183], v[186:187]
	v_pk_fma_f32 v[138:139], v[108:109], v[144:145], v[140:141]
	v_pk_fma_f32 v[108:109], v[106:107], v[184:185], v[188:189]
	v_max_f32_e64 v140, |v113|, |v139|
	v_max_f32_e64 v106, |v110|, |v108|
	v_max_f32_e64 v107, |v111|, |v109|
	v_max3_f32 v106, v106, 0, v107
	v_max_f32_e64 v107, |v112|, |v138|
	v_max3_f32 v144, v106, v107, v140
	s_nop 0
	v_cvt_pk_bf16_f32 v106, v110, v111
	s_nop 0
	v_cvt_pk_bf16_f32 v107, v112, v113
	v_lshlrev_b32_e32 v110, 16, v134
	v_and_b32_e32 v111, 0xffff0000, v134
	v_lshlrev_b32_e32 v112, 16, v135
	v_and_b32_e32 v113, 0xffff0000, v135
	v_lshlrev_b32_e32 v134, 16, v136
	v_and_b32_e32 v135, 0xffff0000, v136
	v_lshlrev_b32_e32 v140, 16, v130
	v_and_b32_e32 v141, 0xffff0000, v130
	v_lshlrev_b32_e32 v130, 16, v131
	v_and_b32_e32 v131, 0xffff0000, v131
	v_lshlrev_b32_e32 v142, 16, v132
	v_and_b32_e32 v143, 0xffff0000, v132
	v_lshlrev_b32_e32 v136, 16, v137
	v_and_b32_e32 v137, 0xffff0000, v137
	v_lshlrev_b32_e32 v132, 16, v133
	v_and_b32_e32 v133, 0xffff0000, v133
	v_pk_fma_f32 v[104:105], v[104:105], v[112:113], v[130:131]
	v_pk_fma_f32 v[102:103], v[102:103], v[110:111], v[140:141]
	v_pk_fma_f32 v[112:113], v[98:99], v[134:135], v[142:143]
	v_pk_fma_f32 v[110:111], v[100:101], v[136:137], v[132:133]
	v_max_f32_e64 v98, |v102|, |v112|
	v_max_f32_e64 v99, |v103|, |v113|
	v_max3_f32 v98, v144, v98, v99
	v_max_f32_e64 v99, |v104|, |v110|
	v_max_f32_e64 v100, |v105|, |v111|
	v_max3_f32 v98, v98, v99, v100
	ds_bpermute_b32 v99, v180, v98
	v_lshl_add_u64 v[172:173], s[2:3], 0, v[172:173]
	v_lshl_add_u64 v[172:173], v[172:173], 0, v[164:165]
	s_nop 0
	v_cvt_pk_bf16_f32 v108, v108, v109
	s_nop 0
	v_cvt_pk_bf16_f32 v109, v138, v139
	s_waitcnt lgkmcnt(0)
	v_max_f32_e32 v99, v99, v99
	v_max_f32_e32 v98, v98, v99
	ds_bpermute_b32 v99, v181, v98
	global_store_dwordx4 v[172:173], v[106:109], off
	s_nop 0
	v_cvt_pk_bf16_f32 v100, v102, v103
	s_nop 0
	v_cvt_pk_bf16_f32 v101, v104, v105
	s_nop 0
	v_cvt_pk_bf16_f32 v102, v112, v113
	s_nop 0
	v_cvt_pk_bf16_f32 v103, v110, v111
	global_store_dwordx4 v[172:173], v[100:103], off offset:256
	s_and_saveexec_b64 s[26:27], s[6:7]
	s_cbranch_execz .LBB0_1572
	s_waitcnt lgkmcnt(0)
	v_max_f32_e32 v99, v99, v99
	v_max_f32_e32 v98, v98, v98
	v_lshl_add_u64 v[100:101], v[168:169], 2, s[12:13]
	v_max_f32_e32 v98, v98, v99
	global_atomic_umax v[100:101], v98, off
.LBB0_1572:
	s_or_b64 exec, exec, s[26:27]
	v_or_b32_e32 v130, 48, v166
	v_ashrrev_i32_e32 v131, 31, v130
	s_waitcnt lgkmcnt(0)
	v_lshlrev_b64 v[98:99], 14, v[130:131]
	v_lshl_add_u64 v[98:99], s[8:9], 0, v[98:99]
	v_lshlrev_b64 v[132:133], 13, v[130:131]
	v_lshl_add_u64 v[98:99], v[98:99], 0, v[164:165]
	v_add_co_u32_e32 v98, vcc, 0x2000, v98
	v_lshl_add_u64 v[100:101], s[10:11], 0, v[132:133]
	s_nop 0
	v_addc_co_u32_e32 v99, vcc, 0, v99, vcc
	v_lshl_add_u64 v[100:101], v[100:101], 0, v[164:165]
	s_mov_b64 s[98:99], 0xc000
	v_lshl_add_u64 v[246:247], v[248:249], 0, s[98:99]
	global_load_dwordx4 v[110:113], v[246:247], off
	global_load_dwordx4 v[102:105], v[246:247], off offset:1024
	s_mov_b64 s[98:99], 0xc000
	v_lshl_add_u64 v[252:253], v[250:251], 0, s[98:99]
	global_load_dwordx4 v[106:109], v[252:253], off
	s_nop 0
	global_load_dwordx4 v[98:101], v[252:253], off offset:1024
	s_waitcnt vmcnt(9)
	v_lshlrev_b32_e32 v136, 16, v126
	v_and_b32_e32 v137, 0xffff0000, v126
	v_lshlrev_b32_e32 v126, 16, v127
	v_and_b32_e32 v127, 0xffff0000, v127
	v_lshlrev_b32_e32 v138, 16, v128
	v_and_b32_e32 v139, 0xffff0000, v128
	v_lshlrev_b32_e32 v128, 16, v129
	v_and_b32_e32 v129, 0xffff0000, v129
	s_waitcnt vmcnt(7)
; __device__ __forceinline__ u32x4 pack8(const f32x4 v0, const f32x4 v1) { u32x4 w; w.x = cvt_pk_bf16(v0[0], v0[1]); w.y = cvt_pk_bf16(v0[2], v0[3]); w.z = cvt_pk_bf16(v1[0], v1[1]); w.w = cvt_pk_bf16(v1[2], v1[3]); return w; }
; __device__ __forceinline__ void unpack8(const u32x4 w, f32x4& v0, f32x4& v1) { v0 = (f32x4){bf_lo(w.x), bf_hi(w.x), bf_lo(w.y), bf_hi(w.y)}; v1 = (f32x4){bf_lo(w.z), bf_hi(w.z), bf_lo(w.w), bf_hi(w.w)}; }
;     __device__ __forceinline__ void operator()(AccRef acc, const Unit& u, int wr, int wc, int fr, int fq) const {
;     ...
;         for (int s = 0; s < 8; ++s) { const int ai = s >> 2, m = s & 3; const int r = row0 + ai * HALF + m * 16; bf16_t* rowp = O + (size_t)r * ldc + col0;
;                 if (MODE >= 2 && s + 1 < 8) load_row(nxt, row0 + ((s + 1) >> 2) * HALF + ((s + 1) & 3) * 16, col0);
;                 float rs = 1.f; if (MODE == 1) rs = __builtin_amdgcn_rsqf(rstd[r] * (1.0f / 4096.0f) + 1e-6f);
;                 float mx = 0.f;
; #pragma unroll
;                 for (int bj = 0; bj < 2; ++bj) { f32x4 v0 = acc[ai][bj][m][0], v1 = acc[ai][bj][m][1];
;                     if (MODE == 1) { v0 = v0 * rs; v1 = v1 * rs;
; #pragma unroll
;                         for (int j = 0; j < 4; ++j) { const float a = v0[j] > 0.f ? v0[j] : 0.f, b = v1[j] > 0.f ? v1[j] : 0.f; v0[j] = a * a; v1[j] = b * b; } }
;                     if (MODE == 2) { f32x4 g0, g1; unpack8(cur.g[bj], g0, g1); v0 = v0 * g0; v1 = v1 * g1; }
;                     if (MODE == 3) { f32x4 g0, g1, a0, a1; unpack8(cur.g[bj], g0, g1); unpack8(cur.a[bj], a0, a1);
;                         v0 = a0 + v0 * g0; v1 = a1 + v1 * g1;
; #pragma unroll
;                         for (int j = 0; j < 4; ++j) mx = fmaxf(mx, fmaxf(fabsf(v0[j]), fabsf(v1[j]))); }
;                     *(u32x4*)(rowp + bj * HALF) = pack8(v0, v1); }
;                 if (MODE == 3) { mx = fmaxf(mx, __shfl_xor(mx, 16)); mx = fmaxf(mx, __shfl_xor(mx, 32)); if (fq == 0) atomicMax(RM + r, __builtin_bit_cast(unsigned, mx)); }
;                 if (MODE >= 2) cur = nxt; }
	v_lshlrev_b32_e32 v140, 16, v122
	v_and_b32_e32 v141, 0xffff0000, v122
	v_lshlrev_b32_e32 v122, 16, v123
	v_and_b32_e32 v123, 0xffff0000, v123
	v_lshlrev_b32_e32 v142, 16, v124
	v_and_b32_e32 v143, 0xffff0000, v124
	v_lshlrev_b32_e32 v124, 16, v125
	v_and_b32_e32 v125, 0xffff0000, v125
	v_pk_fma_f32 v[96:97], v[96:97], v[126:127], v[122:123]
	v_pk_fma_f32 v[94:95], v[94:95], v[136:137], v[140:141]
	v_pk_fma_f32 v[122:123], v[92:93], v[128:129], v[124:125]
	v_pk_fma_f32 v[92:93], v[90:91], v[138:139], v[142:143]
	v_max_f32_e64 v124, |v97|, |v123|
	v_max_f32_e64 v90, |v94|, |v92|
	v_max_f32_e64 v91, |v95|, |v93|
	v_max3_f32 v90, v90, 0, v91
	v_max_f32_e64 v91, |v96|, |v122|
	v_max3_f32 v128, v90, v91, v124
	s_nop 0
	v_cvt_pk_bf16_f32 v90, v94, v95
	s_nop 0
	v_cvt_pk_bf16_f32 v91, v96, v97
	v_lshlrev_b32_e32 v94, 16, v118
	v_and_b32_e32 v95, 0xffff0000, v118
	v_lshlrev_b32_e32 v96, 16, v119
	v_and_b32_e32 v97, 0xffff0000, v119
	v_lshlrev_b32_e32 v118, 16, v120
	v_and_b32_e32 v119, 0xffff0000, v120
	s_waitcnt vmcnt(6)
	v_lshlrev_b32_e32 v124, 16, v114
	v_and_b32_e32 v125, 0xffff0000, v114
	v_lshlrev_b32_e32 v114, 16, v115
	v_and_b32_e32 v115, 0xffff0000, v115
	v_lshlrev_b32_e32 v126, 16, v116
	v_and_b32_e32 v127, 0xffff0000, v116
	v_lshlrev_b32_e32 v120, 16, v121
	v_and_b32_e32 v121, 0xffff0000, v121
	v_lshlrev_b32_e32 v116, 16, v117
	v_and_b32_e32 v117, 0xffff0000, v117
	v_pk_fma_f32 v[88:89], v[88:89], v[96:97], v[114:115]
	v_pk_fma_f32 v[86:87], v[86:87], v[94:95], v[124:125]
	v_pk_fma_f32 v[96:97], v[82:83], v[118:119], v[126:127]
	v_pk_fma_f32 v[94:95], v[84:85], v[120:121], v[116:117]
	v_max_f32_e64 v82, |v86|, |v96|
	v_max_f32_e64 v83, |v87|, |v97|
	v_max3_f32 v82, v128, v82, v83
	v_max_f32_e64 v83, |v88|, |v94|
	v_max_f32_e64 v84, |v89|, |v95|
	v_max3_f32 v82, v82, v83, v84
	ds_bpermute_b32 v83, v180, v82
	v_lshl_add_u64 v[134:135], s[2:3], 0, v[174:175]
	v_lshl_add_u64 v[134:135], v[134:135], 0, v[164:165]
	s_nop 0
	v_cvt_pk_bf16_f32 v92, v92, v93
	s_nop 0
	v_cvt_pk_bf16_f32 v93, v122, v123
	s_waitcnt lgkmcnt(0)
	v_max_f32_e32 v83, v83, v83
	v_max_f32_e32 v82, v82, v83
	ds_bpermute_b32 v83, v181, v82
	global_store_dwordx4 v[134:135], v[90:93], off
	s_nop 0
	v_cvt_pk_bf16_f32 v84, v86, v87
	s_nop 0
	v_cvt_pk_bf16_f32 v85, v88, v89
	s_nop 0
	v_cvt_pk_bf16_f32 v86, v96, v97
	s_nop 0
	v_cvt_pk_bf16_f32 v87, v94, v95
	global_store_dwordx4 v[134:135], v[84:87], off offset:256
	s_and_saveexec_b64 s[26:27], s[6:7]
	s_cbranch_execz .LBB0_1574
	s_waitcnt lgkmcnt(0)
	v_max_f32_e32 v83, v83, v83
	v_max_f32_e32 v82, v82, v82
	v_lshl_add_u64 v[84:85], v[170:171], 2, s[12:13]
	v_max_f32_e32 v82, v82, v83
	global_atomic_umax v[84:85], v82, off
.LBB0_1574:
	s_or_b64 exec, exec, s[26:27]
	v_add_u32_e32 v114, 0x80, v166
	v_ashrrev_i32_e32 v115, 31, v114
	s_waitcnt lgkmcnt(0)
	v_lshlrev_b64 v[82:83], 14, v[114:115]
	v_lshl_add_u64 v[82:83], s[8:9], 0, v[82:83]
	v_lshlrev_b64 v[116:117], 13, v[114:115]
	v_lshl_add_u64 v[82:83], v[82:83], 0, v[164:165]
	v_add_co_u32_e32 v82, vcc, 0x2000, v82
	v_lshl_add_u64 v[84:85], s[10:11], 0, v[116:117]
	s_nop 0
	v_addc_co_u32_e32 v83, vcc, 0, v83, vcc
	v_lshl_add_u64 v[84:85], v[84:85], 0, v[164:165]
	s_mov_b64 s[98:99], 0x10000
	v_lshl_add_u64 v[246:247], v[248:249], 0, s[98:99]
	global_load_dwordx4 v[94:97], v[246:247], off
	global_load_dwordx4 v[86:89], v[246:247], off offset:1024
	s_mov_b64 s[98:99], 0x10000
	v_lshl_add_u64 v[252:253], v[250:251], 0, s[98:99]
	global_load_dwordx4 v[90:93], v[252:253], off
	s_nop 0
	global_load_dwordx4 v[82:85], v[252:253], off offset:1024
	s_waitcnt vmcnt(9)
	v_lshlrev_b32_e32 v120, 16, v110
	v_and_b32_e32 v121, 0xffff0000, v110
	v_lshlrev_b32_e32 v110, 16, v111
	v_and_b32_e32 v111, 0xffff0000, v111
	v_lshlrev_b32_e32 v122, 16, v112
	v_and_b32_e32 v123, 0xffff0000, v112
	v_lshlrev_b32_e32 v112, 16, v113
	v_and_b32_e32 v113, 0xffff0000, v113
	s_waitcnt vmcnt(7)
	v_lshlrev_b32_e32 v124, 16, v106
	v_and_b32_e32 v125, 0xffff0000, v106
	v_lshlrev_b32_e32 v106, 16, v107
	v_and_b32_e32 v107, 0xffff0000, v107
	v_lshlrev_b32_e32 v126, 16, v108
	v_and_b32_e32 v127, 0xffff0000, v108
	v_lshlrev_b32_e32 v108, 16, v109
	v_and_b32_e32 v109, 0xffff0000, v109
	v_pk_fma_f32 v[80:81], v[80:81], v[110:111], v[106:107]
	v_pk_fma_f32 v[78:79], v[78:79], v[120:121], v[124:125]
	v_pk_fma_f32 v[106:107], v[76:77], v[112:113], v[108:109]
	v_pk_fma_f32 v[76:77], v[74:75], v[122:123], v[126:127]
	v_max_f32_e64 v108, |v81|, |v107|
	v_max_f32_e64 v74, |v78|, |v76|
	v_max_f32_e64 v75, |v79|, |v77|
	v_max3_f32 v74, v74, 0, v75
	v_max_f32_e64 v75, |v80|, |v106|
	v_max3_f32 v112, v74, v75, v108
	s_nop 0
	v_cvt_pk_bf16_f32 v74, v78, v79
	s_nop 0
	v_cvt_pk_bf16_f32 v75, v80, v81
	v_lshlrev_b32_e32 v78, 16, v102
	v_and_b32_e32 v79, 0xffff0000, v102
	v_lshlrev_b32_e32 v80, 16, v103
	v_and_b32_e32 v81, 0xffff0000, v103
	v_lshlrev_b32_e32 v102, 16, v104
	v_and_b32_e32 v103, 0xffff0000, v104
	s_waitcnt vmcnt(6)
	v_lshlrev_b32_e32 v108, 16, v98
	v_and_b32_e32 v109, 0xffff0000, v98
	v_lshlrev_b32_e32 v98, 16, v99
	v_and_b32_e32 v99, 0xffff0000, v99
	v_lshlrev_b32_e32 v110, 16, v100
	v_and_b32_e32 v111, 0xffff0000, v100
	v_lshlrev_b32_e32 v104, 16, v105
	v_and_b32_e32 v105, 0xffff0000, v105
	v_lshlrev_b32_e32 v100, 16, v101
	v_and_b32_e32 v101, 0xffff0000, v101
	v_pk_fma_f32 v[72:73], v[72:73], v[80:81], v[98:99]
	v_pk_fma_f32 v[70:71], v[70:71], v[78:79], v[108:109]
	v_pk_fma_f32 v[80:81], v[66:67], v[102:103], v[110:111]
	v_pk_fma_f32 v[78:79], v[68:69], v[104:105], v[100:101]
	v_max_f32_e64 v66, |v70|, |v80|
	v_max_f32_e64 v67, |v71|, |v81|
	v_max3_f32 v66, v112, v66, v67
	v_max_f32_e64 v67, |v72|, |v78|
	v_max_f32_e64 v68, |v73|, |v79|
	v_max3_f32 v66, v66, v67, v68
	ds_bpermute_b32 v67, v180, v66
	v_lshl_add_u64 v[118:119], s[2:3], 0, v[132:133]
	v_lshl_add_u64 v[118:119], v[118:119], 0, v[164:165]
	s_nop 0
	v_cvt_pk_bf16_f32 v76, v76, v77
	s_nop 0
	v_cvt_pk_bf16_f32 v77, v106, v107
	s_waitcnt lgkmcnt(0)
	v_max_f32_e32 v67, v67, v67
	v_max_f32_e32 v66, v66, v67
	ds_bpermute_b32 v67, v181, v66
	global_store_dwordx4 v[118:119], v[74:77], off
	s_nop 0
	v_cvt_pk_bf16_f32 v68, v70, v71
	s_nop 0
	v_cvt_pk_bf16_f32 v69, v72, v73
	s_nop 0
	v_cvt_pk_bf16_f32 v70, v80, v81
	s_nop 0
	v_cvt_pk_bf16_f32 v71, v78, v79
	global_store_dwordx4 v[118:119], v[68:71], off offset:256
	s_and_saveexec_b64 s[26:27], s[6:7]
	s_cbranch_execz .LBB0_1576
	s_waitcnt lgkmcnt(0)
	v_max_f32_e32 v67, v67, v67
	v_max_f32_e32 v66, v66, v66
	v_lshl_add_u64 v[68:69], v[130:131], 2, s[12:13]
	v_max_f32_e32 v66, v66, v67
	global_atomic_umax v[68:69], v66, off
; __device__ __forceinline__ u32x4 pack8(const f32x4 v0, const f32x4 v1) { u32x4 w; w.x = cvt_pk_bf16(v0[0], v0[1]); w.y = cvt_pk_bf16(v0[2], v0[3]); w.z = cvt_pk_bf16(v1[0], v1[1]); w.w = cvt_pk_bf16(v1[2], v1[3]); return w; }
; __device__ __forceinline__ void unpack8(const u32x4 w, f32x4& v0, f32x4& v1) { v0 = (f32x4){bf_lo(w.x), bf_hi(w.x), bf_lo(w.y), bf_hi(w.y)}; v1 = (f32x4){bf_lo(w.z), bf_hi(w.z), bf_lo(w.w), bf_hi(w.w)}; }
;     __device__ __forceinline__ void operator()(AccRef acc, const Unit& u, int wr, int wc, int fr, int fq) const {
;     ...
;         for (int s = 0; s < 8; ++s) { const int ai = s >> 2, m = s & 3; const int r = row0 + ai * HALF + m * 16; bf16_t* rowp = O + (size_t)r * ldc + col0;
;                 if (MODE >= 2 && s + 1 < 8) load_row(nxt, row0 + ((s + 1) >> 2) * HALF + ((s + 1) & 3) * 16, col0);
;                 float rs = 1.f; if (MODE == 1) rs = __builtin_amdgcn_rsqf(rstd[r] * (1.0f / 4096.0f) + 1e-6f);
;                 float mx = 0.f;
; #pragma unroll
;                 for (int bj = 0; bj < 2; ++bj) { f32x4 v0 = acc[ai][bj][m][0], v1 = acc[ai][bj][m][1];
;                     if (MODE == 1) { v0 = v0 * rs; v1 = v1 * rs;
; #pragma unroll
;                         for (int j = 0; j < 4; ++j) { const float a = v0[j] > 0.f ? v0[j] : 0.f, b = v1[j] > 0.f ? v1[j] : 0.f; v0[j] = a * a; v1[j] = b * b; } }
;                     if (MODE == 2) { f32x4 g0, g1; unpack8(cur.g[bj], g0, g1); v0 = v0 * g0; v1 = v1 * g1; }
;                     if (MODE == 3) { f32x4 g0, g1, a0, a1; unpack8(cur.g[bj], g0, g1); unpack8(cur.a[bj], a0, a1);
;                         v0 = a0 + v0 * g0; v1 = a1 + v1 * g1;
; #pragma unroll
;                         for (int j = 0; j < 4; ++j) mx = fmaxf(mx, fmaxf(fabsf(v0[j]), fabsf(v1[j]))); }
;                     *(u32x4*)(rowp + bj * HALF) = pack8(v0, v1); }
;                 if (MODE == 3) { mx = fmaxf(mx, __shfl_xor(mx, 16)); mx = fmaxf(mx, __shfl_xor(mx, 32)); if (fq == 0) atomicMax(RM + r, __builtin_bit_cast(unsigned, mx)); }
;                 if (MODE >= 2) cur = nxt; }
.LBB0_1576:
	s_or_b64 exec, exec, s[26:27]
	v_or_b32_e32 v98, 16, v114
	v_ashrrev_i32_e32 v99, 31, v98
	s_waitcnt lgkmcnt(0)
	v_lshlrev_b64 v[66:67], 14, v[98:99]
	v_lshl_add_u64 v[66:67], s[8:9], 0, v[66:67]
	v_lshlrev_b64 v[100:101], 13, v[98:99]
	v_lshl_add_u64 v[66:67], v[66:67], 0, v[164:165]
	v_add_co_u32_e32 v66, vcc, 0x2000, v66
	v_lshl_add_u64 v[68:69], s[10:11], 0, v[100:101]
	s_nop 0
	v_addc_co_u32_e32 v67, vcc, 0, v67, vcc
	v_lshl_add_u64 v[68:69], v[68:69], 0, v[164:165]
	s_mov_b64 s[98:99], 0x14000
	v_lshl_add_u64 v[246:247], v[248:249], 0, s[98:99]
	global_load_dwordx4 v[78:81], v[246:247], off
	global_load_dwordx4 v[70:73], v[246:247], off offset:1024
	s_mov_b64 s[98:99], 0x14000
	v_lshl_add_u64 v[252:253], v[250:251], 0, s[98:99]
	global_load_dwordx4 v[74:77], v[252:253], off
	s_nop 0
	global_load_dwordx4 v[66:69], v[252:253], off offset:1024
	s_waitcnt vmcnt(9)
	v_lshlrev_b32_e32 v104, 16, v94
	v_and_b32_e32 v105, 0xffff0000, v94
	v_lshlrev_b32_e32 v94, 16, v95
	v_and_b32_e32 v95, 0xffff0000, v95
	v_lshlrev_b32_e32 v106, 16, v96
	v_and_b32_e32 v107, 0xffff0000, v96
	v_lshlrev_b32_e32 v96, 16, v97
	v_and_b32_e32 v97, 0xffff0000, v97
	s_waitcnt vmcnt(7)
	v_lshlrev_b32_e32 v108, 16, v90
	v_and_b32_e32 v109, 0xffff0000, v90
	v_lshlrev_b32_e32 v90, 16, v91
	v_and_b32_e32 v91, 0xffff0000, v91
	v_lshlrev_b32_e32 v110, 16, v92
	v_and_b32_e32 v111, 0xffff0000, v92
	v_lshlrev_b32_e32 v92, 16, v93
	v_and_b32_e32 v93, 0xffff0000, v93
	v_pk_fma_f32 v[64:65], v[64:65], v[94:95], v[90:91]
	v_pk_fma_f32 v[62:63], v[62:63], v[104:105], v[108:109]
	v_pk_fma_f32 v[90:91], v[60:61], v[96:97], v[92:93]
	v_pk_fma_f32 v[60:61], v[58:59], v[106:107], v[110:111]
	v_max_f32_e64 v92, |v65|, |v91|
	v_max_f32_e64 v58, |v62|, |v60|
	v_max_f32_e64 v59, |v63|, |v61|
	v_max3_f32 v58, v58, 0, v59
	v_max_f32_e64 v59, |v64|, |v90|
	v_max3_f32 v96, v58, v59, v92
	s_nop 0
	v_cvt_pk_bf16_f32 v58, v62, v63
	s_nop 0
	v_cvt_pk_bf16_f32 v59, v64, v65
	v_lshlrev_b32_e32 v62, 16, v86
	v_and_b32_e32 v63, 0xffff0000, v86
	v_lshlrev_b32_e32 v64, 16, v87
	v_and_b32_e32 v65, 0xffff0000, v87
	v_lshlrev_b32_e32 v86, 16, v88
	v_and_b32_e32 v87, 0xffff0000, v88
	s_waitcnt vmcnt(6)
	v_lshlrev_b32_e32 v92, 16, v82
	v_and_b32_e32 v93, 0xffff0000, v82
	v_lshlrev_b32_e32 v82, 16, v83
	v_and_b32_e32 v83, 0xffff0000, v83
	v_lshlrev_b32_e32 v94, 16, v84
	v_and_b32_e32 v95, 0xffff0000, v84
	v_lshlrev_b32_e32 v88, 16, v89
	v_and_b32_e32 v89, 0xffff0000, v89
	v_lshlrev_b32_e32 v84, 16, v85
	v_and_b32_e32 v85, 0xffff0000, v85
	v_pk_fma_f32 v[56:57], v[56:57], v[64:65], v[82:83]
	v_pk_fma_f32 v[54:55], v[54:55], v[62:63], v[92:93]
	v_pk_fma_f32 v[64:65], v[50:51], v[86:87], v[94:95]
	v_pk_fma_f32 v[62:63], v[52:53], v[88:89], v[84:85]
	v_max_f32_e64 v50, |v54|, |v64|
	v_max_f32_e64 v51, |v55|, |v65|
	v_max3_f32 v50, v96, v50, v51
	v_max_f32_e64 v51, |v56|, |v62|
	v_max_f32_e64 v52, |v57|, |v63|
	v_max3_f32 v50, v50, v51, v52
	ds_bpermute_b32 v51, v180, v50
	v_lshl_add_u64 v[102:103], s[2:3], 0, v[116:117]
	v_lshl_add_u64 v[102:103], v[102:103], 0, v[164:165]
	s_nop 0
	v_cvt_pk_bf16_f32 v60, v60, v61
	s_nop 0
	v_cvt_pk_bf16_f32 v61, v90, v91
	s_waitcnt lgkmcnt(0)
	v_max_f32_e32 v51, v51, v51
	v_max_f32_e32 v50, v50, v51
	ds_bpermute_b32 v51, v181, v50
	global_store_dwordx4 v[102:103], v[58:61], off
	s_nop 0
	v_cvt_pk_bf16_f32 v52, v54, v55
	s_nop 0
	v_cvt_pk_bf16_f32 v53, v56, v57
	s_nop 0
	v_cvt_pk_bf16_f32 v54, v64, v65
	s_nop 0
	v_cvt_pk_bf16_f32 v55, v62, v63
	global_store_dwordx4 v[102:103], v[52:55], off offset:256
	s_and_saveexec_b64 s[26:27], s[6:7]
	s_cbranch_execz .LBB0_1578
	s_waitcnt lgkmcnt(0)
	v_max_f32_e32 v51, v51, v51
	v_max_f32_e32 v50, v50, v50
	v_lshl_add_u64 v[52:53], v[114:115], 2, s[12:13]
	v_max_f32_e32 v50, v50, v51
	global_atomic_umax v[52:53], v50, off
.LBB0_1578:
	s_or_b64 exec, exec, s[26:27]
	v_or_b32_e32 v82, 32, v114
	v_ashrrev_i32_e32 v83, 31, v82
	s_waitcnt lgkmcnt(0)
	v_lshlrev_b64 v[50:51], 14, v[82:83]
	v_lshl_add_u64 v[50:51], s[8:9], 0, v[50:51]
	v_lshlrev_b64 v[84:85], 13, v[82:83]
	v_lshl_add_u64 v[50:51], v[50:51], 0, v[164:165]
	v_add_co_u32_e32 v50, vcc, 0x2000, v50
	v_lshl_add_u64 v[52:53], s[10:11], 0, v[84:85]
	s_nop 0
	v_addc_co_u32_e32 v51, vcc, 0, v51, vcc
	v_lshl_add_u64 v[52:53], v[52:53], 0, v[164:165]
	s_mov_b64 s[98:99], 0x18000
	v_lshl_add_u64 v[246:247], v[248:249], 0, s[98:99]
	global_load_dwordx4 v[62:65], v[246:247], off
	global_load_dwordx4 v[54:57], v[246:247], off offset:1024
	s_mov_b64 s[98:99], 0x18000
	v_lshl_add_u64 v[252:253], v[250:251], 0, s[98:99]
	global_load_dwordx4 v[58:61], v[252:253], off
	s_nop 0
	global_load_dwordx4 v[50:53], v[252:253], off offset:1024
	s_waitcnt vmcnt(9)
	v_lshlrev_b32_e32 v88, 16, v78
	v_and_b32_e32 v89, 0xffff0000, v78
	v_lshlrev_b32_e32 v78, 16, v79
	v_and_b32_e32 v79, 0xffff0000, v79
	v_lshlrev_b32_e32 v90, 16, v80
	v_and_b32_e32 v91, 0xffff0000, v80
	v_lshlrev_b32_e32 v80, 16, v81
	v_and_b32_e32 v81, 0xffff0000, v81
	s_waitcnt vmcnt(7)
	v_lshlrev_b32_e32 v92, 16, v74
	v_and_b32_e32 v93, 0xffff0000, v74
	v_lshlrev_b32_e32 v74, 16, v75
	v_and_b32_e32 v75, 0xffff0000, v75
	v_lshlrev_b32_e32 v94, 16, v76
	v_and_b32_e32 v95, 0xffff0000, v76
	v_lshlrev_b32_e32 v76, 16, v77
	v_and_b32_e32 v77, 0xffff0000, v77
	v_pk_fma_f32 v[48:49], v[48:49], v[78:79], v[74:75]
	v_pk_fma_f32 v[46:47], v[46:47], v[88:89], v[92:93]
	v_pk_fma_f32 v[74:75], v[44:45], v[80:81], v[76:77]
	v_pk_fma_f32 v[44:45], v[42:43], v[90:91], v[94:95]
	v_max_f32_e64 v76, |v49|, |v75|
	v_max_f32_e64 v42, |v46|, |v44|
	v_max_f32_e64 v43, |v47|, |v45|
	v_max3_f32 v42, v42, 0, v43
	v_max_f32_e64 v43, |v48|, |v74|
	v_max3_f32 v80, v42, v43, v76
	s_nop 0
	v_cvt_pk_bf16_f32 v42, v46, v47
	s_nop 0
	v_cvt_pk_bf16_f32 v43, v48, v49
	v_lshlrev_b32_e32 v46, 16, v70
	v_and_b32_e32 v47, 0xffff0000, v70
	v_lshlrev_b32_e32 v48, 16, v71
	v_and_b32_e32 v49, 0xffff0000, v71
	v_lshlrev_b32_e32 v70, 16, v72
	v_and_b32_e32 v71, 0xffff0000, v72
	s_waitcnt vmcnt(6)
; __device__ __forceinline__ u32x4 pack8(const f32x4 v0, const f32x4 v1) { u32x4 w; w.x = cvt_pk_bf16(v0[0], v0[1]); w.y = cvt_pk_bf16(v0[2], v0[3]); w.z = cvt_pk_bf16(v1[0], v1[1]); w.w = cvt_pk_bf16(v1[2], v1[3]); return w; }
; __device__ __forceinline__ void unpack8(const u32x4 w, f32x4& v0, f32x4& v1) { v0 = (f32x4){bf_lo(w.x), bf_hi(w.x), bf_lo(w.y), bf_hi(w.y)}; v1 = (f32x4){bf_lo(w.z), bf_hi(w.z), bf_lo(w.w), bf_hi(w.w)}; }
;     __device__ __forceinline__ void operator()(AccRef acc, const Unit& u, int wr, int wc, int fr, int fq) const {
;     ...
;         for (int s = 0; s < 8; ++s) { const int ai = s >> 2, m = s & 3; const int r = row0 + ai * HALF + m * 16; bf16_t* rowp = O + (size_t)r * ldc + col0;
;                 if (MODE >= 2 && s + 1 < 8) load_row(nxt, row0 + ((s + 1) >> 2) * HALF + ((s + 1) & 3) * 16, col0);
;                 float rs = 1.f; if (MODE == 1) rs = __builtin_amdgcn_rsqf(rstd[r] * (1.0f / 4096.0f) + 1e-6f);
;                 float mx = 0.f;
; #pragma unroll
;                 for (int bj = 0; bj < 2; ++bj) { f32x4 v0 = acc[ai][bj][m][0], v1 = acc[ai][bj][m][1];
;                     if (MODE == 1) { v0 = v0 * rs; v1 = v1 * rs;
; #pragma unroll
;                         for (int j = 0; j < 4; ++j) { const float a = v0[j] > 0.f ? v0[j] : 0.f, b = v1[j] > 0.f ? v1[j] : 0.f; v0[j] = a * a; v1[j] = b * b; } }
;                     if (MODE == 2) { f32x4 g0, g1; unpack8(cur.g[bj], g0, g1); v0 = v0 * g0; v1 = v1 * g1; }
;                     if (MODE == 3) { f32x4 g0, g1, a0, a1; unpack8(cur.g[bj], g0, g1); unpack8(cur.a[bj], a0, a1);
;                         v0 = a0 + v0 * g0; v1 = a1 + v1 * g1;
; #pragma unroll
;                         for (int j = 0; j < 4; ++j) mx = fmaxf(mx, fmaxf(fabsf(v0[j]), fabsf(v1[j]))); }
;                     *(u32x4*)(rowp + bj * HALF) = pack8(v0, v1); }
;                 if (MODE == 3) { mx = fmaxf(mx, __shfl_xor(mx, 16)); mx = fmaxf(mx, __shfl_xor(mx, 32)); if (fq == 0) atomicMax(RM + r, __builtin_bit_cast(unsigned, mx)); }
;                 if (MODE >= 2) cur = nxt; }
	v_lshlrev_b32_e32 v76, 16, v66
	v_and_b32_e32 v77, 0xffff0000, v66
	v_lshlrev_b32_e32 v66, 16, v67
	v_and_b32_e32 v67, 0xffff0000, v67
	v_lshlrev_b32_e32 v78, 16, v68
	v_and_b32_e32 v79, 0xffff0000, v68
	v_lshlrev_b32_e32 v72, 16, v73
	v_and_b32_e32 v73, 0xffff0000, v73
	v_lshlrev_b32_e32 v68, 16, v69
	v_and_b32_e32 v69, 0xffff0000, v69
	v_pk_fma_f32 v[40:41], v[40:41], v[48:49], v[66:67]
	v_pk_fma_f32 v[38:39], v[38:39], v[46:47], v[76:77]
	v_pk_fma_f32 v[48:49], v[34:35], v[70:71], v[78:79]
	v_pk_fma_f32 v[46:47], v[36:37], v[72:73], v[68:69]
	v_max_f32_e64 v34, |v38|, |v48|
	v_max_f32_e64 v35, |v39|, |v49|
	v_max3_f32 v34, v80, v34, v35
	v_max_f32_e64 v35, |v40|, |v46|
	v_max_f32_e64 v36, |v41|, |v47|
	v_max3_f32 v34, v34, v35, v36
	ds_bpermute_b32 v35, v180, v34
	v_lshl_add_u64 v[86:87], s[2:3], 0, v[100:101]
	v_lshl_add_u64 v[86:87], v[86:87], 0, v[164:165]
	s_nop 0
	v_cvt_pk_bf16_f32 v44, v44, v45
	s_nop 0
	v_cvt_pk_bf16_f32 v45, v74, v75
	s_waitcnt lgkmcnt(0)
	v_max_f32_e32 v35, v35, v35
	v_max_f32_e32 v34, v34, v35
	ds_bpermute_b32 v35, v181, v34
	global_store_dwordx4 v[86:87], v[42:45], off
	s_nop 0
	v_cvt_pk_bf16_f32 v36, v38, v39
	s_nop 0
	v_cvt_pk_bf16_f32 v37, v40, v41
	s_nop 0
	v_cvt_pk_bf16_f32 v38, v48, v49
	s_nop 0
	v_cvt_pk_bf16_f32 v39, v46, v47
	global_store_dwordx4 v[86:87], v[36:39], off offset:256
	s_and_saveexec_b64 s[26:27], s[6:7]
	s_cbranch_execz .LBB0_1580
	s_waitcnt lgkmcnt(0)
	v_max_f32_e32 v35, v35, v35
	v_max_f32_e32 v34, v34, v34
	v_lshl_add_u64 v[36:37], v[98:99], 2, s[12:13]
	v_max_f32_e32 v34, v34, v35
	global_atomic_umax v[36:37], v34, off
.LBB0_1580:
	s_or_b64 exec, exec, s[26:27]
	v_or_b32_e32 v66, 48, v114
	v_ashrrev_i32_e32 v67, 31, v66
	s_waitcnt lgkmcnt(0)
	v_lshlrev_b64 v[34:35], 14, v[66:67]
	v_lshl_add_u64 v[34:35], s[8:9], 0, v[34:35]
	v_lshlrev_b64 v[68:69], 13, v[66:67]
	v_lshl_add_u64 v[34:35], v[34:35], 0, v[164:165]
	v_add_co_u32_e32 v34, vcc, 0x2000, v34
	v_lshl_add_u64 v[36:37], s[10:11], 0, v[68:69]
	s_nop 0
	v_addc_co_u32_e32 v35, vcc, 0, v35, vcc
	v_lshl_add_u64 v[36:37], v[36:37], 0, v[164:165]
	s_mov_b64 s[98:99], 0x1c000
	v_lshl_add_u64 v[246:247], v[248:249], 0, s[98:99]
	global_load_dwordx4 v[46:49], v[246:247], off
	global_load_dwordx4 v[38:41], v[246:247], off offset:1024
	s_mov_b64 s[98:99], 0x1c000
	v_lshl_add_u64 v[252:253], v[250:251], 0, s[98:99]
	global_load_dwordx4 v[42:45], v[252:253], off
	s_nop 0
	global_load_dwordx4 v[34:37], v[252:253], off offset:1024
	s_waitcnt vmcnt(9)
	v_lshlrev_b32_e32 v72, 16, v62
	v_and_b32_e32 v73, 0xffff0000, v62
	v_lshlrev_b32_e32 v62, 16, v63
	v_and_b32_e32 v63, 0xffff0000, v63
	v_lshlrev_b32_e32 v74, 16, v64
	v_and_b32_e32 v75, 0xffff0000, v64
	v_lshlrev_b32_e32 v64, 16, v65
	v_and_b32_e32 v65, 0xffff0000, v65
	s_waitcnt vmcnt(7)
	v_lshlrev_b32_e32 v76, 16, v58
	v_and_b32_e32 v77, 0xffff0000, v58
	v_lshlrev_b32_e32 v58, 16, v59
	v_and_b32_e32 v59, 0xffff0000, v59
	v_lshlrev_b32_e32 v78, 16, v60
	v_and_b32_e32 v79, 0xffff0000, v60
	v_lshlrev_b32_e32 v60, 16, v61
	v_and_b32_e32 v61, 0xffff0000, v61
	v_pk_fma_f32 v[32:33], v[32:33], v[62:63], v[58:59]
	v_pk_fma_f32 v[30:31], v[30:31], v[72:73], v[76:77]
	v_pk_fma_f32 v[58:59], v[28:29], v[64:65], v[60:61]
	v_pk_fma_f32 v[28:29], v[26:27], v[74:75], v[78:79]
	v_max_f32_e64 v60, |v33|, |v59|
	v_max_f32_e64 v26, |v30|, |v28|
	v_max_f32_e64 v27, |v31|, |v29|
	v_max3_f32 v26, v26, 0, v27
	v_max_f32_e64 v27, |v32|, |v58|
	v_max3_f32 v64, v26, v27, v60
	s_nop 0
	v_cvt_pk_bf16_f32 v26, v30, v31
	s_nop 0
	v_cvt_pk_bf16_f32 v27, v32, v33
	v_lshlrev_b32_e32 v30, 16, v54
	v_and_b32_e32 v31, 0xffff0000, v54
	v_lshlrev_b32_e32 v32, 16, v55
	v_and_b32_e32 v33, 0xffff0000, v55
	v_lshlrev_b32_e32 v54, 16, v56
	v_and_b32_e32 v55, 0xffff0000, v56
	s_waitcnt vmcnt(6)
	v_lshlrev_b32_e32 v60, 16, v50
	v_and_b32_e32 v61, 0xffff0000, v50
	v_lshlrev_b32_e32 v50, 16, v51
	v_and_b32_e32 v51, 0xffff0000, v51
	v_lshlrev_b32_e32 v62, 16, v52
	v_and_b32_e32 v63, 0xffff0000, v52
	v_lshlrev_b32_e32 v56, 16, v57
	v_and_b32_e32 v57, 0xffff0000, v57
	v_lshlrev_b32_e32 v52, 16, v53
	v_and_b32_e32 v53, 0xffff0000, v53
	v_pk_fma_f32 v[24:25], v[24:25], v[32:33], v[50:51]
	v_pk_fma_f32 v[22:23], v[22:23], v[30:31], v[60:61]
	v_pk_fma_f32 v[32:33], v[18:19], v[54:55], v[62:63]
	v_pk_fma_f32 v[30:31], v[20:21], v[56:57], v[52:53]
	v_max_f32_e64 v18, |v22|, |v32|
	v_max_f32_e64 v19, |v23|, |v33|
	v_max3_f32 v18, v64, v18, v19
	v_max_f32_e64 v19, |v24|, |v30|
	v_max_f32_e64 v20, |v25|, |v31|
	v_max3_f32 v18, v18, v19, v20
	ds_bpermute_b32 v19, v180, v18
	v_lshl_add_u64 v[70:71], s[2:3], 0, v[84:85]
	v_lshl_add_u64 v[70:71], v[70:71], 0, v[164:165]
	s_nop 0
	v_cvt_pk_bf16_f32 v28, v28, v29
	s_nop 0
	v_cvt_pk_bf16_f32 v29, v58, v59
	s_waitcnt lgkmcnt(0)
	v_max_f32_e32 v19, v19, v19
	v_max_f32_e32 v18, v18, v19
	ds_bpermute_b32 v19, v181, v18
	global_store_dwordx4 v[70:71], v[26:29], off
	s_nop 0
	v_cvt_pk_bf16_f32 v20, v22, v23
	s_nop 0
	v_cvt_pk_bf16_f32 v21, v24, v25
	s_nop 0
	v_cvt_pk_bf16_f32 v22, v32, v33
	s_nop 0
	v_cvt_pk_bf16_f32 v23, v30, v31
	global_store_dwordx4 v[70:71], v[20:23], off offset:256
	s_and_saveexec_b64 s[26:27], s[6:7]
	s_cbranch_execz .LBB0_1582
	s_waitcnt lgkmcnt(0)
	v_max_f32_e32 v19, v19, v19
	v_max_f32_e32 v18, v18, v18
	v_lshl_add_u64 v[20:21], v[82:83], 2, s[12:13]
	v_max_f32_e32 v18, v18, v19
	global_atomic_umax v[20:21], v18, off

; __device__ __forceinline__ f32x4 sig4(const f32x4 v) { return (f32x4){sigmoidf_(v[0]), sigmoidf_(v[1]), sigmoidf_(v[2]), sigmoidf_(v[3])}; }
;     __device__ __forceinline__ void operator()(const typename AccT<I8>::type (&acc)[2][2][4][2], const Unit& u, int wr, int wc, int fr, int fq) const {
;         const int row0 = u.pm * BM + wr * 64 + fr, col0 = u.pn * BM + wc * 32 + 4 * fq;
;         f32x4 sv[2][2];
;         if (I8) {
; #pragma unroll
;             for (int bj = 0; bj < 2; ++bj)
; #pragma unroll
;                 for (int n = 0; n < 2; ++n) sv[bj][n] = *(const f32x4*)(swc + col0 + bj * HALF + n * 16);
;         }
;         float rsv[8];
; #pragma unroll
;         for (int s = 0; s < 8; ++s) { const int r = row0 + (s >> 2) * HALF + (s & 3) * 16; float rs = 1.f; if (MODE == 1) rs = __builtin_amdgcn_rsqf(rstd[r] * (1.0f / 4096.0f) + 1e-6f); if (I8) rs *= sxr[r]; rsv[s] = rs; }
;         RowIn cur, nxt;
;         load_row(cur, (size_t)row0 * 4096 + col0);
; #pragma unroll
;         for (int s = 0; s < 8; ++s) { const int ai = s >> 2, m = s & 3; const int r = row0 + ai * HALF + m * 16; const size_t off = (size_t)r * 4096 + col0;
;                 if (s + 1 < 8) load_row(nxt, (size_t)(row0 + ((s + 1) >> 2) * HALF + ((s + 1) & 3) * 16) * 4096 + col0);
;                 const float rs = rsv[s];
;                 float ss = 0.f, mx = 0.f;
; #pragma unroll
;                 for (int bj = 0; bj < 2; ++bj)
; #pragma unroll
;                     for (int n = 0; n < 2; ++n) { const size_t o = off + bj * HALF + n * 16; const f32x4 b = cur.b[bj][n]; f32x4 v;
;                         if constexpr (I8) v = __builtin_convertvector(acc[ai][bj][m][n], f32x4) * rs * sv[bj][n]; else v = acc[ai][bj][m][n];
;                         if (MODE == 1) { const u32x2 pw = cur.pw[bj][n]; const f32x4 pp = (f32x4){bf_lo(pw.x), bf_hi(pw.x), bf_lo(pw.y), bf_hi(pw.y)}; v = sig4(I8 ? v : v * rs) * pp; }
;                         const f32x4 x = b + v; *(f32x4*)(out + o) = x;
.LBB0_1724:
	s_lshl_b32 s98, s6, 4
	s_add_i32 s98, s98, s2
	s_sub_i32 s99, s98, 888
	s_cmp_lt_u32 s98, 888
	s_cselect_b32 s98, s98, s99
	s_mov_b32 s99, 0x4200000
	s_cselect_b32 s99, 0x3f600000, s99
	s_lshl_b32 s98, s98, 18
	s_add_u32 s98, s98, s99
	v_and_b32_e32 v250, 63, v0
	v_lshlrev_b32_e32 v250, 4, v250
	v_lshrrev_b32_e32 v251, 6, v0
	v_lshl_add_u32 v250, v251, 12, v250
	v_add_u32_e32 v250, s98, v250
	v_mov_b32_e32 v251, 0
	v_lshl_add_u64 v[250:251], s[96:97], 0, v[250:251]
	v_mov_b32_e32 v148, v0
	v_cvt_f32_i32_e32 v145, v145
	v_ashrrev_i32_e32 v34, 2, v148
	v_and_b32_e32 v34, 0xffffffc0, v34
	v_lshl_add_u32 v149, s6, 8, v34
	v_lshrrev_b32_e32 v34, 1, v148
	v_and_b32_e32 v34, 0x60, v34
	v_bfe_u32 v187, v148, 4, 2
	v_lshl_or_b32 v34, s2, 8, v34
	v_lshl_or_b32 v190, v187, 2, v34
	v_ashrrev_i32_e32 v191, 31, v190
	v_and_or_b32 v206, v148, 15, v149
	v_lshlrev_b64 v[146:147], 2, v[190:191]
	v_ashrrev_i32_e32 v207, 31, v206
	v_or_b32_e32 v214, 16, v206
	v_or_b32_e32 v210, 32, v206
	v_or_b32_e32 v204, 48, v206
	v_add_u32_e32 v198, 0x90, v206
	v_add_u32_e32 v194, 0xa0, v206
	v_add_u32_e32 v188, 0xb0, v206
	v_lshl_add_u64 v[34:35], s[14:15], 0, v[146:147]
	v_lshl_add_u64 v[148:149], v[206:207], 2, s[16:17]
	v_ashrrev_i32_e32 v215, 31, v214
	v_ashrrev_i32_e32 v211, 31, v210
	v_ashrrev_i32_e32 v205, 31, v204
	v_ashrrev_i32_e32 v199, 31, v198
	v_ashrrev_i32_e32 v195, 31, v194
	v_ashrrev_i32_e32 v189, 31, v188
	global_load_dwordx4 v[62:65], v[34:35], off
	global_load_dwordx4 v[42:45], v[34:35], off offset:64
	global_load_dwordx4 v[38:41], v[34:35], off offset:512
	s_nop 0
	global_load_dwordx4 v[34:37], v[34:35], off offset:576
	v_lshl_add_u64 v[150:151], v[214:215], 2, s[16:17]
	v_lshl_add_u64 v[152:153], v[210:211], 2, s[16:17]
	v_lshl_add_u64 v[154:155], v[204:205], 2, s[16:17]
	v_lshl_add_u64 v[156:157], v[198:199], 2, s[16:17]
	v_lshl_add_u64 v[158:159], v[194:195], 2, s[16:17]
	v_lshl_add_u64 v[160:161], v[188:189], 2, s[16:17]
	global_load_dword v216, v[148:149], off
	global_load_dword v212, v[150:151], off
	global_load_dword v208, v[152:153], off
	global_load_dword v202, v[154:155], off
	global_load_dword v196, v[156:157], off
	global_load_dword v192, v[158:159], off
	global_load_dword v186, v[160:161], off
	global_load_dword v200, v[148:149], off offset:512
	v_lshlrev_b64 v[148:149], 14, v[206:207]
	v_lshl_add_u64 v[148:149], s[64:65], 0, v[148:149]
	v_lshl_add_u64 v[148:149], v[148:149], 0, v[146:147]
	global_load_dwordx4 v[238:241], v[148:149], off
	global_load_dwordx4 v[170:173], v[148:149], off offset:64
	global_load_dwordx4 v[166:169], v[148:149], off offset:512
	global_load_dwordx4 v[162:165], v[148:149], off offset:576
	v_lshlrev_b64 v[148:149], 14, v[214:215]
	v_lshl_add_u64 v[148:149], s[64:65], 0, v[148:149]
	v_lshl_add_u64 v[146:147], v[148:149], 0, v[146:147]
	global_load_dwordx4 v[158:161], v[146:147], off
	global_load_dwordx4 v[154:157], v[146:147], off offset:64
	global_load_dwordx4 v[150:153], v[146:147], off offset:512
	s_nop 0
	global_load_dwordx4 v[146:149], v[146:147], off offset:576
	v_cvt_f32_i32_e32 v144, v144
	v_cvt_f32_i32_e32 v143, v143
	v_cvt_f32_i32_e32 v142, v142
	v_cvt_f32_i32_e32 v229, v139
	v_cvt_f32_i32_e32 v228, v138
	v_cvt_f32_i32_e32 v231, v141
	v_cvt_f32_i32_e32 v230, v140
	v_cvt_f32_i32_e32 v225, v135
	v_cvt_f32_i32_e32 v224, v134
	v_cvt_f32_i32_e32 v227, v137
	v_cvt_f32_i32_e32 v226, v136
	v_cvt_f32_i32_e32 v219, v131
	v_cvt_f32_i32_e32 v218, v130
	v_cvt_f32_i32_e32 v223, v133
	v_cvt_f32_i32_e32 v222, v132
	v_lshlrev_b64 v[130:131], 12, v[206:207]
	v_readlane_b32 s68, v254, 8
	v_cndmask_b32_e64 v193, 0, 1, s[22:23]
	v_lshl_add_u64 v[134:135], v[130:131], 0, v[190:191]
	v_readlane_b32 s74, v254, 14
	v_readlane_b32 s75, v254, 15
	v_cmp_ne_u32_e64 s[8:9], 1, v193
	v_cmp_eq_u32_e64 s[6:7], 0, v187
	s_mov_b64 s[98:99], 0x0
	v_lshl_add_u64 v[220:221], v[250:251], 0, s[98:99]
	s_andn2_b64 vcc, exec, s[22:23]
	v_readlane_b32 s69, v254, 9
	v_readlane_b32 s70, v254, 10
	v_readlane_b32 s71, v254, 11
	v_readlane_b32 s72, v254, 12
	v_readlane_b32 s73, v254, 13
	s_waitcnt vmcnt(0)
	v_mov_b32_e32 v217, v216
	v_pk_mul_f32 v[130:131], v[216:217], v[142:143] op_sel_hi:[0,1]
	v_pk_mul_f32 v[132:133], v[216:217], v[144:145] op_sel_hi:[0,1]
	v_pk_fma_f32 v[132:133], v[64:65], v[132:133], v[240:241]
	v_pk_fma_f32 v[130:131], v[62:63], v[130:131], v[238:239]
	global_store_dwordx4 v[220:221], v[130:133], off
	s_cbranch_vccnz .LBB0_1783
; __device__ __forceinline__ unsigned cvt_pk_bf16(float lo, float hi) { unsigned r; asm volatile("s_nop 0\n\tv_cvt_pk_bf16_f32 %0, %1, %2" : "=v"(r) : "v"(lo), "v"(hi)); return r; }
; __device__ __forceinline__ f32x4 sig4(const f32x4 v) { return (f32x4){sigmoidf_(v[0]), sigmoidf_(v[1]), sigmoidf_(v[2]), sigmoidf_(v[3])}; }
;     __device__ __forceinline__ void operator()(const typename AccT<I8>::type (&acc)[2][2][4][2], const Unit& u, int wr, int wc, int fr, int fq) const {
;     ...
;                     for (int n = 0; n < 2; ++n) { const size_t o = off + bj * HALF + n * 16; const f32x4 b = cur.b[bj][n]; f32x4 v;
;                         if constexpr (I8) v = __builtin_convertvector(acc[ai][bj][m][n], f32x4) * rs * sv[bj][n]; else v = acc[ai][bj][m][n];
;                         if (MODE == 1) { const u32x2 pw = cur.pw[bj][n]; const f32x4 pp = (f32x4){bf_lo(pw.x), bf_hi(pw.x), bf_lo(pw.y), bf_hi(pw.y)}; v = sig4(I8 ? v : v * rs) * pp; }
;                         const f32x4 x = b + v; *(f32x4*)(out + o) = x;
;                         if (MODE == 0 && XB) { u32x2 w; w.x = cvt_pk_bf16(x[0], x[1]); w.y = cvt_pk_bf16(x[2], x[3]); *(u32x2*)(XB + o) = w; ss += (x[0] * x[0] + x[1] * x[1]) + (x[2] * x[2] + x[3] * x[3]);
;                             if (RM) mx = fmaxf(fmaxf(mx, fmaxf(fabsf(x[0]), fabsf(x[1]))), fmaxf(fabsf(x[2]), fabsf(x[3]))); } }
;                 if (MODE == 0 && XB) { ss += __shfl_xor(ss, 16); ss += __shfl_xor(ss, 32); if (fq == 0) unsafeAtomicAdd(SS + r, ss);
;                     if (RM) { mx = fmaxf(mx, __shfl_xor(mx, 16)); mx = fmaxf(mx, __shfl_xor(mx, 32)); if (fq == 0) atomicMax(RM + r, __builtin_bit_cast(unsigned, mx)); } }
	v_readlane_b32 s2, v254, 40
	v_lshlrev_b64 v[238:239], 1, v[134:135]
	v_readlane_b32 s3, v254, 41
	s_nop 0
	v_cvt_pk_bf16_f32 v136, v130, v131
	s_nop 0
	v_cvt_pk_bf16_f32 v137, v132, v133
	v_mov_b32_e32 v142, v216
	v_mov_b32_e32 v143, v216
	v_lshl_add_u64 v[134:135], s[2:3], 0, v[238:239]
	global_store_dwordx2 v[134:135], v[136:137], off
	v_mul_f32_e32 v134, v131, v131
	v_mul_f32_e32 v135, v133, v133
	v_fmac_f32_e32 v134, v130, v130
	v_fmac_f32_e32 v135, v132, v132
	v_add_f32_e32 v144, v134, v135
	v_pk_mul_f32 v[134:135], v[142:143], v[230:231]
	v_pk_mul_f32 v[138:139], v[216:217], v[228:229]
	v_pk_fma_f32 v[136:137], v[44:45], v[134:135], v[172:173]
	v_pk_fma_f32 v[134:135], v[42:43], v[138:139], v[170:171]
	v_or_b32_e32 v140, 32, v238
	v_mov_b32_e32 v141, v239
	global_store_dwordx4 v[220:221], v[134:137], off offset:1024
	s_nop 0
	v_cvt_pk_bf16_f32 v138, v134, v135
	s_nop 0
	v_cvt_pk_bf16_f32 v139, v136, v137
	v_lshl_add_u64 v[140:141], s[2:3], 0, v[140:141]
	global_store_dwordx2 v[140:141], v[138:139], off
	v_mul_f32_e32 v138, v135, v135
	v_mul_f32_e32 v139, v137, v137
	v_fmac_f32_e32 v138, v134, v134
	v_fmac_f32_e32 v139, v136, v136
	v_add_f32_e32 v138, v138, v139
	v_add_f32_e32 v187, v144, v138
	v_pk_mul_f32 v[138:139], v[142:143], v[226:227]
	v_pk_mul_f32 v[144:145], v[216:217], v[224:225]
	v_pk_fma_f32 v[140:141], v[40:41], v[138:139], v[168:169]
	v_pk_fma_f32 v[138:139], v[38:39], v[144:145], v[166:167]
	v_mul_f32_e32 v145, v141, v141
	v_mul_f32_e32 v144, v139, v139
	v_fmac_f32_e32 v144, v138, v138
	v_fmac_f32_e32 v145, v140, v140
	v_add_f32_e32 v144, v144, v145
	v_pk_mul_f32 v[142:143], v[142:143], v[222:223]
	v_pk_mul_f32 v[244:245], v[216:217], v[218:219]
	v_add_f32_e32 v187, v187, v144
	v_pk_fma_f32 v[144:145], v[36:37], v[142:143], v[164:165]
	v_pk_fma_f32 v[142:143], v[34:35], v[244:245], v[162:163]
	v_mul_f32_e32 v197, v145, v145
	v_mul_f32_e32 v193, v143, v143
	v_fmac_f32_e32 v193, v142, v142
	v_fmac_f32_e32 v197, v144, v144
	v_add_f32_e32 v193, v193, v197
	v_and_b32_e32 v197, 64, v236
	v_add_f32_e32 v193, v187, v193
	v_xor_b32_e32 v187, 16, v236
	v_add_u32_e32 v201, 64, v197
	v_cmp_lt_i32_e32 vcc, v187, v201
	v_or_b32_e32 v242, 0x100, v238
	v_mov_b32_e32 v243, v239
	v_cndmask_b32_e32 v187, v236, v187, vcc
	v_lshlrev_b32_e32 v187, 2, v187
	ds_bpermute_b32 v197, v187, v193
	v_or_b32_e32 v238, 0x120, v238
	global_store_dwordx4 v[220:221], v[138:141], off offset:2048
	s_nop 0
	v_cvt_pk_bf16_f32 v240, v138, v139
	s_nop 0
	v_cvt_pk_bf16_f32 v241, v140, v141
	s_waitcnt lgkmcnt(0)
	v_add_f32_e32 v197, v193, v197
	v_xor_b32_e32 v193, 32, v236
	v_cmp_lt_i32_e32 vcc, v193, v201
	v_lshl_add_u64 v[242:243], s[2:3], 0, v[242:243]
	v_lshl_add_u64 v[238:239], s[2:3], 0, v[238:239]
	v_cndmask_b32_e32 v193, v236, v193, vcc
	v_lshlrev_b32_e32 v193, 2, v193
	ds_bpermute_b32 v201, v193, v197
	global_store_dwordx2 v[242:243], v[240:241], off
	global_store_dwordx4 v[220:221], v[142:145], off offset:3072
	s_nop 0
	v_cvt_pk_bf16_f32 v240, v142, v143
	s_nop 0
	v_cvt_pk_bf16_f32 v241, v144, v145
	global_store_dwordx2 v[238:239], v[240:241], off
	s_and_saveexec_b64 s[2:3], s[6:7]
	s_cbranch_execz .LBB0_1727
	v_lshl_add_u64 v[238:239], v[206:207], 2, s[10:11]
	s_waitcnt lgkmcnt(0)
	v_add_f32_e32 v197, v197, v201
	global_atomic_add_f32 v[238:239], v197, off

; __device__ __forceinline__ unsigned cvt_pk_bf16(float lo, float hi) { unsigned r; asm volatile("s_nop 0\n\tv_cvt_pk_bf16_f32 %0, %1, %2" : "=v"(r) : "v"(lo), "v"(hi)); return r; }
; __device__ __forceinline__ f32x4 sig4(const f32x4 v) { return (f32x4){sigmoidf_(v[0]), sigmoidf_(v[1]), sigmoidf_(v[2]), sigmoidf_(v[3])}; }
;     __device__ __forceinline__ void operator()(const typename AccT<I8>::type (&acc)[2][2][4][2], const Unit& u, int wr, int wc, int fr, int fq) const {
;     ...
;         for (int s = 0; s < 8; ++s) { const int ai = s >> 2, m = s & 3; const int r = row0 + ai * HALF + m * 16; const size_t off = (size_t)r * 4096 + col0;
;                 if (s + 1 < 8) load_row(nxt, (size_t)(row0 + ((s + 1) >> 2) * HALF + ((s + 1) & 3) * 16) * 4096 + col0);
;                 const float rs = rsv[s];
;                 float ss = 0.f, mx = 0.f;
; #pragma unroll
;                 for (int bj = 0; bj < 2; ++bj)
; #pragma unroll
;                     for (int n = 0; n < 2; ++n) { const size_t o = off + bj * HALF + n * 16; const f32x4 b = cur.b[bj][n]; f32x4 v;
;                         if constexpr (I8) v = __builtin_convertvector(acc[ai][bj][m][n], f32x4) * rs * sv[bj][n]; else v = acc[ai][bj][m][n];
;                         if (MODE == 1) { const u32x2 pw = cur.pw[bj][n]; const f32x4 pp = (f32x4){bf_lo(pw.x), bf_hi(pw.x), bf_lo(pw.y), bf_hi(pw.y)}; v = sig4(I8 ? v : v * rs) * pp; }
;                         const f32x4 x = b + v; *(f32x4*)(out + o) = x;
;                         if (MODE == 0 && XB) { u32x2 w; w.x = cvt_pk_bf16(x[0], x[1]); w.y = cvt_pk_bf16(x[2], x[3]); *(u32x2*)(XB + o) = w; ss += (x[0] * x[0] + x[1] * x[1]) + (x[2] * x[2] + x[3] * x[3]);
;                             if (RM) mx = fmaxf(fmaxf(mx, fmaxf(fabsf(x[0]), fabsf(x[1]))), fmaxf(fabsf(x[2]), fabsf(x[3]))); } }
;                 if (MODE == 0 && XB) { ss += __shfl_xor(ss, 16); ss += __shfl_xor(ss, 32); if (fq == 0) unsafeAtomicAdd(SS + r, ss);
;                     if (RM) { mx = fmaxf(mx, __shfl_xor(mx, 16)); mx = fmaxf(mx, __shfl_xor(mx, 32)); if (fq == 0) atomicMax(RM + r, __builtin_bit_cast(unsigned, mx)); } }
.LBB0_1731:
	s_waitcnt lgkmcnt(0)
	s_nop 0
	v_lshlrev_b64 v[130:131], 14, v[210:211]
	v_lshl_add_u64 v[130:131], s[64:65], 0, v[130:131]
	v_lshl_add_u64 v[130:131], v[190:191], 2, v[130:131]
	global_load_dwordx4 v[142:145], v[130:131], off
	global_load_dwordx4 v[138:141], v[130:131], off offset:64
	global_load_dwordx4 v[134:137], v[130:131], off offset:512
	s_nop 0
	global_load_dwordx4 v[130:133], v[130:131], off offset:576
	v_cvt_f32_i32_e32 v127, v127
	v_cvt_f32_i32_e32 v126, v126
	v_cvt_f32_i32_e32 v129, v129
	v_cvt_f32_i32_e32 v128, v128
	v_mov_b32_e32 v213, v212
	v_lshlrev_b64 v[162:163], 12, v[214:215]
	v_pk_mul_f32 v[126:127], v[212:213], v[126:127] op_sel_hi:[0,1]
	v_lshl_add_u64 v[172:173], v[162:163], 0, v[190:191]
	v_pk_fma_f32 v[126:127], v[62:63], v[126:127], v[158:159]
	v_cvt_f32_i32_e32 v169, v123
	v_cvt_f32_i32_e32 v168, v122
	v_cvt_f32_i32_e32 v171, v125
	v_cvt_f32_i32_e32 v170, v124
	v_cvt_f32_i32_e32 v165, v119
	v_cvt_f32_i32_e32 v164, v118
	v_cvt_f32_i32_e32 v167, v121
	v_cvt_f32_i32_e32 v166, v120
	v_cvt_f32_i32_e32 v159, v115
	v_cvt_f32_i32_e32 v158, v114
	v_cvt_f32_i32_e32 v163, v117
	v_cvt_f32_i32_e32 v162, v116
	v_readlane_b32 s68, v254, 8
	v_pk_mul_f32 v[128:129], v[212:213], v[128:129] op_sel_hi:[0,1]
	v_readlane_b32 s74, v254, 14
	v_readlane_b32 s75, v254, 15
	v_pk_fma_f32 v[128:129], v[64:65], v[128:129], v[160:161]
	s_and_b64 vcc, exec, s[8:9]
	s_mov_b64 s[98:99], 0x8000
	v_lshl_add_u64 v[160:161], v[250:251], 0, s[98:99]
	v_readlane_b32 s69, v254, 9
	v_readlane_b32 s70, v254, 10
	v_readlane_b32 s71, v254, 11
	v_readlane_b32 s72, v254, 12
	v_readlane_b32 s73, v254, 13
	global_store_dwordx4 v[160:161], v[126:129], off
	s_cbranch_vccnz .LBB0_1784
	v_readlane_b32 s2, v254, 40
	v_lshlrev_b64 v[216:217], 1, v[172:173]
	v_readlane_b32 s3, v254, 41
	s_nop 0
	v_cvt_pk_bf16_f32 v114, v126, v127
	s_nop 0
	v_cvt_pk_bf16_f32 v115, v128, v129
	v_mov_b32_e32 v122, v212
	v_mov_b32_e32 v123, v212
	v_lshl_add_u64 v[116:117], s[2:3], 0, v[216:217]
	global_store_dwordx2 v[116:117], v[114:115], off
	v_mul_f32_e32 v114, v127, v127
	v_mul_f32_e32 v115, v129, v129
	v_fmac_f32_e32 v114, v126, v126
	v_fmac_f32_e32 v115, v128, v128
	v_add_f32_e32 v124, v114, v115
	v_pk_mul_f32 v[114:115], v[122:123], v[170:171]
	v_pk_mul_f32 v[118:119], v[212:213], v[168:169]
	v_pk_fma_f32 v[116:117], v[44:45], v[114:115], v[156:157]
	v_pk_fma_f32 v[114:115], v[42:43], v[118:119], v[154:155]
	v_or_b32_e32 v120, 32, v216
	v_mov_b32_e32 v121, v217
	global_store_dwordx4 v[160:161], v[114:117], off offset:1024
	s_nop 0
	v_cvt_pk_bf16_f32 v118, v114, v115
	s_nop 0
	v_cvt_pk_bf16_f32 v119, v116, v117
	v_lshl_add_u64 v[120:121], s[2:3], 0, v[120:121]
	global_store_dwordx2 v[120:121], v[118:119], off
	v_mul_f32_e32 v118, v115, v115
	v_mul_f32_e32 v119, v117, v117
	v_fmac_f32_e32 v118, v114, v114
	v_fmac_f32_e32 v119, v116, v116
	v_add_f32_e32 v118, v118, v119
	v_add_f32_e32 v172, v124, v118
	v_pk_mul_f32 v[118:119], v[122:123], v[166:167]
	v_pk_mul_f32 v[124:125], v[212:213], v[164:165]
	v_pk_fma_f32 v[120:121], v[40:41], v[118:119], v[152:153]
	v_pk_fma_f32 v[118:119], v[38:39], v[124:125], v[150:151]
	v_mul_f32_e32 v125, v121, v121
	v_mul_f32_e32 v124, v119, v119
	v_fmac_f32_e32 v124, v118, v118
	v_fmac_f32_e32 v125, v120, v120
	v_add_f32_e32 v124, v124, v125
	v_add_f32_e32 v187, v172, v124
	v_pk_mul_f32 v[122:123], v[122:123], v[162:163]
	v_pk_mul_f32 v[172:173], v[212:213], v[158:159]
	v_pk_fma_f32 v[124:125], v[36:37], v[122:123], v[148:149]
	v_pk_fma_f32 v[122:123], v[34:35], v[172:173], v[146:147]
	v_mul_f32_e32 v173, v125, v125
	v_mul_f32_e32 v172, v123, v123
	v_fmac_f32_e32 v172, v122, v122
	v_fmac_f32_e32 v173, v124, v124
	v_add_f32_e32 v172, v172, v173
	v_add_f32_e32 v173, v187, v172
	v_and_b32_e32 v187, 64, v236
	v_xor_b32_e32 v172, 16, v236
	v_add_u32_e32 v193, 64, v187
	v_cmp_lt_i32_e32 vcc, v172, v193
	v_or_b32_e32 v220, 0x100, v216
	v_mov_b32_e32 v221, v217
	v_cndmask_b32_e32 v172, v236, v172, vcc
	v_lshlrev_b32_e32 v172, 2, v172
	ds_bpermute_b32 v187, v172, v173
	v_or_b32_e32 v216, 0x120, v216
	global_store_dwordx4 v[160:161], v[118:121], off offset:2048
	s_nop 0
	v_cvt_pk_bf16_f32 v218, v118, v119
	s_nop 0
	v_cvt_pk_bf16_f32 v219, v120, v121
	s_waitcnt lgkmcnt(0)
	v_add_f32_e32 v187, v173, v187
	v_xor_b32_e32 v173, 32, v236
	v_cmp_lt_i32_e32 vcc, v173, v193
	v_lshl_add_u64 v[220:221], s[2:3], 0, v[220:221]
	v_lshl_add_u64 v[216:217], s[2:3], 0, v[216:217]
	v_cndmask_b32_e32 v173, v236, v173, vcc
	v_lshlrev_b32_e32 v173, 2, v173
	ds_bpermute_b32 v193, v173, v187
	global_store_dwordx2 v[220:221], v[218:219], off
	global_store_dwordx4 v[160:161], v[122:125], off offset:3072
	s_nop 0
	v_cvt_pk_bf16_f32 v218, v122, v123
	s_nop 0
	v_cvt_pk_bf16_f32 v219, v124, v125
	global_store_dwordx2 v[216:217], v[218:219], off
	s_and_saveexec_b64 s[2:3], s[6:7]
	s_cbranch_execz .LBB0_1734
	v_lshl_add_u64 v[216:217], v[214:215], 2, s[10:11]
	s_waitcnt lgkmcnt(0)
	v_add_f32_e32 v187, v187, v193
	global_atomic_add_f32 v[216:217], v187, off

; __device__ __forceinline__ unsigned cvt_pk_bf16(float lo, float hi) { unsigned r; asm volatile("s_nop 0\n\tv_cvt_pk_bf16_f32 %0, %1, %2" : "=v"(r) : "v"(lo), "v"(hi)); return r; }
; __device__ __forceinline__ f32x4 sig4(const f32x4 v) { return (f32x4){sigmoidf_(v[0]), sigmoidf_(v[1]), sigmoidf_(v[2]), sigmoidf_(v[3])}; }
;     __device__ __forceinline__ void operator()(const typename AccT<I8>::type (&acc)[2][2][4][2], const Unit& u, int wr, int wc, int fr, int fq) const {
;     ...
;         for (int s = 0; s < 8; ++s) { const int ai = s >> 2, m = s & 3; const int r = row0 + ai * HALF + m * 16; const size_t off = (size_t)r * 4096 + col0;
;                 if (s + 1 < 8) load_row(nxt, (size_t)(row0 + ((s + 1) >> 2) * HALF + ((s + 1) & 3) * 16) * 4096 + col0);
;                 const float rs = rsv[s];
;                 float ss = 0.f, mx = 0.f;
; #pragma unroll
;                 for (int bj = 0; bj < 2; ++bj)
; #pragma unroll
;                     for (int n = 0; n < 2; ++n) { const size_t o = off + bj * HALF + n * 16; const f32x4 b = cur.b[bj][n]; f32x4 v;
;                         if constexpr (I8) v = __builtin_convertvector(acc[ai][bj][m][n], f32x4) * rs * sv[bj][n]; else v = acc[ai][bj][m][n];
;                         if (MODE == 1) { const u32x2 pw = cur.pw[bj][n]; const f32x4 pp = (f32x4){bf_lo(pw.x), bf_hi(pw.x), bf_lo(pw.y), bf_hi(pw.y)}; v = sig4(I8 ? v : v * rs) * pp; }
;                         const f32x4 x = b + v; *(f32x4*)(out + o) = x;
;                         if (MODE == 0 && XB) { u32x2 w; w.x = cvt_pk_bf16(x[0], x[1]); w.y = cvt_pk_bf16(x[2], x[3]); *(u32x2*)(XB + o) = w; ss += (x[0] * x[0] + x[1] * x[1]) + (x[2] * x[2] + x[3] * x[3]);
;                             if (RM) mx = fmaxf(fmaxf(mx, fmaxf(fabsf(x[0]), fabsf(x[1]))), fmaxf(fabsf(x[2]), fabsf(x[3]))); } }
;                 if (MODE == 0 && XB) { ss += __shfl_xor(ss, 16); ss += __shfl_xor(ss, 32); if (fq == 0) unsafeAtomicAdd(SS + r, ss);
;                     if (RM) { mx = fmaxf(mx, __shfl_xor(mx, 16)); mx = fmaxf(mx, __shfl_xor(mx, 32)); if (fq == 0) atomicMax(RM + r, __builtin_bit_cast(unsigned, mx)); } }
.LBB0_1738:
	s_waitcnt lgkmcnt(0)
	s_nop 0
	v_lshlrev_b64 v[114:115], 14, v[204:205]
	v_lshl_add_u64 v[114:115], s[64:65], 0, v[114:115]
	v_lshl_add_u64 v[114:115], v[190:191], 2, v[114:115]
	global_load_dwordx4 v[126:129], v[114:115], off
	global_load_dwordx4 v[122:125], v[114:115], off offset:64
	global_load_dwordx4 v[118:121], v[114:115], off offset:512
	s_nop 0
	global_load_dwordx4 v[114:117], v[114:115], off offset:576
	v_cvt_f32_i32_e32 v111, v111
	v_cvt_f32_i32_e32 v110, v110
	v_cvt_f32_i32_e32 v113, v113
	v_cvt_f32_i32_e32 v112, v112
	v_mov_b32_e32 v209, v208
	v_lshlrev_b64 v[146:147], 12, v[210:211]
	v_pk_mul_f32 v[110:111], v[208:209], v[110:111] op_sel_hi:[0,1]
	v_lshl_add_u64 v[156:157], v[146:147], 0, v[190:191]
	s_waitcnt vmcnt(8)
	v_pk_fma_f32 v[110:111], v[62:63], v[110:111], v[142:143]
	v_cvt_f32_i32_e32 v153, v107
	v_cvt_f32_i32_e32 v152, v106
	v_cvt_f32_i32_e32 v155, v109
	v_cvt_f32_i32_e32 v154, v108
	v_cvt_f32_i32_e32 v149, v103
	v_cvt_f32_i32_e32 v148, v102
	v_cvt_f32_i32_e32 v151, v105
	v_cvt_f32_i32_e32 v150, v104
	v_cvt_f32_i32_e32 v143, v99
	v_cvt_f32_i32_e32 v142, v98
	v_cvt_f32_i32_e32 v147, v101
	v_cvt_f32_i32_e32 v146, v100
	v_readlane_b32 s68, v254, 8
	v_pk_mul_f32 v[112:113], v[208:209], v[112:113] op_sel_hi:[0,1]
	v_readlane_b32 s74, v254, 14
	v_readlane_b32 s75, v254, 15
	v_pk_fma_f32 v[112:113], v[64:65], v[112:113], v[144:145]
	s_and_b64 vcc, exec, s[8:9]
	s_mov_b64 s[98:99], 0x10000
	v_lshl_add_u64 v[144:145], v[250:251], 0, s[98:99]
	v_readlane_b32 s69, v254, 9
	v_readlane_b32 s70, v254, 10
	v_readlane_b32 s71, v254, 11
	v_readlane_b32 s72, v254, 12
	v_readlane_b32 s73, v254, 13
	global_store_dwordx4 v[144:145], v[110:113], off
	s_cbranch_vccnz .LBB0_1785
	v_readlane_b32 s2, v254, 40
	v_lshlrev_b64 v[160:161], 1, v[156:157]
	v_readlane_b32 s3, v254, 41
	s_nop 0
	v_cvt_pk_bf16_f32 v98, v110, v111
	s_nop 0
	v_cvt_pk_bf16_f32 v99, v112, v113
	v_mov_b32_e32 v106, v208
	v_mov_b32_e32 v107, v208
	v_lshl_add_u64 v[100:101], s[2:3], 0, v[160:161]
	global_store_dwordx2 v[100:101], v[98:99], off
	v_mul_f32_e32 v98, v111, v111
	v_mul_f32_e32 v99, v113, v113
	v_fmac_f32_e32 v98, v110, v110
	v_fmac_f32_e32 v99, v112, v112
	v_add_f32_e32 v108, v98, v99
	v_pk_mul_f32 v[98:99], v[106:107], v[154:155]
	v_pk_mul_f32 v[102:103], v[208:209], v[152:153]
	s_waitcnt vmcnt(9)
	v_pk_fma_f32 v[100:101], v[44:45], v[98:99], v[140:141]
	v_pk_fma_f32 v[98:99], v[42:43], v[102:103], v[138:139]
	v_or_b32_e32 v104, 32, v160
	v_mov_b32_e32 v105, v161
	global_store_dwordx4 v[144:145], v[98:101], off offset:1024
	s_nop 0
	v_cvt_pk_bf16_f32 v102, v98, v99
	s_nop 0
	v_cvt_pk_bf16_f32 v103, v100, v101
	v_lshl_add_u64 v[104:105], s[2:3], 0, v[104:105]
	global_store_dwordx2 v[104:105], v[102:103], off
	v_mul_f32_e32 v102, v99, v99
	v_mul_f32_e32 v103, v101, v101
	v_fmac_f32_e32 v102, v98, v98
	v_fmac_f32_e32 v103, v100, v100
	v_add_f32_e32 v102, v102, v103
	v_add_f32_e32 v156, v108, v102
	v_pk_mul_f32 v[102:103], v[106:107], v[150:151]
	v_pk_mul_f32 v[108:109], v[208:209], v[148:149]
	s_waitcnt vmcnt(10)
	v_pk_fma_f32 v[104:105], v[40:41], v[102:103], v[136:137]
	v_pk_fma_f32 v[102:103], v[38:39], v[108:109], v[134:135]
	v_mul_f32_e32 v109, v105, v105
	v_mul_f32_e32 v108, v103, v103
	v_fmac_f32_e32 v108, v102, v102
	v_fmac_f32_e32 v109, v104, v104
	v_add_f32_e32 v108, v108, v109
	v_add_f32_e32 v164, v156, v108
	v_pk_mul_f32 v[106:107], v[106:107], v[146:147]
	v_pk_mul_f32 v[156:157], v[208:209], v[142:143]
	s_waitcnt vmcnt(9)
	v_pk_fma_f32 v[108:109], v[36:37], v[106:107], v[132:133]
	v_pk_fma_f32 v[106:107], v[34:35], v[156:157], v[130:131]
	v_mul_f32_e32 v157, v109, v109
	v_mul_f32_e32 v156, v107, v107
	v_fmac_f32_e32 v156, v106, v106
	v_fmac_f32_e32 v157, v108, v108
	v_add_f32_e32 v156, v156, v157
	v_add_f32_e32 v157, v164, v156
	v_and_b32_e32 v164, 64, v236
	v_xor_b32_e32 v156, 16, v236
	v_add_u32_e32 v164, 64, v164
	v_cmp_lt_i32_e32 vcc, v156, v164
	v_or_b32_e32 v162, 0x100, v160
	v_mov_b32_e32 v163, v161
	v_cndmask_b32_e32 v156, v236, v156, vcc
	v_lshlrev_b32_e32 v156, 2, v156
	ds_bpermute_b32 v165, v156, v157
	global_store_dwordx4 v[144:145], v[102:105], off offset:2048
	s_nop 0
	v_cvt_pk_bf16_f32 v158, v102, v103
	s_nop 0
	v_cvt_pk_bf16_f32 v159, v104, v105
	v_lshl_add_u64 v[162:163], s[2:3], 0, v[162:163]
	global_store_dwordx2 v[162:163], v[158:159], off
	global_store_dwordx4 v[144:145], v[106:109], off offset:3072
	s_waitcnt lgkmcnt(0)
	v_add_f32_e32 v158, v157, v165
	v_xor_b32_e32 v157, 32, v236
	v_cmp_lt_i32_e32 vcc, v157, v164
	v_or_b32_e32 v160, 0x120, v160
	v_lshl_add_u64 v[160:161], s[2:3], 0, v[160:161]
	v_cndmask_b32_e32 v157, v236, v157, vcc
	v_lshlrev_b32_e32 v157, 2, v157
	ds_bpermute_b32 v159, v157, v158
	s_nop 0
	v_cvt_pk_bf16_f32 v162, v106, v107
	s_nop 0
	v_cvt_pk_bf16_f32 v163, v108, v109
	global_store_dwordx2 v[160:161], v[162:163], off
	s_and_saveexec_b64 s[2:3], s[6:7]
	s_cbranch_execz .LBB0_1741
	v_lshl_add_u64 v[160:161], v[210:211], 2, s[10:11]
	s_waitcnt lgkmcnt(0)
	v_add_f32_e32 v158, v158, v159
	global_atomic_add_f32 v[160:161], v158, off

; __device__ __forceinline__ unsigned cvt_pk_bf16(float lo, float hi) { unsigned r; asm volatile("s_nop 0\n\tv_cvt_pk_bf16_f32 %0, %1, %2" : "=v"(r) : "v"(lo), "v"(hi)); return r; }
; __device__ __forceinline__ f32x4 sig4(const f32x4 v) { return (f32x4){sigmoidf_(v[0]), sigmoidf_(v[1]), sigmoidf_(v[2]), sigmoidf_(v[3])}; }
;     __device__ __forceinline__ void operator()(const typename AccT<I8>::type (&acc)[2][2][4][2], const Unit& u, int wr, int wc, int fr, int fq) const {
;     ...
;         for (int s = 0; s < 8; ++s) { const int ai = s >> 2, m = s & 3; const int r = row0 + ai * HALF + m * 16; const size_t off = (size_t)r * 4096 + col0;
;                 if (s + 1 < 8) load_row(nxt, (size_t)(row0 + ((s + 1) >> 2) * HALF + ((s + 1) & 3) * 16) * 4096 + col0);
;                 const float rs = rsv[s];
;                 float ss = 0.f, mx = 0.f;
; #pragma unroll
;                 for (int bj = 0; bj < 2; ++bj)
; #pragma unroll
;                     for (int n = 0; n < 2; ++n) { const size_t o = off + bj * HALF + n * 16; const f32x4 b = cur.b[bj][n]; f32x4 v;
;                         if constexpr (I8) v = __builtin_convertvector(acc[ai][bj][m][n], f32x4) * rs * sv[bj][n]; else v = acc[ai][bj][m][n];
;                         if (MODE == 1) { const u32x2 pw = cur.pw[bj][n]; const f32x4 pp = (f32x4){bf_lo(pw.x), bf_hi(pw.x), bf_lo(pw.y), bf_hi(pw.y)}; v = sig4(I8 ? v : v * rs) * pp; }
;                         const f32x4 x = b + v; *(f32x4*)(out + o) = x;
;                         if (MODE == 0 && XB) { u32x2 w; w.x = cvt_pk_bf16(x[0], x[1]); w.y = cvt_pk_bf16(x[2], x[3]); *(u32x2*)(XB + o) = w; ss += (x[0] * x[0] + x[1] * x[1]) + (x[2] * x[2] + x[3] * x[3]);
;                             if (RM) mx = fmaxf(fmaxf(mx, fmaxf(fabsf(x[0]), fabsf(x[1]))), fmaxf(fabsf(x[2]), fabsf(x[3]))); } }
;                 if (MODE == 0 && XB) { ss += __shfl_xor(ss, 16); ss += __shfl_xor(ss, 32); if (fq == 0) unsafeAtomicAdd(SS + r, ss);
;                     if (RM) { mx = fmaxf(mx, __shfl_xor(mx, 16)); mx = fmaxf(mx, __shfl_xor(mx, 32)); if (fq == 0) atomicMax(RM + r, __builtin_bit_cast(unsigned, mx)); } }
.LBB0_1745:
	s_waitcnt vmcnt(6)
	v_add_u32_e32 v130, 0x80, v206
	v_ashrrev_i32_e32 v131, 31, v130
	s_waitcnt lgkmcnt(0)
	v_lshlrev_b64 v[98:99], 14, v[130:131]
	v_lshl_add_u64 v[98:99], s[64:65], 0, v[98:99]
	v_lshl_add_u64 v[98:99], v[190:191], 2, v[98:99]
	global_load_dwordx4 v[110:113], v[98:99], off
	global_load_dwordx4 v[106:109], v[98:99], off offset:64
	global_load_dwordx4 v[102:105], v[98:99], off offset:512
	s_nop 0
	global_load_dwordx4 v[98:101], v[98:99], off offset:576
	v_cvt_f32_i32_e32 v95, v95
	v_cvt_f32_i32_e32 v94, v94
	v_cvt_f32_i32_e32 v97, v97
	v_cvt_f32_i32_e32 v96, v96
	v_mov_b32_e32 v203, v202
	v_lshlrev_b64 v[132:133], 12, v[204:205]
	v_pk_mul_f32 v[94:95], v[202:203], v[94:95] op_sel_hi:[0,1]
	v_lshl_add_u64 v[142:143], v[132:133], 0, v[190:191]
	s_waitcnt vmcnt(8)
	v_pk_fma_f32 v[94:95], v[62:63], v[94:95], v[126:127]
	v_cvt_f32_i32_e32 v139, v91
	v_cvt_f32_i32_e32 v138, v90
	v_cvt_f32_i32_e32 v141, v93
	v_cvt_f32_i32_e32 v140, v92
	v_cvt_f32_i32_e32 v135, v87
	v_cvt_f32_i32_e32 v134, v86
	v_cvt_f32_i32_e32 v137, v89
	v_cvt_f32_i32_e32 v136, v88
	v_cvt_f32_i32_e32 v127, v83
	v_cvt_f32_i32_e32 v126, v82
	v_cvt_f32_i32_e32 v133, v85
	v_cvt_f32_i32_e32 v132, v84
	v_readlane_b32 s68, v254, 8
	v_pk_mul_f32 v[96:97], v[202:203], v[96:97] op_sel_hi:[0,1]
	v_readlane_b32 s74, v254, 14
	v_readlane_b32 s75, v254, 15
	v_pk_fma_f32 v[96:97], v[64:65], v[96:97], v[128:129]
	s_and_b64 vcc, exec, s[8:9]
	s_mov_b64 s[98:99], 0x18000
	v_lshl_add_u64 v[128:129], v[250:251], 0, s[98:99]
	v_readlane_b32 s69, v254, 9
	v_readlane_b32 s70, v254, 10
	v_readlane_b32 s71, v254, 11
	v_readlane_b32 s72, v254, 12
	v_readlane_b32 s73, v254, 13
	global_store_dwordx4 v[128:129], v[94:97], off
	s_cbranch_vccnz .LBB0_1786
	v_readlane_b32 s2, v254, 40
	v_lshlrev_b64 v[146:147], 1, v[142:143]
	v_readlane_b32 s3, v254, 41
	s_nop 0
	v_cvt_pk_bf16_f32 v82, v94, v95
	s_nop 0
	v_cvt_pk_bf16_f32 v83, v96, v97
	v_mov_b32_e32 v90, v202
	v_mov_b32_e32 v91, v202
	v_lshl_add_u64 v[84:85], s[2:3], 0, v[146:147]
	global_store_dwordx2 v[84:85], v[82:83], off
	v_mul_f32_e32 v82, v95, v95
	v_mul_f32_e32 v83, v97, v97
	v_fmac_f32_e32 v82, v94, v94
	v_fmac_f32_e32 v83, v96, v96
	v_add_f32_e32 v92, v82, v83
	v_pk_mul_f32 v[82:83], v[90:91], v[140:141]
	v_pk_mul_f32 v[86:87], v[202:203], v[138:139]
	s_waitcnt vmcnt(9)
	v_pk_fma_f32 v[84:85], v[44:45], v[82:83], v[124:125]
	v_pk_fma_f32 v[82:83], v[42:43], v[86:87], v[122:123]
	v_or_b32_e32 v88, 32, v146
	v_mov_b32_e32 v89, v147
	global_store_dwordx4 v[128:129], v[82:85], off offset:1024
	s_nop 0
	v_cvt_pk_bf16_f32 v86, v82, v83
	s_nop 0
	v_cvt_pk_bf16_f32 v87, v84, v85
	v_lshl_add_u64 v[88:89], s[2:3], 0, v[88:89]
	global_store_dwordx2 v[88:89], v[86:87], off
	v_mul_f32_e32 v86, v83, v83
	v_mul_f32_e32 v87, v85, v85
	v_fmac_f32_e32 v86, v82, v82
	v_fmac_f32_e32 v87, v84, v84
	v_add_f32_e32 v86, v86, v87
	v_add_f32_e32 v142, v92, v86
	v_pk_mul_f32 v[86:87], v[90:91], v[136:137]
	v_pk_mul_f32 v[92:93], v[202:203], v[134:135]
	s_waitcnt vmcnt(10)
	v_pk_fma_f32 v[88:89], v[40:41], v[86:87], v[120:121]
	v_pk_fma_f32 v[86:87], v[38:39], v[92:93], v[118:119]
	v_mul_f32_e32 v93, v89, v89
	v_mul_f32_e32 v92, v87, v87
	v_fmac_f32_e32 v92, v86, v86
	v_fmac_f32_e32 v93, v88, v88
	v_add_f32_e32 v92, v92, v93
	v_add_f32_e32 v150, v142, v92
	v_pk_mul_f32 v[90:91], v[90:91], v[132:133]
	v_pk_mul_f32 v[142:143], v[202:203], v[126:127]
	s_waitcnt vmcnt(9)
	v_pk_fma_f32 v[92:93], v[36:37], v[90:91], v[116:117]
	v_pk_fma_f32 v[90:91], v[34:35], v[142:143], v[114:115]
	v_mul_f32_e32 v143, v93, v93
	v_mul_f32_e32 v142, v91, v91
	v_fmac_f32_e32 v142, v90, v90
	v_fmac_f32_e32 v143, v92, v92
	v_add_f32_e32 v142, v142, v143
	v_add_f32_e32 v143, v150, v142
	v_and_b32_e32 v150, 64, v236
	v_xor_b32_e32 v142, 16, v236
	v_add_u32_e32 v150, 64, v150
	v_cmp_lt_i32_e32 vcc, v142, v150
	v_or_b32_e32 v148, 0x100, v146
	v_mov_b32_e32 v149, v147
	v_cndmask_b32_e32 v142, v236, v142, vcc
	v_lshlrev_b32_e32 v142, 2, v142
	ds_bpermute_b32 v151, v142, v143
	global_store_dwordx4 v[128:129], v[86:89], off offset:2048
	s_nop 0
	v_cvt_pk_bf16_f32 v144, v86, v87
	s_nop 0
	v_cvt_pk_bf16_f32 v145, v88, v89
	v_lshl_add_u64 v[148:149], s[2:3], 0, v[148:149]
	global_store_dwordx2 v[148:149], v[144:145], off
	global_store_dwordx4 v[128:129], v[90:93], off offset:3072
	s_waitcnt lgkmcnt(0)
	v_add_f32_e32 v144, v143, v151
	v_xor_b32_e32 v143, 32, v236
	v_cmp_lt_i32_e32 vcc, v143, v150
	v_or_b32_e32 v146, 0x120, v146
	v_lshl_add_u64 v[146:147], s[2:3], 0, v[146:147]
	v_cndmask_b32_e32 v143, v236, v143, vcc
	v_lshlrev_b32_e32 v143, 2, v143
	ds_bpermute_b32 v145, v143, v144
	s_nop 0
	v_cvt_pk_bf16_f32 v148, v90, v91
	s_nop 0
	v_cvt_pk_bf16_f32 v149, v92, v93
	global_store_dwordx2 v[146:147], v[148:149], off
	s_and_saveexec_b64 s[2:3], s[6:7]
	s_cbranch_execz .LBB0_1748
	v_lshl_add_u64 v[146:147], v[204:205], 2, s[10:11]
	s_waitcnt lgkmcnt(0)
	v_add_f32_e32 v144, v144, v145
	global_atomic_add_f32 v[146:147], v144, off

; __device__ __forceinline__ unsigned cvt_pk_bf16(float lo, float hi) { unsigned r; asm volatile("s_nop 0\n\tv_cvt_pk_bf16_f32 %0, %1, %2" : "=v"(r) : "v"(lo), "v"(hi)); return r; }
; __device__ __forceinline__ f32x4 sig4(const f32x4 v) { return (f32x4){sigmoidf_(v[0]), sigmoidf_(v[1]), sigmoidf_(v[2]), sigmoidf_(v[3])}; }
;     __device__ __forceinline__ void operator()(const typename AccT<I8>::type (&acc)[2][2][4][2], const Unit& u, int wr, int wc, int fr, int fq) const {
;     ...
;         for (int s = 0; s < 8; ++s) { const int ai = s >> 2, m = s & 3; const int r = row0 + ai * HALF + m * 16; const size_t off = (size_t)r * 4096 + col0;
;                 if (s + 1 < 8) load_row(nxt, (size_t)(row0 + ((s + 1) >> 2) * HALF + ((s + 1) & 3) * 16) * 4096 + col0);
;                 const float rs = rsv[s];
;                 float ss = 0.f, mx = 0.f;
; #pragma unroll
;                 for (int bj = 0; bj < 2; ++bj)
; #pragma unroll
;                     for (int n = 0; n < 2; ++n) { const size_t o = off + bj * HALF + n * 16; const f32x4 b = cur.b[bj][n]; f32x4 v;
;                         if constexpr (I8) v = __builtin_convertvector(acc[ai][bj][m][n], f32x4) * rs * sv[bj][n]; else v = acc[ai][bj][m][n];
;                         if (MODE == 1) { const u32x2 pw = cur.pw[bj][n]; const f32x4 pp = (f32x4){bf_lo(pw.x), bf_hi(pw.x), bf_lo(pw.y), bf_hi(pw.y)}; v = sig4(I8 ? v : v * rs) * pp; }
;                         const f32x4 x = b + v; *(f32x4*)(out + o) = x;
;                         if (MODE == 0 && XB) { u32x2 w; w.x = cvt_pk_bf16(x[0], x[1]); w.y = cvt_pk_bf16(x[2], x[3]); *(u32x2*)(XB + o) = w; ss += (x[0] * x[0] + x[1] * x[1]) + (x[2] * x[2] + x[3] * x[3]);
;                             if (RM) mx = fmaxf(fmaxf(mx, fmaxf(fabsf(x[0]), fabsf(x[1]))), fmaxf(fabsf(x[2]), fabsf(x[3]))); } }
;                 if (MODE == 0 && XB) { ss += __shfl_xor(ss, 16); ss += __shfl_xor(ss, 32); if (fq == 0) unsafeAtomicAdd(SS + r, ss);
;                     if (RM) { mx = fmaxf(mx, __shfl_xor(mx, 16)); mx = fmaxf(mx, __shfl_xor(mx, 32)); if (fq == 0) atomicMax(RM + r, __builtin_bit_cast(unsigned, mx)); } }
.LBB0_1752:
	s_waitcnt lgkmcnt(0)
	s_nop 0
	v_lshlrev_b64 v[82:83], 14, v[198:199]
	v_lshl_add_u64 v[82:83], s[64:65], 0, v[82:83]
	v_lshl_add_u64 v[82:83], v[190:191], 2, v[82:83]
	global_load_dwordx4 v[94:97], v[82:83], off
	global_load_dwordx4 v[90:93], v[82:83], off offset:64
	global_load_dwordx4 v[86:89], v[82:83], off offset:512
	s_nop 0
	global_load_dwordx4 v[82:85], v[82:83], off offset:576
	v_cvt_f32_i32_e32 v79, v79
	v_cvt_f32_i32_e32 v78, v78
	v_cvt_f32_i32_e32 v81, v81
	v_cvt_f32_i32_e32 v80, v80
	v_mov_b32_e32 v201, v200
	s_waitcnt vmcnt(10)
	v_lshlrev_b64 v[114:115], 12, v[130:131]
	v_pk_mul_f32 v[78:79], v[200:201], v[78:79] op_sel_hi:[0,1]
	v_lshl_add_u64 v[124:125], v[114:115], 0, v[190:191]
	s_waitcnt vmcnt(8)
	v_pk_fma_f32 v[78:79], v[62:63], v[78:79], v[110:111]
	v_cvt_f32_i32_e32 v121, v75
	v_cvt_f32_i32_e32 v120, v74
	v_cvt_f32_i32_e32 v123, v77
	v_cvt_f32_i32_e32 v122, v76
	v_cvt_f32_i32_e32 v117, v71
	v_cvt_f32_i32_e32 v116, v70
	v_cvt_f32_i32_e32 v119, v73
	v_cvt_f32_i32_e32 v118, v72
	v_cvt_f32_i32_e32 v111, v67
	v_cvt_f32_i32_e32 v110, v66
	v_cvt_f32_i32_e32 v115, v69
	v_cvt_f32_i32_e32 v114, v68
	v_readlane_b32 s68, v254, 8
	v_pk_mul_f32 v[80:81], v[200:201], v[80:81] op_sel_hi:[0,1]
	v_readlane_b32 s74, v254, 14
	v_readlane_b32 s75, v254, 15
	v_pk_fma_f32 v[80:81], v[64:65], v[80:81], v[112:113]
	s_and_b64 vcc, exec, s[8:9]
	s_mov_b64 s[98:99], 0x20000
	v_lshl_add_u64 v[112:113], v[250:251], 0, s[98:99]
	v_readlane_b32 s69, v254, 9
	v_readlane_b32 s70, v254, 10
	v_readlane_b32 s71, v254, 11
	v_readlane_b32 s72, v254, 12
	v_readlane_b32 s73, v254, 13
	global_store_dwordx4 v[112:113], v[78:81], off
	s_cbranch_vccnz .LBB0_1787
	v_readlane_b32 s2, v254, 40
	v_lshlrev_b64 v[128:129], 1, v[124:125]
	v_readlane_b32 s3, v254, 41
	s_nop 0
	v_cvt_pk_bf16_f32 v66, v78, v79
	s_nop 0
	v_cvt_pk_bf16_f32 v67, v80, v81
	v_mov_b32_e32 v74, v200
	v_mov_b32_e32 v75, v200
	v_lshl_add_u64 v[68:69], s[2:3], 0, v[128:129]
	global_store_dwordx2 v[68:69], v[66:67], off
	v_mul_f32_e32 v66, v79, v79
	v_mul_f32_e32 v67, v81, v81
	v_fmac_f32_e32 v66, v78, v78
	v_fmac_f32_e32 v67, v80, v80
	v_add_f32_e32 v76, v66, v67
	v_pk_mul_f32 v[66:67], v[74:75], v[122:123]
	v_pk_mul_f32 v[70:71], v[200:201], v[120:121]
	s_waitcnt vmcnt(9)
	v_pk_fma_f32 v[68:69], v[44:45], v[66:67], v[108:109]
	v_pk_fma_f32 v[66:67], v[42:43], v[70:71], v[106:107]
	v_or_b32_e32 v72, 32, v128
	v_mov_b32_e32 v73, v129
	global_store_dwordx4 v[112:113], v[66:69], off offset:1024
	s_nop 0
	v_cvt_pk_bf16_f32 v70, v66, v67
	s_nop 0
	v_cvt_pk_bf16_f32 v71, v68, v69
	v_lshl_add_u64 v[72:73], s[2:3], 0, v[72:73]
	global_store_dwordx2 v[72:73], v[70:71], off
	v_mul_f32_e32 v70, v67, v67
	v_mul_f32_e32 v71, v69, v69
	v_fmac_f32_e32 v70, v66, v66
	v_fmac_f32_e32 v71, v68, v68
	v_add_f32_e32 v70, v70, v71
	v_add_f32_e32 v124, v76, v70
	v_pk_mul_f32 v[70:71], v[74:75], v[118:119]
	v_pk_mul_f32 v[76:77], v[200:201], v[116:117]
	s_waitcnt vmcnt(10)
	v_pk_fma_f32 v[72:73], v[40:41], v[70:71], v[104:105]
	v_pk_fma_f32 v[70:71], v[38:39], v[76:77], v[102:103]
	v_mul_f32_e32 v77, v73, v73
	v_mul_f32_e32 v76, v71, v71
	v_fmac_f32_e32 v76, v70, v70
	v_fmac_f32_e32 v77, v72, v72
	v_add_f32_e32 v76, v76, v77
	v_add_f32_e32 v134, v124, v76
	v_pk_mul_f32 v[74:75], v[74:75], v[114:115]
	v_pk_mul_f32 v[124:125], v[200:201], v[110:111]
	s_waitcnt vmcnt(9)
	v_pk_fma_f32 v[76:77], v[36:37], v[74:75], v[100:101]
	v_pk_fma_f32 v[74:75], v[34:35], v[124:125], v[98:99]
	v_mul_f32_e32 v125, v77, v77
	v_mul_f32_e32 v124, v75, v75
	v_fmac_f32_e32 v124, v74, v74
	v_fmac_f32_e32 v125, v76, v76
	v_add_f32_e32 v124, v124, v125
	v_add_f32_e32 v125, v134, v124
	v_and_b32_e32 v134, 64, v236
	v_xor_b32_e32 v124, 16, v236
	v_add_u32_e32 v134, 64, v134
	v_cmp_lt_i32_e32 vcc, v124, v134
	v_or_b32_e32 v132, 0x100, v128
	v_mov_b32_e32 v133, v129
	v_cndmask_b32_e32 v124, v236, v124, vcc
	v_lshlrev_b32_e32 v124, 2, v124
	ds_bpermute_b32 v135, v124, v125
	global_store_dwordx4 v[112:113], v[70:73], off offset:2048
	s_nop 0
	v_cvt_pk_bf16_f32 v126, v70, v71
	s_nop 0
	v_cvt_pk_bf16_f32 v127, v72, v73
	v_lshl_add_u64 v[132:133], s[2:3], 0, v[132:133]
	global_store_dwordx2 v[132:133], v[126:127], off
	global_store_dwordx4 v[112:113], v[74:77], off offset:3072
	s_waitcnt lgkmcnt(0)
	v_add_f32_e32 v126, v125, v135
	v_xor_b32_e32 v125, 32, v236
	v_cmp_lt_i32_e32 vcc, v125, v134
	v_or_b32_e32 v128, 0x120, v128
	v_lshl_add_u64 v[128:129], s[2:3], 0, v[128:129]
	v_cndmask_b32_e32 v125, v236, v125, vcc
	v_lshlrev_b32_e32 v125, 2, v125
	ds_bpermute_b32 v127, v125, v126
	s_nop 0
	v_cvt_pk_bf16_f32 v132, v74, v75
	s_nop 0
	v_cvt_pk_bf16_f32 v133, v76, v77
	global_store_dwordx2 v[128:129], v[132:133], off
	s_and_saveexec_b64 s[2:3], s[6:7]
	s_cbranch_execz .LBB0_1755
	v_lshl_add_u64 v[128:129], v[130:131], 2, s[10:11]
	s_waitcnt lgkmcnt(0)
	v_add_f32_e32 v126, v126, v127
	global_atomic_add_f32 v[128:129], v126, off

; __device__ __forceinline__ unsigned cvt_pk_bf16(float lo, float hi) { unsigned r; asm volatile("s_nop 0\n\tv_cvt_pk_bf16_f32 %0, %1, %2" : "=v"(r) : "v"(lo), "v"(hi)); return r; }
; __device__ __forceinline__ f32x4 sig4(const f32x4 v) { return (f32x4){sigmoidf_(v[0]), sigmoidf_(v[1]), sigmoidf_(v[2]), sigmoidf_(v[3])}; }
;     __device__ __forceinline__ void operator()(const typename AccT<I8>::type (&acc)[2][2][4][2], const Unit& u, int wr, int wc, int fr, int fq) const {
;     ...
;         for (int s = 0; s < 8; ++s) { const int ai = s >> 2, m = s & 3; const int r = row0 + ai * HALF + m * 16; const size_t off = (size_t)r * 4096 + col0;
;                 if (s + 1 < 8) load_row(nxt, (size_t)(row0 + ((s + 1) >> 2) * HALF + ((s + 1) & 3) * 16) * 4096 + col0);
;                 const float rs = rsv[s];
;                 float ss = 0.f, mx = 0.f;
; #pragma unroll
;                 for (int bj = 0; bj < 2; ++bj)
; #pragma unroll
;                     for (int n = 0; n < 2; ++n) { const size_t o = off + bj * HALF + n * 16; const f32x4 b = cur.b[bj][n]; f32x4 v;
;                         if constexpr (I8) v = __builtin_convertvector(acc[ai][bj][m][n], f32x4) * rs * sv[bj][n]; else v = acc[ai][bj][m][n];
;                         if (MODE == 1) { const u32x2 pw = cur.pw[bj][n]; const f32x4 pp = (f32x4){bf_lo(pw.x), bf_hi(pw.x), bf_lo(pw.y), bf_hi(pw.y)}; v = sig4(I8 ? v : v * rs) * pp; }
;                         const f32x4 x = b + v; *(f32x4*)(out + o) = x;
;                         if (MODE == 0 && XB) { u32x2 w; w.x = cvt_pk_bf16(x[0], x[1]); w.y = cvt_pk_bf16(x[2], x[3]); *(u32x2*)(XB + o) = w; ss += (x[0] * x[0] + x[1] * x[1]) + (x[2] * x[2] + x[3] * x[3]);
;                             if (RM) mx = fmaxf(fmaxf(mx, fmaxf(fabsf(x[0]), fabsf(x[1]))), fmaxf(fabsf(x[2]), fabsf(x[3]))); } }
;                 if (MODE == 0 && XB) { ss += __shfl_xor(ss, 16); ss += __shfl_xor(ss, 32); if (fq == 0) unsafeAtomicAdd(SS + r, ss);
;                     if (RM) { mx = fmaxf(mx, __shfl_xor(mx, 16)); mx = fmaxf(mx, __shfl_xor(mx, 32)); if (fq == 0) atomicMax(RM + r, __builtin_bit_cast(unsigned, mx)); } }
.LBB0_1759:
	s_waitcnt lgkmcnt(0)
	s_nop 0
	v_lshlrev_b64 v[66:67], 14, v[194:195]
	v_lshl_add_u64 v[66:67], s[64:65], 0, v[66:67]
	v_lshl_add_u64 v[66:67], v[190:191], 2, v[66:67]
	global_load_dwordx4 v[78:81], v[66:67], off
	global_load_dwordx4 v[74:77], v[66:67], off offset:64
	global_load_dwordx4 v[70:73], v[66:67], off offset:512
	s_nop 0
	global_load_dwordx4 v[66:69], v[66:67], off offset:576
	v_cvt_f32_i32_e32 v59, v59
	v_cvt_f32_i32_e32 v58, v58
	v_cvt_f32_i32_e32 v61, v61
	v_cvt_f32_i32_e32 v60, v60
	v_mov_b32_e32 v197, v196
	s_waitcnt vmcnt(10)
	v_lshlrev_b64 v[98:99], 12, v[198:199]
	v_pk_mul_f32 v[58:59], v[196:197], v[58:59] op_sel_hi:[0,1]
	v_lshl_add_u64 v[108:109], v[98:99], 0, v[190:191]
	s_waitcnt vmcnt(8)
	v_pk_fma_f32 v[58:59], v[62:63], v[58:59], v[94:95]
	v_cvt_f32_i32_e32 v105, v55
	v_cvt_f32_i32_e32 v104, v54
	v_cvt_f32_i32_e32 v107, v57
	v_cvt_f32_i32_e32 v106, v56
	v_cvt_f32_i32_e32 v101, v51
	v_cvt_f32_i32_e32 v100, v50
	v_cvt_f32_i32_e32 v103, v53
	v_cvt_f32_i32_e32 v102, v52
	v_cvt_f32_i32_e32 v95, v47
	v_cvt_f32_i32_e32 v94, v46
	v_cvt_f32_i32_e32 v99, v49
	v_cvt_f32_i32_e32 v98, v48
	v_readlane_b32 s68, v254, 8
	v_pk_mul_f32 v[60:61], v[196:197], v[60:61] op_sel_hi:[0,1]
	v_readlane_b32 s74, v254, 14
	v_readlane_b32 s75, v254, 15
	v_pk_fma_f32 v[60:61], v[64:65], v[60:61], v[96:97]
	s_and_b64 vcc, exec, s[8:9]
	s_mov_b64 s[98:99], 0x28000
	v_lshl_add_u64 v[96:97], v[250:251], 0, s[98:99]
	v_readlane_b32 s69, v254, 9
	v_readlane_b32 s70, v254, 10
	v_readlane_b32 s71, v254, 11
	v_readlane_b32 s72, v254, 12
	v_readlane_b32 s73, v254, 13
	global_store_dwordx4 v[96:97], v[58:61], off
	s_cbranch_vccnz .LBB0_1788
	v_readlane_b32 s2, v254, 40
	v_lshlrev_b64 v[112:113], 1, v[108:109]
	v_readlane_b32 s3, v254, 41
	s_nop 0
	v_cvt_pk_bf16_f32 v46, v58, v59
	s_nop 0
	v_cvt_pk_bf16_f32 v47, v60, v61
	v_mov_b32_e32 v54, v196
	v_mov_b32_e32 v55, v196
	v_lshl_add_u64 v[48:49], s[2:3], 0, v[112:113]
	global_store_dwordx2 v[48:49], v[46:47], off
	v_mul_f32_e32 v46, v59, v59
	v_mul_f32_e32 v47, v61, v61
	v_fmac_f32_e32 v46, v58, v58
	v_fmac_f32_e32 v47, v60, v60
	v_add_f32_e32 v56, v46, v47
	v_pk_mul_f32 v[46:47], v[54:55], v[106:107]
	v_pk_mul_f32 v[50:51], v[196:197], v[104:105]
	s_waitcnt vmcnt(9)
	v_pk_fma_f32 v[48:49], v[44:45], v[46:47], v[92:93]
	v_pk_fma_f32 v[46:47], v[42:43], v[50:51], v[90:91]
	v_or_b32_e32 v52, 32, v112
	v_mov_b32_e32 v53, v113
	global_store_dwordx4 v[96:97], v[46:49], off offset:1024
	s_nop 0
	v_cvt_pk_bf16_f32 v50, v46, v47
	s_nop 0
	v_cvt_pk_bf16_f32 v51, v48, v49
	v_lshl_add_u64 v[52:53], s[2:3], 0, v[52:53]
	global_store_dwordx2 v[52:53], v[50:51], off
	v_mul_f32_e32 v50, v47, v47
	v_mul_f32_e32 v51, v49, v49
	v_fmac_f32_e32 v50, v46, v46
	v_fmac_f32_e32 v51, v48, v48
	v_add_f32_e32 v50, v50, v51
	v_add_f32_e32 v108, v56, v50
	v_pk_mul_f32 v[50:51], v[54:55], v[102:103]
	v_pk_mul_f32 v[56:57], v[196:197], v[100:101]
	s_waitcnt vmcnt(10)
	v_pk_fma_f32 v[52:53], v[40:41], v[50:51], v[88:89]
	v_pk_fma_f32 v[50:51], v[38:39], v[56:57], v[86:87]
	v_mul_f32_e32 v57, v53, v53
	v_mul_f32_e32 v56, v51, v51
	v_fmac_f32_e32 v56, v50, v50
	v_fmac_f32_e32 v57, v52, v52
	v_add_f32_e32 v56, v56, v57
	v_add_f32_e32 v116, v108, v56
	v_pk_mul_f32 v[54:55], v[54:55], v[98:99]
	v_pk_mul_f32 v[108:109], v[196:197], v[94:95]
	s_waitcnt vmcnt(9)
	v_pk_fma_f32 v[56:57], v[36:37], v[54:55], v[84:85]
	v_pk_fma_f32 v[54:55], v[34:35], v[108:109], v[82:83]
	v_mul_f32_e32 v109, v57, v57
	v_mul_f32_e32 v108, v55, v55
	v_fmac_f32_e32 v108, v54, v54
	v_fmac_f32_e32 v109, v56, v56
	v_add_f32_e32 v108, v108, v109
	v_add_f32_e32 v109, v116, v108
	v_and_b32_e32 v116, 64, v236
	v_xor_b32_e32 v108, 16, v236
	v_add_u32_e32 v116, 64, v116
	v_cmp_lt_i32_e32 vcc, v108, v116
	v_or_b32_e32 v114, 0x100, v112
	v_mov_b32_e32 v115, v113
	v_cndmask_b32_e32 v108, v236, v108, vcc
	v_lshlrev_b32_e32 v108, 2, v108
	ds_bpermute_b32 v117, v108, v109
	global_store_dwordx4 v[96:97], v[50:53], off offset:2048
	s_nop 0
	v_cvt_pk_bf16_f32 v110, v50, v51
	s_nop 0
	v_cvt_pk_bf16_f32 v111, v52, v53
	v_lshl_add_u64 v[114:115], s[2:3], 0, v[114:115]
	global_store_dwordx2 v[114:115], v[110:111], off
	global_store_dwordx4 v[96:97], v[54:57], off offset:3072
	s_waitcnt lgkmcnt(0)
	v_add_f32_e32 v110, v109, v117
	v_xor_b32_e32 v109, 32, v236
	v_cmp_lt_i32_e32 vcc, v109, v116
	v_or_b32_e32 v112, 0x120, v112
	v_lshl_add_u64 v[112:113], s[2:3], 0, v[112:113]
	v_cndmask_b32_e32 v109, v236, v109, vcc
	v_lshlrev_b32_e32 v109, 2, v109
	ds_bpermute_b32 v111, v109, v110
	s_nop 0
	v_cvt_pk_bf16_f32 v114, v54, v55
	s_nop 0
	v_cvt_pk_bf16_f32 v115, v56, v57
	global_store_dwordx2 v[112:113], v[114:115], off
	s_and_saveexec_b64 s[2:3], s[6:7]
	s_cbranch_execz .LBB0_1762
	v_lshl_add_u64 v[112:113], v[198:199], 2, s[10:11]
	s_waitcnt lgkmcnt(0)
	v_add_f32_e32 v110, v110, v111
	global_atomic_add_f32 v[112:113], v110, off

; __device__ __forceinline__ unsigned cvt_pk_bf16(float lo, float hi) { unsigned r; asm volatile("s_nop 0\n\tv_cvt_pk_bf16_f32 %0, %1, %2" : "=v"(r) : "v"(lo), "v"(hi)); return r; }
; __device__ __forceinline__ f32x4 sig4(const f32x4 v) { return (f32x4){sigmoidf_(v[0]), sigmoidf_(v[1]), sigmoidf_(v[2]), sigmoidf_(v[3])}; }
;     __device__ __forceinline__ void operator()(const typename AccT<I8>::type (&acc)[2][2][4][2], const Unit& u, int wr, int wc, int fr, int fq) const {
;     ...
;         for (int s = 0; s < 8; ++s) { const int ai = s >> 2, m = s & 3; const int r = row0 + ai * HALF + m * 16; const size_t off = (size_t)r * 4096 + col0;
;                 if (s + 1 < 8) load_row(nxt, (size_t)(row0 + ((s + 1) >> 2) * HALF + ((s + 1) & 3) * 16) * 4096 + col0);
;                 const float rs = rsv[s];
;                 float ss = 0.f, mx = 0.f;
; #pragma unroll
;                 for (int bj = 0; bj < 2; ++bj)
; #pragma unroll
;                     for (int n = 0; n < 2; ++n) { const size_t o = off + bj * HALF + n * 16; const f32x4 b = cur.b[bj][n]; f32x4 v;
;                         if constexpr (I8) v = __builtin_convertvector(acc[ai][bj][m][n], f32x4) * rs * sv[bj][n]; else v = acc[ai][bj][m][n];
;                         if (MODE == 1) { const u32x2 pw = cur.pw[bj][n]; const f32x4 pp = (f32x4){bf_lo(pw.x), bf_hi(pw.x), bf_lo(pw.y), bf_hi(pw.y)}; v = sig4(I8 ? v : v * rs) * pp; }
;                         const f32x4 x = b + v; *(f32x4*)(out + o) = x;
;                         if (MODE == 0 && XB) { u32x2 w; w.x = cvt_pk_bf16(x[0], x[1]); w.y = cvt_pk_bf16(x[2], x[3]); *(u32x2*)(XB + o) = w; ss += (x[0] * x[0] + x[1] * x[1]) + (x[2] * x[2] + x[3] * x[3]);
;                             if (RM) mx = fmaxf(fmaxf(mx, fmaxf(fabsf(x[0]), fabsf(x[1]))), fmaxf(fabsf(x[2]), fabsf(x[3]))); } }
;                 if (MODE == 0 && XB) { ss += __shfl_xor(ss, 16); ss += __shfl_xor(ss, 32); if (fq == 0) unsafeAtomicAdd(SS + r, ss);
;                     if (RM) { mx = fmaxf(mx, __shfl_xor(mx, 16)); mx = fmaxf(mx, __shfl_xor(mx, 32)); if (fq == 0) atomicMax(RM + r, __builtin_bit_cast(unsigned, mx)); } }
.LBB0_1766:
	s_waitcnt lgkmcnt(0)
	s_nop 0
	v_lshlrev_b64 v[46:47], 14, v[188:189]
	v_lshl_add_u64 v[46:47], s[64:65], 0, v[46:47]
	v_lshl_add_u64 v[46:47], v[190:191], 2, v[46:47]
	global_load_dwordx4 v[58:61], v[46:47], off
	global_load_dwordx4 v[54:57], v[46:47], off offset:64
	global_load_dwordx4 v[50:53], v[46:47], off offset:512
	s_nop 0
	global_load_dwordx4 v[46:49], v[46:47], off offset:576
	v_cvt_f32_i32_e32 v31, v31
	v_cvt_f32_i32_e32 v30, v30
	v_cvt_f32_i32_e32 v33, v33
	v_cvt_f32_i32_e32 v32, v32
	v_mov_b32_e32 v193, v192
	s_waitcnt vmcnt(10)
	v_lshlrev_b64 v[82:83], 12, v[194:195]
	v_pk_mul_f32 v[30:31], v[192:193], v[30:31] op_sel_hi:[0,1]
	v_lshl_add_u64 v[92:93], v[82:83], 0, v[190:191]
	s_waitcnt vmcnt(8)
	v_pk_fma_f32 v[30:31], v[62:63], v[30:31], v[78:79]
	v_cvt_f32_i32_e32 v89, v27
	v_cvt_f32_i32_e32 v88, v26
	v_cvt_f32_i32_e32 v91, v29
	v_cvt_f32_i32_e32 v90, v28
	v_cvt_f32_i32_e32 v85, v23
	v_cvt_f32_i32_e32 v84, v22
	v_cvt_f32_i32_e32 v87, v25
	v_cvt_f32_i32_e32 v86, v24
	v_cvt_f32_i32_e32 v79, v19
	v_cvt_f32_i32_e32 v78, v18
	v_cvt_f32_i32_e32 v83, v21
	v_cvt_f32_i32_e32 v82, v20
	v_readlane_b32 s68, v254, 8
	v_pk_mul_f32 v[32:33], v[192:193], v[32:33] op_sel_hi:[0,1]
	v_readlane_b32 s74, v254, 14
	v_readlane_b32 s75, v254, 15
	v_pk_fma_f32 v[32:33], v[64:65], v[32:33], v[80:81]
	s_and_b64 vcc, exec, s[8:9]
	s_mov_b64 s[98:99], 0x30000
	v_lshl_add_u64 v[80:81], v[250:251], 0, s[98:99]
	v_readlane_b32 s69, v254, 9
	v_readlane_b32 s70, v254, 10
	v_readlane_b32 s71, v254, 11
	v_readlane_b32 s72, v254, 12
	v_readlane_b32 s73, v254, 13
	global_store_dwordx4 v[80:81], v[30:33], off
	s_cbranch_vccnz .LBB0_1789
	v_readlane_b32 s2, v254, 40
	v_lshlrev_b64 v[96:97], 1, v[92:93]
	v_readlane_b32 s3, v254, 41
	s_nop 0
	v_cvt_pk_bf16_f32 v18, v30, v31
	s_nop 0
	v_cvt_pk_bf16_f32 v19, v32, v33
	v_mov_b32_e32 v26, v192
	v_mov_b32_e32 v27, v192
	v_lshl_add_u64 v[20:21], s[2:3], 0, v[96:97]
	global_store_dwordx2 v[20:21], v[18:19], off
	v_mul_f32_e32 v18, v31, v31
	v_mul_f32_e32 v19, v33, v33
	v_fmac_f32_e32 v18, v30, v30
	v_fmac_f32_e32 v19, v32, v32
	v_add_f32_e32 v28, v18, v19
	v_pk_mul_f32 v[18:19], v[26:27], v[90:91]
	v_pk_mul_f32 v[22:23], v[192:193], v[88:89]
	s_waitcnt vmcnt(9)
	v_pk_fma_f32 v[20:21], v[44:45], v[18:19], v[76:77]
	v_pk_fma_f32 v[18:19], v[42:43], v[22:23], v[74:75]
	v_or_b32_e32 v24, 32, v96
	v_mov_b32_e32 v25, v97
	global_store_dwordx4 v[80:81], v[18:21], off offset:1024
	s_nop 0
	v_cvt_pk_bf16_f32 v22, v18, v19
	s_nop 0
	v_cvt_pk_bf16_f32 v23, v20, v21
	v_lshl_add_u64 v[24:25], s[2:3], 0, v[24:25]
	global_store_dwordx2 v[24:25], v[22:23], off
	v_mul_f32_e32 v22, v19, v19
	v_mul_f32_e32 v23, v21, v21
	v_fmac_f32_e32 v22, v18, v18
	v_fmac_f32_e32 v23, v20, v20
	v_add_f32_e32 v22, v22, v23
	v_add_f32_e32 v92, v28, v22
	v_pk_mul_f32 v[22:23], v[26:27], v[86:87]
	v_pk_mul_f32 v[28:29], v[192:193], v[84:85]
	s_waitcnt vmcnt(10)
	v_pk_fma_f32 v[24:25], v[40:41], v[22:23], v[72:73]
	v_pk_fma_f32 v[22:23], v[38:39], v[28:29], v[70:71]
	v_mul_f32_e32 v29, v25, v25
	v_mul_f32_e32 v28, v23, v23
	v_fmac_f32_e32 v28, v22, v22
	v_fmac_f32_e32 v29, v24, v24
	v_add_f32_e32 v28, v28, v29
	v_add_f32_e32 v100, v92, v28
	v_pk_mul_f32 v[26:27], v[26:27], v[82:83]
	v_pk_mul_f32 v[92:93], v[192:193], v[78:79]
	s_waitcnt vmcnt(9)
	v_pk_fma_f32 v[28:29], v[36:37], v[26:27], v[68:69]
	v_pk_fma_f32 v[26:27], v[34:35], v[92:93], v[66:67]
	v_mul_f32_e32 v93, v29, v29
	v_mul_f32_e32 v92, v27, v27
	v_fmac_f32_e32 v92, v26, v26
	v_fmac_f32_e32 v93, v28, v28
	v_add_f32_e32 v92, v92, v93
	v_add_f32_e32 v93, v100, v92
	v_and_b32_e32 v100, 64, v236
	v_xor_b32_e32 v92, 16, v236
	v_add_u32_e32 v100, 64, v100
	v_cmp_lt_i32_e32 vcc, v92, v100
	v_or_b32_e32 v98, 0x100, v96
	v_mov_b32_e32 v99, v97
	v_cndmask_b32_e32 v92, v236, v92, vcc
	v_lshlrev_b32_e32 v92, 2, v92
	ds_bpermute_b32 v101, v92, v93
	global_store_dwordx4 v[80:81], v[22:25], off offset:2048
	s_nop 0
	v_cvt_pk_bf16_f32 v94, v22, v23
	s_nop 0
	v_cvt_pk_bf16_f32 v95, v24, v25
	v_lshl_add_u64 v[98:99], s[2:3], 0, v[98:99]
	global_store_dwordx2 v[98:99], v[94:95], off
	global_store_dwordx4 v[80:81], v[26:29], off offset:3072
	s_waitcnt lgkmcnt(0)
	v_add_f32_e32 v94, v93, v101
	v_xor_b32_e32 v93, 32, v236
	v_cmp_lt_i32_e32 vcc, v93, v100
	v_or_b32_e32 v96, 0x120, v96
	v_lshl_add_u64 v[96:97], s[2:3], 0, v[96:97]
	v_cndmask_b32_e32 v93, v236, v93, vcc
	v_lshlrev_b32_e32 v93, 2, v93
	ds_bpermute_b32 v95, v93, v94
	s_nop 0
	v_cvt_pk_bf16_f32 v98, v26, v27
	s_nop 0
	v_cvt_pk_bf16_f32 v99, v28, v29
	global_store_dwordx2 v[96:97], v[98:99], off
	s_and_saveexec_b64 s[2:3], s[6:7]
	s_cbranch_execz .LBB0_1769
	v_lshl_add_u64 v[96:97], v[194:195], 2, s[10:11]
	s_waitcnt lgkmcnt(0)
	v_add_f32_e32 v94, v94, v95
	global_atomic_add_f32 v[96:97], v94, off

; __device__ __forceinline__ unsigned cvt_pk_bf16(float lo, float hi) { unsigned r; asm volatile("s_nop 0\n\tv_cvt_pk_bf16_f32 %0, %1, %2" : "=v"(r) : "v"(lo), "v"(hi)); return r; }
; __device__ __forceinline__ f32x4 sig4(const f32x4 v) { return (f32x4){sigmoidf_(v[0]), sigmoidf_(v[1]), sigmoidf_(v[2]), sigmoidf_(v[3])}; }
;     __device__ __forceinline__ void operator()(const typename AccT<I8>::type (&acc)[2][2][4][2], const Unit& u, int wr, int wc, int fr, int fq) const {
;     ...
;         for (int s = 0; s < 8; ++s) { const int ai = s >> 2, m = s & 3; const int r = row0 + ai * HALF + m * 16; const size_t off = (size_t)r * 4096 + col0;
;                 if (s + 1 < 8) load_row(nxt, (size_t)(row0 + ((s + 1) >> 2) * HALF + ((s + 1) & 3) * 16) * 4096 + col0);
;                 const float rs = rsv[s];
;                 float ss = 0.f, mx = 0.f;
; #pragma unroll
;                 for (int bj = 0; bj < 2; ++bj)
; #pragma unroll
;                     for (int n = 0; n < 2; ++n) { const size_t o = off + bj * HALF + n * 16; const f32x4 b = cur.b[bj][n]; f32x4 v;
;                         if constexpr (I8) v = __builtin_convertvector(acc[ai][bj][m][n], f32x4) * rs * sv[bj][n]; else v = acc[ai][bj][m][n];
;                         if (MODE == 1) { const u32x2 pw = cur.pw[bj][n]; const f32x4 pp = (f32x4){bf_lo(pw.x), bf_hi(pw.x), bf_lo(pw.y), bf_hi(pw.y)}; v = sig4(I8 ? v : v * rs) * pp; }
;                         const f32x4 x = b + v; *(f32x4*)(out + o) = x;
;                         if (MODE == 0 && XB) { u32x2 w; w.x = cvt_pk_bf16(x[0], x[1]); w.y = cvt_pk_bf16(x[2], x[3]); *(u32x2*)(XB + o) = w; ss += (x[0] * x[0] + x[1] * x[1]) + (x[2] * x[2] + x[3] * x[3]);
;                             if (RM) mx = fmaxf(fmaxf(mx, fmaxf(fabsf(x[0]), fabsf(x[1]))), fmaxf(fabsf(x[2]), fabsf(x[3]))); } }
;                 if (MODE == 0 && XB) { ss += __shfl_xor(ss, 16); ss += __shfl_xor(ss, 32); if (fq == 0) unsafeAtomicAdd(SS + r, ss);
;                     if (RM) { mx = fmaxf(mx, __shfl_xor(mx, 16)); mx = fmaxf(mx, __shfl_xor(mx, 32)); if (fq == 0) atomicMax(RM + r, __builtin_bit_cast(unsigned, mx)); } }
.LBB0_1773:
	v_cvt_f32_i32_e32 v17, v17
	v_cvt_f32_i32_e32 v15, v15
	v_cvt_f32_i32_e32 v14, v14
	v_cvt_f32_i32_e32 v16, v16
	s_waitcnt lgkmcnt(0)
	v_lshlrev_b64 v[18:19], 12, v[188:189]
	v_lshl_add_u64 v[32:33], v[18:19], 0, v[190:191]
	v_cvt_f32_i32_e32 v29, v11
	v_cvt_f32_i32_e32 v28, v10
	v_cvt_f32_i32_e32 v31, v13
	v_cvt_f32_i32_e32 v30, v12
	v_cvt_f32_i32_e32 v25, v7
	v_cvt_f32_i32_e32 v24, v6
	v_cvt_f32_i32_e32 v27, v9
	v_cvt_f32_i32_e32 v26, v8
	v_cvt_f32_i32_e32 v19, v3
	v_cvt_f32_i32_e32 v18, v2
	v_cvt_f32_i32_e32 v23, v5
	v_cvt_f32_i32_e32 v22, v4
	v_mov_b32_e32 v187, v186
	v_readlane_b32 s68, v254, 8
	v_pk_mul_f32 v[14:15], v[186:187], v[14:15] op_sel_hi:[0,1]
	v_pk_mul_f32 v[16:17], v[186:187], v[16:17] op_sel_hi:[0,1]
	v_readlane_b32 s74, v254, 14
	v_readlane_b32 s75, v254, 15
	s_waitcnt vmcnt(4)
	v_pk_fma_f32 v[16:17], v[64:65], v[16:17], v[60:61]
	v_pk_fma_f32 v[14:15], v[62:63], v[14:15], v[58:59]
	s_mov_b64 s[98:99], 0x38000
	v_lshl_add_u64 v[20:21], v[250:251], 0, s[98:99]
	s_and_b64 vcc, exec, s[8:9]
	v_readlane_b32 s69, v254, 9
	v_readlane_b32 s70, v254, 10
	v_readlane_b32 s71, v254, 11
	v_readlane_b32 s72, v254, 12
	v_readlane_b32 s73, v254, 13
	global_store_dwordx4 v[20:21], v[14:17], off
	s_cbranch_vccnz .LBB0_1790
	v_readlane_b32 s2, v254, 40
	v_lshlrev_b64 v[60:61], 1, v[32:33]
	v_readlane_b32 s3, v254, 41
	s_nop 0
	v_cvt_pk_bf16_f32 v2, v14, v15
	s_nop 0
	v_cvt_pk_bf16_f32 v3, v16, v17
	v_mov_b32_e32 v10, v186
	v_mov_b32_e32 v11, v186
	v_lshl_add_u64 v[4:5], s[2:3], 0, v[60:61]
	global_store_dwordx2 v[4:5], v[2:3], off
	v_mul_f32_e32 v2, v15, v15
	v_mul_f32_e32 v3, v17, v17
	v_fmac_f32_e32 v2, v14, v14
	v_fmac_f32_e32 v3, v16, v16
	v_add_f32_e32 v12, v2, v3
	v_pk_mul_f32 v[2:3], v[10:11], v[30:31]
	v_pk_mul_f32 v[6:7], v[186:187], v[28:29]
	s_waitcnt vmcnt(5)
	v_pk_fma_f32 v[4:5], v[44:45], v[2:3], v[56:57]
	v_pk_fma_f32 v[2:3], v[42:43], v[6:7], v[54:55]
	v_or_b32_e32 v8, 32, v60
	v_mov_b32_e32 v9, v61
	global_store_dwordx4 v[20:21], v[2:5], off offset:1024
	s_nop 0
	v_cvt_pk_bf16_f32 v6, v2, v3
	s_nop 0
	v_cvt_pk_bf16_f32 v7, v4, v5
	v_lshl_add_u64 v[8:9], s[2:3], 0, v[8:9]
	global_store_dwordx2 v[8:9], v[6:7], off
	v_mul_f32_e32 v6, v3, v3
	v_mul_f32_e32 v7, v5, v5
	v_fmac_f32_e32 v6, v2, v2
	v_fmac_f32_e32 v7, v4, v4
	v_add_f32_e32 v6, v6, v7
	v_add_f32_e32 v32, v12, v6
	v_pk_mul_f32 v[6:7], v[10:11], v[26:27]
	v_pk_mul_f32 v[12:13], v[186:187], v[24:25]
	s_waitcnt vmcnt(6)
	v_pk_fma_f32 v[8:9], v[40:41], v[6:7], v[52:53]
	v_pk_fma_f32 v[6:7], v[38:39], v[12:13], v[50:51]
	v_mul_f32_e32 v13, v9, v9
	v_mul_f32_e32 v12, v7, v7
	v_fmac_f32_e32 v12, v6, v6
	v_fmac_f32_e32 v13, v8, v8
	v_add_f32_e32 v12, v12, v13
	v_add_f32_e32 v64, v32, v12
	v_pk_mul_f32 v[10:11], v[10:11], v[22:23]
	v_pk_mul_f32 v[32:33], v[186:187], v[18:19]
	s_waitcnt vmcnt(5)
	v_pk_fma_f32 v[12:13], v[36:37], v[10:11], v[48:49]
	v_pk_fma_f32 v[10:11], v[34:35], v[32:33], v[46:47]
	v_mul_f32_e32 v33, v13, v13
	v_mul_f32_e32 v32, v11, v11
	v_fmac_f32_e32 v32, v10, v10
	v_fmac_f32_e32 v33, v12, v12
	v_add_f32_e32 v32, v32, v33
	v_add_f32_e32 v33, v64, v32
	v_and_b32_e32 v64, 64, v236
	v_xor_b32_e32 v32, 16, v236
	v_add_u32_e32 v64, 64, v64
	v_cmp_lt_i32_e32 vcc, v32, v64
	v_or_b32_e32 v62, 0x100, v60
	v_mov_b32_e32 v63, v61
	v_cndmask_b32_e32 v32, v236, v32, vcc
	v_lshlrev_b32_e32 v32, 2, v32
	ds_bpermute_b32 v65, v32, v33
	global_store_dwordx4 v[20:21], v[6:9], off offset:2048
	s_nop 0
	v_cvt_pk_bf16_f32 v58, v6, v7
	s_nop 0
	v_cvt_pk_bf16_f32 v59, v8, v9
	v_lshl_add_u64 v[62:63], s[2:3], 0, v[62:63]
	global_store_dwordx2 v[62:63], v[58:59], off
	global_store_dwordx4 v[20:21], v[10:13], off offset:3072
	s_waitcnt lgkmcnt(0)
	v_add_f32_e32 v58, v33, v65
	v_xor_b32_e32 v33, 32, v236
	v_cmp_lt_i32_e32 vcc, v33, v64
	v_or_b32_e32 v60, 0x120, v60
	v_lshl_add_u64 v[60:61], s[2:3], 0, v[60:61]
	v_cndmask_b32_e32 v33, v236, v33, vcc
	v_lshlrev_b32_e32 v33, 2, v33
	ds_bpermute_b32 v59, v33, v58
	s_nop 0
	v_cvt_pk_bf16_f32 v62, v10, v11
	s_nop 0
	v_cvt_pk_bf16_f32 v63, v12, v13
	global_store_dwordx2 v[60:61], v[62:63], off
	s_and_saveexec_b64 s[2:3], s[6:7]
	s_cbranch_execz .LBB0_1776
	v_lshl_add_u64 v[60:61], v[188:189], 2, s[10:11]
	s_waitcnt lgkmcnt(0)
	v_add_f32_e32 v58, v58, v59
	global_atomic_add_f32 v[60:61], v58, off

;     __device__ __forceinline__ void operator()(const typename AccT<I8>::type (&acc)[2][2][4][2], const Unit& u, int wr, int wc, int fr, int fq) const {
;         const int row0 = u.pm * BM + wr * 64 + fr, col0 = u.pn * BM + wc * 32 + 4 * fq;
;         f32x4 sv[2][2];
;         if (I8) {
; #pragma unroll
;             for (int bj = 0; bj < 2; ++bj)
; #pragma unroll
;                 for (int n = 0; n < 2; ++n) sv[bj][n] = *(const f32x4*)(swc + col0 + bj * HALF + n * 16);
;         }
;         float rsv[8];
; #pragma unroll
;         for (int s = 0; s < 8; ++s) { const int r = row0 + (s >> 2) * HALF + (s & 3) * 16; float rs = 1.f; if (MODE == 1) rs = __builtin_amdgcn_rsqf(rstd[r] * (1.0f / 4096.0f) + 1e-6f); if (I8) rs *= sxr[r]; rsv[s] = rs; }
;         RowIn cur, nxt;
;         load_row(cur, (size_t)row0 * 4096 + col0);
; #pragma unroll
;         for (int s = 0; s < 8; ++s) { const int ai = s >> 2, m = s & 3; const int r = row0 + ai * HALF + m * 16; const size_t off = (size_t)r * 4096 + col0;
;                 if (s + 1 < 8) load_row(nxt, (size_t)(row0 + ((s + 1) >> 2) * HALF + ((s + 1) & 3) * 16) * 4096 + col0);
;                 const float rs = rsv[s];
;                 float ss = 0.f, mx = 0.f;
; #pragma unroll
;                 for (int bj = 0; bj < 2; ++bj)
; #pragma unroll
;                     for (int n = 0; n < 2; ++n) { const size_t o = off + bj * HALF + n * 16; const f32x4 b = cur.b[bj][n]; f32x4 v;
;                         if constexpr (I8) v = __builtin_convertvector(acc[ai][bj][m][n], f32x4) * rs * sv[bj][n]; else v = acc[ai][bj][m][n];
;                         if (MODE == 1) { const u32x2 pw = cur.pw[bj][n]; const f32x4 pp = (f32x4){bf_lo(pw.x), bf_hi(pw.x), bf_lo(pw.y), bf_hi(pw.y)}; v = sig4(I8 ? v : v * rs) * pp; }
;                         const f32x4 x = b + v; *(f32x4*)(out + o) = x;
;                         if (MODE == 0 && XB) { u32x2 w; w.x = cvt_pk_bf16(x[0], x[1]); w.y = cvt_pk_bf16(x[2], x[3]); *(u32x2*)(XB + o) = w; ss += (x[0] * x[0] + x[1] * x[1]) + (x[2] * x[2] + x[3] * x[3]);
;                             if (RM) mx = fmaxf(fmaxf(mx, fmaxf(fabsf(x[0]), fabsf(x[1]))), fmaxf(fabsf(x[2]), fabsf(x[3]))); } }
;                 if (MODE == 0 && XB) { ss += __shfl_xor(ss, 16); ss += __shfl_xor(ss, 32); if (fq == 0) unsafeAtomicAdd(SS + r, ss);
.LBB0_2095:
	s_lshl_b32 s98, s6, 4
	s_add_i32 s98, s98, s2
	s_sub_i32 s99, s98, 888
	s_cmp_lt_u32 s98, 888
	s_cselect_b32 s98, s98, s99
	s_mov_b32 s99, 0x4200000
	s_cselect_b32 s99, 0x3f600000, s99
	s_lshl_b32 s98, s98, 18
	s_add_u32 s98, s98, s99
	v_and_b32_e32 v250, 63, v0
	v_lshlrev_b32_e32 v250, 4, v250
	v_lshrrev_b32_e32 v251, 6, v0
	v_lshl_add_u32 v250, v251, 12, v250
	v_add_u32_e32 v250, s98, v250
	v_mov_b32_e32 v251, 0
	v_lshl_add_u64 v[250:251], s[96:97], 0, v[250:251]
	v_mov_b32_e32 v130, v0
	v_readlane_b32 s52, v254, 8
	v_ashrrev_i32_e32 v131, 2, v130
	v_and_b32_e32 v131, 0xffffffc0, v131
	v_lshl_add_u32 v131, s6, 8, v131
	v_bfe_u32 v162, v130, 4, 2
	v_and_or_b32 v184, v130, 15, v131
	v_lshrrev_b32_e32 v130, 1, v130
	v_and_b32_e32 v130, 0x60, v130
	v_lshl_or_b32 v130, s2, 8, v130
	v_lshl_or_b32 v182, v162, 2, v130
	v_ashrrev_i32_e32 v185, 31, v184
	v_readlane_b32 s58, v254, 14
	v_readlane_b32 s59, v254, 15
	v_ashrrev_i32_e32 v183, 31, v182
	v_lshlrev_b64 v[130:131], 14, v[184:185]
	s_mov_b64 s[6:7], s[58:59]
	v_or_b32_e32 v188, 16, v184
	v_lshl_add_u64 v[130:131], s[6:7], 0, v[130:131]
	v_lshlrev_b64 v[132:133], 2, v[182:183]
	v_ashrrev_i32_e32 v189, 31, v188
	s_mov_b64 s[98:99], 0x0
	v_lshl_add_u64 v[190:191], v[250:251], 0, s[98:99]
	v_lshlrev_b64 v[130:131], 14, v[188:189]
	v_lshl_add_u64 v[130:131], s[6:7], 0, v[130:131]
	s_mov_b64 s[98:99], 0x8000
	v_lshl_add_u64 v[186:187], v[250:251], 0, s[98:99]
	s_mov_b64 s[98:99], 0x0
	v_lshl_add_u64 v[252:253], v[250:251], 0, s[98:99]
	global_load_dwordx4 v[158:161], v[252:253], off
	global_load_dwordx4 v[154:157], v[252:253], off offset:1024
	global_load_dwordx4 v[150:153], v[252:253], off offset:2048
	global_load_dwordx4 v[146:149], v[252:253], off offset:3072
	s_mov_b64 s[98:99], 0x8000
	v_lshl_add_u64 v[252:253], v[250:251], 0, s[98:99]
	global_load_dwordx4 v[142:145], v[252:253], off
	global_load_dwordx4 v[138:141], v[252:253], off offset:1024
	global_load_dwordx4 v[134:137], v[252:253], off offset:2048
	global_load_dwordx4 v[130:133], v[252:253], off offset:3072
	v_cndmask_b32_e64 v163, 0, 1, s[18:19]
	v_cmp_ne_u32_e64 s[8:9], 1, v163
	s_andn2_b64 vcc, exec, s[18:19]
	v_cmp_eq_u32_e64 s[6:7], 0, v162
	v_readlane_b32 s53, v254, 9
	v_readlane_b32 s54, v254, 10
	v_readlane_b32 s55, v254, 11
	v_readlane_b32 s56, v254, 12
	v_readlane_b32 s57, v254, 13
	s_waitcnt vmcnt(0)
	v_pk_add_f32 v[168:169], v[128:129], v[160:161]
	v_pk_add_f32 v[166:167], v[126:127], v[158:159]
	v_pk_add_f32 v[162:163], v[122:123], v[154:155]
	v_pk_add_f32 v[158:159], v[118:119], v[150:151]
	v_pk_add_f32 v[126:127], v[114:115], v[146:147]
	global_store_dwordx4 v[190:191], v[166:169], off
	s_cbranch_vccnz .LBB0_2154
	v_lshlrev_b64 v[114:115], 12, v[184:185]
	v_lshl_add_u64 v[114:115], v[114:115], 0, v[182:183]
	v_readlane_b32 s2, v254, 40
	v_lshlrev_b64 v[122:123], 1, v[114:115]
	v_readlane_b32 s3, v254, 41
	s_nop 0
	v_cvt_pk_bf16_f32 v118, v166, v167
	s_nop 0
	v_cvt_pk_bf16_f32 v119, v168, v169
	v_pk_add_f32 v[164:165], v[124:125], v[156:157]
	v_pk_add_f32 v[160:161], v[120:121], v[152:153]
	v_lshl_add_u64 v[114:115], s[2:3], 0, v[122:123]
	global_store_dwordx2 v[114:115], v[118:119], off
	v_mul_f32_e32 v114, v167, v167
	v_mul_f32_e32 v115, v169, v169
	v_fmac_f32_e32 v114, v166, v166
	v_fmac_f32_e32 v115, v168, v168
	v_or_b32_e32 v118, 32, v122
	v_mov_b32_e32 v119, v123
	v_add_f32_e32 v128, v114, v115
	global_store_dwordx4 v[190:191], v[162:165], off offset:1024
	s_nop 0
	v_cvt_pk_bf16_f32 v114, v162, v163
	s_nop 0
	v_cvt_pk_bf16_f32 v115, v164, v165
	v_lshl_add_u64 v[118:119], s[2:3], 0, v[118:119]
	global_store_dwordx2 v[118:119], v[114:115], off
	v_mul_f32_e32 v114, v163, v163
	v_mul_f32_e32 v115, v165, v165
	v_fmac_f32_e32 v114, v162, v162
	v_fmac_f32_e32 v115, v164, v164
	v_add_f32_e32 v114, v114, v115
	v_add_f32_e32 v114, v128, v114
	v_mul_f32_e32 v115, v159, v159
	v_mul_f32_e32 v128, v161, v161
	v_fmac_f32_e32 v115, v158, v158
	v_fmac_f32_e32 v128, v160, v160
	v_add_f32_e32 v115, v115, v128
	v_pk_add_f32 v[128:129], v[116:117], v[148:149]
	v_add_f32_e32 v114, v114, v115
	v_mul_f32_e32 v115, v127, v127
	v_mul_f32_e32 v150, v129, v129
	v_fmac_f32_e32 v115, v126, v126
	v_fmac_f32_e32 v150, v128, v128
	v_add_f32_e32 v115, v115, v150
	v_and_b32_e32 v150, 64, v195
	v_add_f32_e32 v115, v114, v115
	v_xor_b32_e32 v114, 16, v195
	v_add_u32_e32 v150, 64, v150
	v_cmp_lt_i32_e32 vcc, v114, v150
	v_or_b32_e32 v146, 0x100, v122
	v_mov_b32_e32 v147, v123
	v_cndmask_b32_e32 v114, v195, v114, vcc
	v_lshlrev_b32_e32 v114, 2, v114
	ds_bpermute_b32 v151, v114, v115
	global_store_dwordx4 v[190:191], v[158:161], off offset:2048
	s_nop 0
	v_cvt_pk_bf16_f32 v118, v158, v159
	s_nop 0
	v_cvt_pk_bf16_f32 v119, v160, v161
	v_lshl_add_u64 v[146:147], s[2:3], 0, v[146:147]
	global_store_dwordx2 v[146:147], v[118:119], off
	global_store_dwordx4 v[190:191], v[126:129], off offset:3072
	s_waitcnt lgkmcnt(0)
	v_add_f32_e32 v118, v115, v151
	v_xor_b32_e32 v115, 32, v195
	v_cmp_lt_i32_e32 vcc, v115, v150
	v_or_b32_e32 v122, 0x120, v122
	v_lshl_add_u64 v[122:123], s[2:3], 0, v[122:123]
	v_cndmask_b32_e32 v115, v195, v115, vcc
	v_lshlrev_b32_e32 v115, 2, v115
	ds_bpermute_b32 v119, v115, v118
	s_nop 0
	v_cvt_pk_bf16_f32 v146, v126, v127
	s_nop 0
	v_cvt_pk_bf16_f32 v147, v128, v129
	global_store_dwordx2 v[122:123], v[146:147], off
	s_and_saveexec_b64 s[2:3], s[6:7]
	s_cbranch_execz .LBB0_2098
	v_lshl_add_u64 v[122:123], v[184:185], 2, s[10:11]
	s_waitcnt lgkmcnt(0)
	v_add_f32_e32 v118, v118, v119
	global_atomic_add_f32 v[122:123], v118, off

; __device__ __forceinline__ unsigned cvt_pk_bf16(float lo, float hi) { unsigned r; asm volatile("s_nop 0\n\tv_cvt_pk_bf16_f32 %0, %1, %2" : "=v"(r) : "v"(lo), "v"(hi)); return r; }
; __device__ __forceinline__ f32x4 sig4(const f32x4 v) { return (f32x4){sigmoidf_(v[0]), sigmoidf_(v[1]), sigmoidf_(v[2]), sigmoidf_(v[3])}; }
;     __device__ __forceinline__ void operator()(const typename AccT<I8>::type (&acc)[2][2][4][2], const Unit& u, int wr, int wc, int fr, int fq) const {
;     ...
;         for (int s = 0; s < 8; ++s) { const int ai = s >> 2, m = s & 3; const int r = row0 + ai * HALF + m * 16; const size_t off = (size_t)r * 4096 + col0;
;                 if (s + 1 < 8) load_row(nxt, (size_t)(row0 + ((s + 1) >> 2) * HALF + ((s + 1) & 3) * 16) * 4096 + col0);
;                 const float rs = rsv[s];
;                 float ss = 0.f, mx = 0.f;
; #pragma unroll
;                 for (int bj = 0; bj < 2; ++bj)
; #pragma unroll
;                     for (int n = 0; n < 2; ++n) { const size_t o = off + bj * HALF + n * 16; const f32x4 b = cur.b[bj][n]; f32x4 v;
;                         if constexpr (I8) v = __builtin_convertvector(acc[ai][bj][m][n], f32x4) * rs * sv[bj][n]; else v = acc[ai][bj][m][n];
;                         if (MODE == 1) { const u32x2 pw = cur.pw[bj][n]; const f32x4 pp = (f32x4){bf_lo(pw.x), bf_hi(pw.x), bf_lo(pw.y), bf_hi(pw.y)}; v = sig4(I8 ? v : v * rs) * pp; }
;                         const f32x4 x = b + v; *(f32x4*)(out + o) = x;
;                         if (MODE == 0 && XB) { u32x2 w; w.x = cvt_pk_bf16(x[0], x[1]); w.y = cvt_pk_bf16(x[2], x[3]); *(u32x2*)(XB + o) = w; ss += (x[0] * x[0] + x[1] * x[1]) + (x[2] * x[2] + x[3] * x[3]);
;                             if (RM) mx = fmaxf(fmaxf(mx, fmaxf(fabsf(x[0]), fabsf(x[1]))), fmaxf(fabsf(x[2]), fabsf(x[3]))); } }
;                 if (MODE == 0 && XB) { ss += __shfl_xor(ss, 16); ss += __shfl_xor(ss, 32); if (fq == 0) unsafeAtomicAdd(SS + r, ss);
;                     if (RM) { mx = fmaxf(mx, __shfl_xor(mx, 16)); mx = fmaxf(mx, __shfl_xor(mx, 32)); if (fq == 0) atomicMax(RM + r, __builtin_bit_cast(unsigned, mx)); } }
.LBB0_2102:
	v_or_b32_e32 v156, 32, v184
	v_ashrrev_i32_e32 v157, 31, v156
	v_readlane_b32 s52, v254, 8
	s_waitcnt lgkmcnt(0)
	v_lshlrev_b64 v[114:115], 14, v[156:157]
	v_readlane_b32 s58, v254, 14
	v_readlane_b32 s59, v254, 15
	v_pk_add_f32 v[152:153], v[112:113], v[144:145]
	v_pk_add_f32 v[150:151], v[110:111], v[142:143]
	v_lshl_add_u64 v[114:115], s[58:59], 0, v[114:115]
	s_mov_b64 s[98:99], 0x10000
	v_lshl_add_u64 v[154:155], v[250:251], 0, s[98:99]
	s_mov_b64 s[98:99], 0x10000
	v_lshl_add_u64 v[252:253], v[250:251], 0, s[98:99]
	global_load_dwordx4 v[126:129], v[252:253], off
	global_load_dwordx4 v[122:125], v[252:253], off offset:1024
	global_load_dwordx4 v[118:121], v[252:253], off offset:2048
	global_load_dwordx4 v[114:117], v[252:253], off offset:3072
	s_and_b64 vcc, exec, s[8:9]
	v_pk_add_f32 v[146:147], v[106:107], v[138:139]
	v_pk_add_f32 v[142:143], v[102:103], v[134:135]
	v_pk_add_f32 v[110:111], v[98:99], v[130:131]
	v_readlane_b32 s53, v254, 9
	v_readlane_b32 s54, v254, 10
	v_readlane_b32 s55, v254, 11
	v_readlane_b32 s56, v254, 12
	v_readlane_b32 s57, v254, 13
	global_store_dwordx4 v[186:187], v[150:153], off
	s_cbranch_vccnz .LBB0_2155
	v_lshlrev_b64 v[98:99], 12, v[188:189]
	v_lshl_add_u64 v[98:99], v[98:99], 0, v[182:183]
	v_readlane_b32 s2, v254, 40
	v_lshlrev_b64 v[106:107], 1, v[98:99]
	v_readlane_b32 s3, v254, 41
	s_nop 0
	v_cvt_pk_bf16_f32 v102, v150, v151
	s_nop 0
	v_cvt_pk_bf16_f32 v103, v152, v153
	v_pk_add_f32 v[148:149], v[108:109], v[140:141]
	v_pk_add_f32 v[144:145], v[104:105], v[136:137]
	v_lshl_add_u64 v[98:99], s[2:3], 0, v[106:107]
	global_store_dwordx2 v[98:99], v[102:103], off
	v_mul_f32_e32 v98, v151, v151
	v_mul_f32_e32 v99, v153, v153
	v_fmac_f32_e32 v98, v150, v150
	v_fmac_f32_e32 v99, v152, v152
	v_or_b32_e32 v102, 32, v106
	v_mov_b32_e32 v103, v107
	v_add_f32_e32 v112, v98, v99
	global_store_dwordx4 v[186:187], v[146:149], off offset:1024
	s_nop 0
	v_cvt_pk_bf16_f32 v98, v146, v147
	s_nop 0
	v_cvt_pk_bf16_f32 v99, v148, v149
	v_lshl_add_u64 v[102:103], s[2:3], 0, v[102:103]
	global_store_dwordx2 v[102:103], v[98:99], off
	v_mul_f32_e32 v98, v147, v147
	v_mul_f32_e32 v99, v149, v149
	v_fmac_f32_e32 v98, v146, v146
	v_fmac_f32_e32 v99, v148, v148
	v_add_f32_e32 v98, v98, v99
	v_add_f32_e32 v98, v112, v98
	v_mul_f32_e32 v99, v143, v143
	v_mul_f32_e32 v112, v145, v145
	v_fmac_f32_e32 v99, v142, v142
	v_fmac_f32_e32 v112, v144, v144
	v_add_f32_e32 v99, v99, v112
	v_pk_add_f32 v[112:113], v[100:101], v[132:133]
	v_add_f32_e32 v98, v98, v99
	v_mul_f32_e32 v99, v111, v111
	v_mul_f32_e32 v134, v113, v113
	v_fmac_f32_e32 v99, v110, v110
	v_fmac_f32_e32 v134, v112, v112
	v_add_f32_e32 v99, v99, v134
	v_and_b32_e32 v134, 64, v195
	v_add_f32_e32 v99, v98, v99
	v_xor_b32_e32 v98, 16, v195
	v_add_u32_e32 v134, 64, v134
	v_cmp_lt_i32_e32 vcc, v98, v134
	v_or_b32_e32 v130, 0x100, v106
	v_mov_b32_e32 v131, v107
	v_cndmask_b32_e32 v98, v195, v98, vcc
	v_lshlrev_b32_e32 v98, 2, v98
	ds_bpermute_b32 v135, v98, v99
	global_store_dwordx4 v[186:187], v[142:145], off offset:2048
	s_nop 0
	v_cvt_pk_bf16_f32 v102, v142, v143
	s_nop 0
	v_cvt_pk_bf16_f32 v103, v144, v145
	v_lshl_add_u64 v[130:131], s[2:3], 0, v[130:131]
	global_store_dwordx2 v[130:131], v[102:103], off
	global_store_dwordx4 v[186:187], v[110:113], off offset:3072
	s_waitcnt lgkmcnt(0)
	v_add_f32_e32 v102, v99, v135
	v_xor_b32_e32 v99, 32, v195
	v_cmp_lt_i32_e32 vcc, v99, v134
	v_or_b32_e32 v106, 0x120, v106
	v_lshl_add_u64 v[106:107], s[2:3], 0, v[106:107]
	v_cndmask_b32_e32 v99, v195, v99, vcc
	v_lshlrev_b32_e32 v99, 2, v99
	ds_bpermute_b32 v103, v99, v102
	s_nop 0
	v_cvt_pk_bf16_f32 v130, v110, v111
	s_nop 0
	v_cvt_pk_bf16_f32 v131, v112, v113
	global_store_dwordx2 v[106:107], v[130:131], off
	s_and_saveexec_b64 s[2:3], s[6:7]
	s_cbranch_execz .LBB0_2105
	v_lshl_add_u64 v[106:107], v[188:189], 2, s[10:11]
	s_waitcnt lgkmcnt(0)
	v_add_f32_e32 v102, v102, v103
	global_atomic_add_f32 v[106:107], v102, off

; __device__ __forceinline__ unsigned cvt_pk_bf16(float lo, float hi) { unsigned r; asm volatile("s_nop 0\n\tv_cvt_pk_bf16_f32 %0, %1, %2" : "=v"(r) : "v"(lo), "v"(hi)); return r; }
; __device__ __forceinline__ f32x4 sig4(const f32x4 v) { return (f32x4){sigmoidf_(v[0]), sigmoidf_(v[1]), sigmoidf_(v[2]), sigmoidf_(v[3])}; }
;     __device__ __forceinline__ void operator()(const typename AccT<I8>::type (&acc)[2][2][4][2], const Unit& u, int wr, int wc, int fr, int fq) const {
;     ...
;         for (int s = 0; s < 8; ++s) { const int ai = s >> 2, m = s & 3; const int r = row0 + ai * HALF + m * 16; const size_t off = (size_t)r * 4096 + col0;
;                 if (s + 1 < 8) load_row(nxt, (size_t)(row0 + ((s + 1) >> 2) * HALF + ((s + 1) & 3) * 16) * 4096 + col0);
;                 const float rs = rsv[s];
;                 float ss = 0.f, mx = 0.f;
; #pragma unroll
;                 for (int bj = 0; bj < 2; ++bj)
; #pragma unroll
;                     for (int n = 0; n < 2; ++n) { const size_t o = off + bj * HALF + n * 16; const f32x4 b = cur.b[bj][n]; f32x4 v;
;                         if constexpr (I8) v = __builtin_convertvector(acc[ai][bj][m][n], f32x4) * rs * sv[bj][n]; else v = acc[ai][bj][m][n];
;                         if (MODE == 1) { const u32x2 pw = cur.pw[bj][n]; const f32x4 pp = (f32x4){bf_lo(pw.x), bf_hi(pw.x), bf_lo(pw.y), bf_hi(pw.y)}; v = sig4(I8 ? v : v * rs) * pp; }
;                         const f32x4 x = b + v; *(f32x4*)(out + o) = x;
;                         if (MODE == 0 && XB) { u32x2 w; w.x = cvt_pk_bf16(x[0], x[1]); w.y = cvt_pk_bf16(x[2], x[3]); *(u32x2*)(XB + o) = w; ss += (x[0] * x[0] + x[1] * x[1]) + (x[2] * x[2] + x[3] * x[3]);
;                             if (RM) mx = fmaxf(fmaxf(mx, fmaxf(fabsf(x[0]), fabsf(x[1]))), fmaxf(fabsf(x[2]), fabsf(x[3]))); } }
;                 if (MODE == 0 && XB) { ss += __shfl_xor(ss, 16); ss += __shfl_xor(ss, 32); if (fq == 0) unsafeAtomicAdd(SS + r, ss);
;                     if (RM) { mx = fmaxf(mx, __shfl_xor(mx, 16)); mx = fmaxf(mx, __shfl_xor(mx, 32)); if (fq == 0) atomicMax(RM + r, __builtin_bit_cast(unsigned, mx)); } }
.LBB0_2109:
	v_or_b32_e32 v140, 48, v184
	v_ashrrev_i32_e32 v141, 31, v140
	v_readlane_b32 s52, v254, 8
	s_waitcnt lgkmcnt(0)
	v_lshlrev_b64 v[98:99], 14, v[140:141]
	v_readlane_b32 s58, v254, 14
	v_readlane_b32 s59, v254, 15
	s_waitcnt vmcnt(4)
	v_pk_add_f32 v[136:137], v[96:97], v[128:129]
	v_pk_add_f32 v[134:135], v[94:95], v[126:127]
	v_lshl_add_u64 v[98:99], s[58:59], 0, v[98:99]
	s_mov_b64 s[98:99], 0x18000
	v_lshl_add_u64 v[138:139], v[250:251], 0, s[98:99]
	s_mov_b64 s[98:99], 0x18000
	v_lshl_add_u64 v[252:253], v[250:251], 0, s[98:99]
	global_load_dwordx4 v[110:113], v[252:253], off
	global_load_dwordx4 v[106:109], v[252:253], off offset:1024
	global_load_dwordx4 v[102:105], v[252:253], off offset:2048
	global_load_dwordx4 v[98:101], v[252:253], off offset:3072
	s_and_b64 vcc, exec, s[8:9]
	s_waitcnt vmcnt(7)
	v_pk_add_f32 v[130:131], v[90:91], v[122:123]
	s_waitcnt vmcnt(6)
	v_pk_add_f32 v[126:127], v[86:87], v[118:119]
	s_waitcnt vmcnt(5)
	v_pk_add_f32 v[94:95], v[82:83], v[114:115]
	v_readlane_b32 s53, v254, 9
	v_readlane_b32 s54, v254, 10
	v_readlane_b32 s55, v254, 11
	v_readlane_b32 s56, v254, 12
	v_readlane_b32 s57, v254, 13
	global_store_dwordx4 v[154:155], v[134:137], off
	s_cbranch_vccnz .LBB0_2156
	v_lshlrev_b64 v[82:83], 12, v[156:157]
	v_lshl_add_u64 v[82:83], v[82:83], 0, v[182:183]
	v_readlane_b32 s2, v254, 40
	v_lshlrev_b64 v[90:91], 1, v[82:83]
	v_readlane_b32 s3, v254, 41
	s_nop 0
	v_cvt_pk_bf16_f32 v86, v134, v135
	s_nop 0
	v_cvt_pk_bf16_f32 v87, v136, v137
	v_pk_add_f32 v[132:133], v[92:93], v[124:125]
	v_pk_add_f32 v[128:129], v[88:89], v[120:121]
	v_lshl_add_u64 v[82:83], s[2:3], 0, v[90:91]
	global_store_dwordx2 v[82:83], v[86:87], off
	v_mul_f32_e32 v82, v135, v135
	v_mul_f32_e32 v83, v137, v137
	v_fmac_f32_e32 v82, v134, v134
	v_fmac_f32_e32 v83, v136, v136
	v_or_b32_e32 v86, 32, v90
	v_mov_b32_e32 v87, v91
	v_add_f32_e32 v96, v82, v83
	global_store_dwordx4 v[154:155], v[130:133], off offset:1024
	s_nop 0
	v_cvt_pk_bf16_f32 v82, v130, v131
	s_nop 0
	v_cvt_pk_bf16_f32 v83, v132, v133
	v_lshl_add_u64 v[86:87], s[2:3], 0, v[86:87]
	global_store_dwordx2 v[86:87], v[82:83], off
	v_mul_f32_e32 v82, v131, v131
	v_mul_f32_e32 v83, v133, v133
	v_fmac_f32_e32 v82, v130, v130
	v_fmac_f32_e32 v83, v132, v132
	v_add_f32_e32 v82, v82, v83
	v_add_f32_e32 v82, v96, v82
	v_mul_f32_e32 v83, v127, v127
	v_mul_f32_e32 v96, v129, v129
	v_fmac_f32_e32 v83, v126, v126
	v_fmac_f32_e32 v96, v128, v128
	v_add_f32_e32 v83, v83, v96
	v_pk_add_f32 v[96:97], v[84:85], v[116:117]
	v_add_f32_e32 v82, v82, v83
	v_mul_f32_e32 v83, v95, v95
	v_mul_f32_e32 v118, v97, v97
	v_fmac_f32_e32 v83, v94, v94
	v_fmac_f32_e32 v118, v96, v96
	v_add_f32_e32 v83, v83, v118
	v_and_b32_e32 v118, 64, v195
	v_add_f32_e32 v83, v82, v83
	v_xor_b32_e32 v82, 16, v195
	v_add_u32_e32 v118, 64, v118
	v_cmp_lt_i32_e32 vcc, v82, v118
	v_or_b32_e32 v114, 0x100, v90
	v_mov_b32_e32 v115, v91
	v_cndmask_b32_e32 v82, v195, v82, vcc
	v_lshlrev_b32_e32 v82, 2, v82
	ds_bpermute_b32 v119, v82, v83
	global_store_dwordx4 v[154:155], v[126:129], off offset:2048
	s_nop 0
	v_cvt_pk_bf16_f32 v86, v126, v127
	s_nop 0
	v_cvt_pk_bf16_f32 v87, v128, v129
	v_lshl_add_u64 v[114:115], s[2:3], 0, v[114:115]
	global_store_dwordx2 v[114:115], v[86:87], off
	global_store_dwordx4 v[154:155], v[94:97], off offset:3072
	s_waitcnt lgkmcnt(0)
	v_add_f32_e32 v86, v83, v119
	v_xor_b32_e32 v83, 32, v195
	v_cmp_lt_i32_e32 vcc, v83, v118
	v_or_b32_e32 v90, 0x120, v90
	v_lshl_add_u64 v[90:91], s[2:3], 0, v[90:91]
	v_cndmask_b32_e32 v83, v195, v83, vcc
	v_lshlrev_b32_e32 v83, 2, v83
	ds_bpermute_b32 v87, v83, v86
	s_nop 0
	v_cvt_pk_bf16_f32 v114, v94, v95
	s_nop 0
	v_cvt_pk_bf16_f32 v115, v96, v97
	global_store_dwordx2 v[90:91], v[114:115], off
	s_and_saveexec_b64 s[2:3], s[6:7]
	s_cbranch_execz .LBB0_2112
	v_lshl_add_u64 v[90:91], v[156:157], 2, s[10:11]
	s_waitcnt lgkmcnt(0)
	v_add_f32_e32 v86, v86, v87
	global_atomic_add_f32 v[90:91], v86, off

; __device__ __forceinline__ unsigned cvt_pk_bf16(float lo, float hi) { unsigned r; asm volatile("s_nop 0\n\tv_cvt_pk_bf16_f32 %0, %1, %2" : "=v"(r) : "v"(lo), "v"(hi)); return r; }
; __device__ __forceinline__ f32x4 sig4(const f32x4 v) { return (f32x4){sigmoidf_(v[0]), sigmoidf_(v[1]), sigmoidf_(v[2]), sigmoidf_(v[3])}; }
;     __device__ __forceinline__ void operator()(const typename AccT<I8>::type (&acc)[2][2][4][2], const Unit& u, int wr, int wc, int fr, int fq) const {
;     ...
;         for (int s = 0; s < 8; ++s) { const int ai = s >> 2, m = s & 3; const int r = row0 + ai * HALF + m * 16; const size_t off = (size_t)r * 4096 + col0;
;                 if (s + 1 < 8) load_row(nxt, (size_t)(row0 + ((s + 1) >> 2) * HALF + ((s + 1) & 3) * 16) * 4096 + col0);
;                 const float rs = rsv[s];
;                 float ss = 0.f, mx = 0.f;
; #pragma unroll
;                 for (int bj = 0; bj < 2; ++bj)
; #pragma unroll
;                     for (int n = 0; n < 2; ++n) { const size_t o = off + bj * HALF + n * 16; const f32x4 b = cur.b[bj][n]; f32x4 v;
;                         if constexpr (I8) v = __builtin_convertvector(acc[ai][bj][m][n], f32x4) * rs * sv[bj][n]; else v = acc[ai][bj][m][n];
;                         if (MODE == 1) { const u32x2 pw = cur.pw[bj][n]; const f32x4 pp = (f32x4){bf_lo(pw.x), bf_hi(pw.x), bf_lo(pw.y), bf_hi(pw.y)}; v = sig4(I8 ? v : v * rs) * pp; }
;                         const f32x4 x = b + v; *(f32x4*)(out + o) = x;
;                         if (MODE == 0 && XB) { u32x2 w; w.x = cvt_pk_bf16(x[0], x[1]); w.y = cvt_pk_bf16(x[2], x[3]); *(u32x2*)(XB + o) = w; ss += (x[0] * x[0] + x[1] * x[1]) + (x[2] * x[2] + x[3] * x[3]);
;                             if (RM) mx = fmaxf(fmaxf(mx, fmaxf(fabsf(x[0]), fabsf(x[1]))), fmaxf(fabsf(x[2]), fabsf(x[3]))); } }
;                 if (MODE == 0 && XB) { ss += __shfl_xor(ss, 16); ss += __shfl_xor(ss, 32); if (fq == 0) unsafeAtomicAdd(SS + r, ss);
;                     if (RM) { mx = fmaxf(mx, __shfl_xor(mx, 16)); mx = fmaxf(mx, __shfl_xor(mx, 32)); if (fq == 0) atomicMax(RM + r, __builtin_bit_cast(unsigned, mx)); } }
.LBB0_2116:
	v_add_u32_e32 v122, 0x80, v184
	v_ashrrev_i32_e32 v123, 31, v122
	v_readlane_b32 s52, v254, 8
	s_waitcnt lgkmcnt(0)
	v_lshlrev_b64 v[82:83], 14, v[122:123]
	v_readlane_b32 s58, v254, 14
	v_readlane_b32 s59, v254, 15
	s_waitcnt vmcnt(4)
	v_pk_add_f32 v[120:121], v[80:81], v[112:113]
	v_pk_add_f32 v[118:119], v[78:79], v[110:111]
	v_lshl_add_u64 v[82:83], s[58:59], 0, v[82:83]
	s_mov_b64 s[98:99], 0x20000
	v_lshl_add_u64 v[124:125], v[250:251], 0, s[98:99]
	s_mov_b64 s[98:99], 0x20000
	v_lshl_add_u64 v[252:253], v[250:251], 0, s[98:99]
	global_load_dwordx4 v[94:97], v[252:253], off
	global_load_dwordx4 v[90:93], v[252:253], off offset:1024
	global_load_dwordx4 v[86:89], v[252:253], off offset:2048
	global_load_dwordx4 v[82:85], v[252:253], off offset:3072
	s_and_b64 vcc, exec, s[8:9]
	s_waitcnt vmcnt(7)
	v_pk_add_f32 v[114:115], v[74:75], v[106:107]
	s_waitcnt vmcnt(6)
	v_pk_add_f32 v[110:111], v[70:71], v[102:103]
	s_waitcnt vmcnt(5)
	v_pk_add_f32 v[78:79], v[66:67], v[98:99]
	v_readlane_b32 s53, v254, 9
	v_readlane_b32 s54, v254, 10
	v_readlane_b32 s55, v254, 11
	v_readlane_b32 s56, v254, 12
	v_readlane_b32 s57, v254, 13
	global_store_dwordx4 v[138:139], v[118:121], off
	s_cbranch_vccnz .LBB0_2157
	v_lshlrev_b64 v[66:67], 12, v[140:141]
	v_lshl_add_u64 v[66:67], v[66:67], 0, v[182:183]
	v_readlane_b32 s2, v254, 40
	v_lshlrev_b64 v[74:75], 1, v[66:67]
	v_readlane_b32 s3, v254, 41
	s_nop 0
	v_cvt_pk_bf16_f32 v70, v118, v119
	s_nop 0
	v_cvt_pk_bf16_f32 v71, v120, v121
	v_pk_add_f32 v[116:117], v[76:77], v[108:109]
	v_pk_add_f32 v[112:113], v[72:73], v[104:105]
	v_lshl_add_u64 v[66:67], s[2:3], 0, v[74:75]
	global_store_dwordx2 v[66:67], v[70:71], off
	v_mul_f32_e32 v66, v119, v119
	v_mul_f32_e32 v67, v121, v121
	v_fmac_f32_e32 v66, v118, v118
	v_fmac_f32_e32 v67, v120, v120
	v_or_b32_e32 v70, 32, v74
	v_mov_b32_e32 v71, v75
	v_add_f32_e32 v80, v66, v67
	global_store_dwordx4 v[138:139], v[114:117], off offset:1024
	s_nop 0
	v_cvt_pk_bf16_f32 v66, v114, v115
	s_nop 0
	v_cvt_pk_bf16_f32 v67, v116, v117
	v_lshl_add_u64 v[70:71], s[2:3], 0, v[70:71]
	global_store_dwordx2 v[70:71], v[66:67], off
	v_mul_f32_e32 v66, v115, v115
	v_mul_f32_e32 v67, v117, v117
	v_fmac_f32_e32 v66, v114, v114
	v_fmac_f32_e32 v67, v116, v116
	v_add_f32_e32 v66, v66, v67
	v_add_f32_e32 v66, v80, v66
	v_mul_f32_e32 v67, v111, v111
	v_mul_f32_e32 v80, v113, v113
	v_fmac_f32_e32 v67, v110, v110
	v_fmac_f32_e32 v80, v112, v112
	v_add_f32_e32 v67, v67, v80
	v_pk_add_f32 v[80:81], v[68:69], v[100:101]
	v_add_f32_e32 v66, v66, v67
	v_mul_f32_e32 v67, v79, v79
	v_mul_f32_e32 v102, v81, v81
	v_fmac_f32_e32 v67, v78, v78
	v_fmac_f32_e32 v102, v80, v80
	v_add_f32_e32 v67, v67, v102
	v_and_b32_e32 v102, 64, v195
	v_add_f32_e32 v67, v66, v67
	v_xor_b32_e32 v66, 16, v195
	v_add_u32_e32 v102, 64, v102
	v_cmp_lt_i32_e32 vcc, v66, v102
	v_or_b32_e32 v98, 0x100, v74
	v_mov_b32_e32 v99, v75
	v_cndmask_b32_e32 v66, v195, v66, vcc
	v_lshlrev_b32_e32 v66, 2, v66
	ds_bpermute_b32 v103, v66, v67
	global_store_dwordx4 v[138:139], v[110:113], off offset:2048
	s_nop 0
	v_cvt_pk_bf16_f32 v70, v110, v111
	s_nop 0
	v_cvt_pk_bf16_f32 v71, v112, v113
	v_lshl_add_u64 v[98:99], s[2:3], 0, v[98:99]
	global_store_dwordx2 v[98:99], v[70:71], off
	global_store_dwordx4 v[138:139], v[78:81], off offset:3072
	s_waitcnt lgkmcnt(0)
	v_add_f32_e32 v70, v67, v103
	v_xor_b32_e32 v67, 32, v195
	v_cmp_lt_i32_e32 vcc, v67, v102
	v_or_b32_e32 v74, 0x120, v74
	v_lshl_add_u64 v[74:75], s[2:3], 0, v[74:75]
	v_cndmask_b32_e32 v67, v195, v67, vcc
	v_lshlrev_b32_e32 v67, 2, v67
	ds_bpermute_b32 v71, v67, v70
	s_nop 0
	v_cvt_pk_bf16_f32 v98, v78, v79
	s_nop 0
	v_cvt_pk_bf16_f32 v99, v80, v81
	global_store_dwordx2 v[74:75], v[98:99], off
	s_and_saveexec_b64 s[2:3], s[6:7]
	s_cbranch_execz .LBB0_2119
	v_lshl_add_u64 v[74:75], v[140:141], 2, s[10:11]
	s_waitcnt lgkmcnt(0)
	v_add_f32_e32 v70, v70, v71
	global_atomic_add_f32 v[74:75], v70, off

; __device__ __forceinline__ unsigned cvt_pk_bf16(float lo, float hi) { unsigned r; asm volatile("s_nop 0\n\tv_cvt_pk_bf16_f32 %0, %1, %2" : "=v"(r) : "v"(lo), "v"(hi)); return r; }
; __device__ __forceinline__ f32x4 sig4(const f32x4 v) { return (f32x4){sigmoidf_(v[0]), sigmoidf_(v[1]), sigmoidf_(v[2]), sigmoidf_(v[3])}; }
;     __device__ __forceinline__ void operator()(const typename AccT<I8>::type (&acc)[2][2][4][2], const Unit& u, int wr, int wc, int fr, int fq) const {
;     ...
;         for (int s = 0; s < 8; ++s) { const int ai = s >> 2, m = s & 3; const int r = row0 + ai * HALF + m * 16; const size_t off = (size_t)r * 4096 + col0;
;                 if (s + 1 < 8) load_row(nxt, (size_t)(row0 + ((s + 1) >> 2) * HALF + ((s + 1) & 3) * 16) * 4096 + col0);
;                 const float rs = rsv[s];
;                 float ss = 0.f, mx = 0.f;
; #pragma unroll
;                 for (int bj = 0; bj < 2; ++bj)
; #pragma unroll
;                     for (int n = 0; n < 2; ++n) { const size_t o = off + bj * HALF + n * 16; const f32x4 b = cur.b[bj][n]; f32x4 v;
;                         if constexpr (I8) v = __builtin_convertvector(acc[ai][bj][m][n], f32x4) * rs * sv[bj][n]; else v = acc[ai][bj][m][n];
;                         if (MODE == 1) { const u32x2 pw = cur.pw[bj][n]; const f32x4 pp = (f32x4){bf_lo(pw.x), bf_hi(pw.x), bf_lo(pw.y), bf_hi(pw.y)}; v = sig4(I8 ? v : v * rs) * pp; }
;                         const f32x4 x = b + v; *(f32x4*)(out + o) = x;
;                         if (MODE == 0 && XB) { u32x2 w; w.x = cvt_pk_bf16(x[0], x[1]); w.y = cvt_pk_bf16(x[2], x[3]); *(u32x2*)(XB + o) = w; ss += (x[0] * x[0] + x[1] * x[1]) + (x[2] * x[2] + x[3] * x[3]);
;                             if (RM) mx = fmaxf(fmaxf(mx, fmaxf(fabsf(x[0]), fabsf(x[1]))), fmaxf(fabsf(x[2]), fabsf(x[3]))); } }
;                 if (MODE == 0 && XB) { ss += __shfl_xor(ss, 16); ss += __shfl_xor(ss, 32); if (fq == 0) unsafeAtomicAdd(SS + r, ss);
;                     if (RM) { mx = fmaxf(mx, __shfl_xor(mx, 16)); mx = fmaxf(mx, __shfl_xor(mx, 32)); if (fq == 0) atomicMax(RM + r, __builtin_bit_cast(unsigned, mx)); } }
.LBB0_2123:
	v_or_b32_e32 v108, 16, v122
	v_ashrrev_i32_e32 v109, 31, v108
	v_readlane_b32 s52, v254, 8
	s_waitcnt lgkmcnt(0)
	v_lshlrev_b64 v[66:67], 14, v[108:109]
	v_readlane_b32 s58, v254, 14
	v_readlane_b32 s59, v254, 15
	s_waitcnt vmcnt(4)
	v_pk_add_f32 v[104:105], v[64:65], v[96:97]
	v_pk_add_f32 v[102:103], v[62:63], v[94:95]
	v_lshl_add_u64 v[66:67], s[58:59], 0, v[66:67]
	s_mov_b64 s[98:99], 0x28000
	v_lshl_add_u64 v[106:107], v[250:251], 0, s[98:99]
	s_mov_b64 s[98:99], 0x28000
	v_lshl_add_u64 v[252:253], v[250:251], 0, s[98:99]
	global_load_dwordx4 v[78:81], v[252:253], off
	global_load_dwordx4 v[74:77], v[252:253], off offset:1024
	global_load_dwordx4 v[70:73], v[252:253], off offset:2048
	global_load_dwordx4 v[66:69], v[252:253], off offset:3072
	s_and_b64 vcc, exec, s[8:9]
	s_waitcnt vmcnt(7)
	v_pk_add_f32 v[98:99], v[58:59], v[90:91]
	s_waitcnt vmcnt(6)
	v_pk_add_f32 v[94:95], v[54:55], v[86:87]
	s_waitcnt vmcnt(5)
	v_pk_add_f32 v[62:63], v[50:51], v[82:83]
	v_readlane_b32 s53, v254, 9
	v_readlane_b32 s54, v254, 10
	v_readlane_b32 s55, v254, 11
	v_readlane_b32 s56, v254, 12
	v_readlane_b32 s57, v254, 13
	global_store_dwordx4 v[124:125], v[102:105], off
	s_cbranch_vccnz .LBB0_2158
	v_lshlrev_b64 v[50:51], 12, v[122:123]
	v_lshl_add_u64 v[50:51], v[50:51], 0, v[182:183]
	v_readlane_b32 s2, v254, 40
	v_lshlrev_b64 v[58:59], 1, v[50:51]
	v_readlane_b32 s3, v254, 41
	s_nop 0
	v_cvt_pk_bf16_f32 v54, v102, v103
	s_nop 0
	v_cvt_pk_bf16_f32 v55, v104, v105
	v_pk_add_f32 v[100:101], v[60:61], v[92:93]
	v_pk_add_f32 v[96:97], v[56:57], v[88:89]
	v_lshl_add_u64 v[50:51], s[2:3], 0, v[58:59]
	global_store_dwordx2 v[50:51], v[54:55], off
	v_mul_f32_e32 v50, v103, v103
	v_mul_f32_e32 v51, v105, v105
	v_fmac_f32_e32 v50, v102, v102
	v_fmac_f32_e32 v51, v104, v104
	v_or_b32_e32 v54, 32, v58
	v_mov_b32_e32 v55, v59
	v_add_f32_e32 v64, v50, v51
	global_store_dwordx4 v[124:125], v[98:101], off offset:1024
	s_nop 0
	v_cvt_pk_bf16_f32 v50, v98, v99
	s_nop 0
	v_cvt_pk_bf16_f32 v51, v100, v101
	v_lshl_add_u64 v[54:55], s[2:3], 0, v[54:55]
	global_store_dwordx2 v[54:55], v[50:51], off
	v_mul_f32_e32 v50, v99, v99
	v_mul_f32_e32 v51, v101, v101
	v_fmac_f32_e32 v50, v98, v98
	v_fmac_f32_e32 v51, v100, v100
	v_add_f32_e32 v50, v50, v51
	v_add_f32_e32 v50, v64, v50
	v_mul_f32_e32 v51, v95, v95
	v_mul_f32_e32 v64, v97, v97
	v_fmac_f32_e32 v51, v94, v94
	v_fmac_f32_e32 v64, v96, v96
	v_add_f32_e32 v51, v51, v64
	v_pk_add_f32 v[64:65], v[52:53], v[84:85]
	v_add_f32_e32 v50, v50, v51
	v_mul_f32_e32 v51, v63, v63
	v_mul_f32_e32 v86, v65, v65
	v_fmac_f32_e32 v51, v62, v62
	v_fmac_f32_e32 v86, v64, v64
	v_add_f32_e32 v51, v51, v86
	v_and_b32_e32 v86, 64, v195
	v_add_f32_e32 v51, v50, v51
	v_xor_b32_e32 v50, 16, v195
	v_add_u32_e32 v86, 64, v86
	v_cmp_lt_i32_e32 vcc, v50, v86
	v_or_b32_e32 v82, 0x100, v58
	v_mov_b32_e32 v83, v59
	v_cndmask_b32_e32 v50, v195, v50, vcc
	v_lshlrev_b32_e32 v50, 2, v50
	ds_bpermute_b32 v87, v50, v51
	global_store_dwordx4 v[124:125], v[94:97], off offset:2048
	s_nop 0
	v_cvt_pk_bf16_f32 v54, v94, v95
	s_nop 0
	v_cvt_pk_bf16_f32 v55, v96, v97
	v_lshl_add_u64 v[82:83], s[2:3], 0, v[82:83]
	global_store_dwordx2 v[82:83], v[54:55], off
	global_store_dwordx4 v[124:125], v[62:65], off offset:3072
	s_waitcnt lgkmcnt(0)
	v_add_f32_e32 v54, v51, v87
	v_xor_b32_e32 v51, 32, v195
	v_cmp_lt_i32_e32 vcc, v51, v86
	v_or_b32_e32 v58, 0x120, v58
	v_lshl_add_u64 v[58:59], s[2:3], 0, v[58:59]
	v_cndmask_b32_e32 v51, v195, v51, vcc
	v_lshlrev_b32_e32 v51, 2, v51
	ds_bpermute_b32 v55, v51, v54
	s_nop 0
	v_cvt_pk_bf16_f32 v82, v62, v63
	s_nop 0
	v_cvt_pk_bf16_f32 v83, v64, v65
	global_store_dwordx2 v[58:59], v[82:83], off
	s_and_saveexec_b64 s[2:3], s[6:7]
	s_cbranch_execz .LBB0_2126
	v_lshl_add_u64 v[58:59], v[122:123], 2, s[10:11]
	s_waitcnt lgkmcnt(0)
	v_add_f32_e32 v54, v54, v55
	global_atomic_add_f32 v[58:59], v54, off

; __device__ __forceinline__ unsigned cvt_pk_bf16(float lo, float hi) { unsigned r; asm volatile("s_nop 0\n\tv_cvt_pk_bf16_f32 %0, %1, %2" : "=v"(r) : "v"(lo), "v"(hi)); return r; }
; __device__ __forceinline__ f32x4 sig4(const f32x4 v) { return (f32x4){sigmoidf_(v[0]), sigmoidf_(v[1]), sigmoidf_(v[2]), sigmoidf_(v[3])}; }
;     __device__ __forceinline__ void operator()(const typename AccT<I8>::type (&acc)[2][2][4][2], const Unit& u, int wr, int wc, int fr, int fq) const {
;     ...
;         for (int s = 0; s < 8; ++s) { const int ai = s >> 2, m = s & 3; const int r = row0 + ai * HALF + m * 16; const size_t off = (size_t)r * 4096 + col0;
;                 if (s + 1 < 8) load_row(nxt, (size_t)(row0 + ((s + 1) >> 2) * HALF + ((s + 1) & 3) * 16) * 4096 + col0);
;                 const float rs = rsv[s];
;                 float ss = 0.f, mx = 0.f;
; #pragma unroll
;                 for (int bj = 0; bj < 2; ++bj)
; #pragma unroll
;                     for (int n = 0; n < 2; ++n) { const size_t o = off + bj * HALF + n * 16; const f32x4 b = cur.b[bj][n]; f32x4 v;
;                         if constexpr (I8) v = __builtin_convertvector(acc[ai][bj][m][n], f32x4) * rs * sv[bj][n]; else v = acc[ai][bj][m][n];
;                         if (MODE == 1) { const u32x2 pw = cur.pw[bj][n]; const f32x4 pp = (f32x4){bf_lo(pw.x), bf_hi(pw.x), bf_lo(pw.y), bf_hi(pw.y)}; v = sig4(I8 ? v : v * rs) * pp; }
;                         const f32x4 x = b + v; *(f32x4*)(out + o) = x;
;                         if (MODE == 0 && XB) { u32x2 w; w.x = cvt_pk_bf16(x[0], x[1]); w.y = cvt_pk_bf16(x[2], x[3]); *(u32x2*)(XB + o) = w; ss += (x[0] * x[0] + x[1] * x[1]) + (x[2] * x[2] + x[3] * x[3]);
;                             if (RM) mx = fmaxf(fmaxf(mx, fmaxf(fabsf(x[0]), fabsf(x[1]))), fmaxf(fabsf(x[2]), fabsf(x[3]))); } }
;                 if (MODE == 0 && XB) { ss += __shfl_xor(ss, 16); ss += __shfl_xor(ss, 32); if (fq == 0) unsafeAtomicAdd(SS + r, ss);
;                     if (RM) { mx = fmaxf(mx, __shfl_xor(mx, 16)); mx = fmaxf(mx, __shfl_xor(mx, 32)); if (fq == 0) atomicMax(RM + r, __builtin_bit_cast(unsigned, mx)); } }
.LBB0_2130:
	v_or_b32_e32 v92, 32, v122
	v_ashrrev_i32_e32 v93, 31, v92
	v_readlane_b32 s52, v254, 8
	s_waitcnt lgkmcnt(0)
	v_lshlrev_b64 v[50:51], 14, v[92:93]
	v_readlane_b32 s58, v254, 14
	v_readlane_b32 s59, v254, 15
	s_waitcnt vmcnt(4)
	v_pk_add_f32 v[88:89], v[48:49], v[80:81]
	v_pk_add_f32 v[86:87], v[46:47], v[78:79]
	v_lshl_add_u64 v[50:51], s[58:59], 0, v[50:51]
	s_mov_b64 s[98:99], 0x30000
	v_lshl_add_u64 v[90:91], v[250:251], 0, s[98:99]
	s_mov_b64 s[98:99], 0x30000
	v_lshl_add_u64 v[252:253], v[250:251], 0, s[98:99]
	global_load_dwordx4 v[62:65], v[252:253], off
	global_load_dwordx4 v[58:61], v[252:253], off offset:1024
	global_load_dwordx4 v[54:57], v[252:253], off offset:2048
	global_load_dwordx4 v[50:53], v[252:253], off offset:3072
	s_and_b64 vcc, exec, s[8:9]
	s_waitcnt vmcnt(7)
	v_pk_add_f32 v[82:83], v[42:43], v[74:75]
	s_waitcnt vmcnt(6)
	v_pk_add_f32 v[78:79], v[38:39], v[70:71]
	s_waitcnt vmcnt(5)
	v_pk_add_f32 v[46:47], v[34:35], v[66:67]
	v_readlane_b32 s53, v254, 9
	v_readlane_b32 s54, v254, 10
	v_readlane_b32 s55, v254, 11
	v_readlane_b32 s56, v254, 12
	v_readlane_b32 s57, v254, 13
	global_store_dwordx4 v[106:107], v[86:89], off
	s_cbranch_vccnz .LBB0_2159
	v_lshlrev_b64 v[34:35], 12, v[108:109]
	v_lshl_add_u64 v[34:35], v[34:35], 0, v[182:183]
	v_readlane_b32 s2, v254, 40
	v_lshlrev_b64 v[42:43], 1, v[34:35]
	v_readlane_b32 s3, v254, 41
	s_nop 0
	v_cvt_pk_bf16_f32 v38, v86, v87
	s_nop 0
	v_cvt_pk_bf16_f32 v39, v88, v89
	v_pk_add_f32 v[84:85], v[44:45], v[76:77]
	v_pk_add_f32 v[80:81], v[40:41], v[72:73]
	v_lshl_add_u64 v[34:35], s[2:3], 0, v[42:43]
	global_store_dwordx2 v[34:35], v[38:39], off
	v_mul_f32_e32 v34, v87, v87
	v_mul_f32_e32 v35, v89, v89
	v_fmac_f32_e32 v34, v86, v86
	v_fmac_f32_e32 v35, v88, v88
	v_or_b32_e32 v38, 32, v42
	v_mov_b32_e32 v39, v43
	v_add_f32_e32 v48, v34, v35
	global_store_dwordx4 v[106:107], v[82:85], off offset:1024
	s_nop 0
	v_cvt_pk_bf16_f32 v34, v82, v83
	s_nop 0
	v_cvt_pk_bf16_f32 v35, v84, v85
	v_lshl_add_u64 v[38:39], s[2:3], 0, v[38:39]
	global_store_dwordx2 v[38:39], v[34:35], off
	v_mul_f32_e32 v34, v83, v83
	v_mul_f32_e32 v35, v85, v85
	v_fmac_f32_e32 v34, v82, v82
	v_fmac_f32_e32 v35, v84, v84
	v_add_f32_e32 v34, v34, v35
	v_add_f32_e32 v34, v48, v34
	v_mul_f32_e32 v35, v79, v79
	v_mul_f32_e32 v48, v81, v81
	v_fmac_f32_e32 v35, v78, v78
	v_fmac_f32_e32 v48, v80, v80
	v_add_f32_e32 v35, v35, v48
	v_pk_add_f32 v[48:49], v[36:37], v[68:69]
	v_add_f32_e32 v34, v34, v35
	v_mul_f32_e32 v35, v47, v47
	v_mul_f32_e32 v70, v49, v49
	v_fmac_f32_e32 v35, v46, v46
	v_fmac_f32_e32 v70, v48, v48
	v_add_f32_e32 v35, v35, v70
	v_and_b32_e32 v70, 64, v195
	v_add_f32_e32 v35, v34, v35
	v_xor_b32_e32 v34, 16, v195
	v_add_u32_e32 v70, 64, v70
	v_cmp_lt_i32_e32 vcc, v34, v70
	v_or_b32_e32 v66, 0x100, v42
	v_mov_b32_e32 v67, v43
	v_cndmask_b32_e32 v34, v195, v34, vcc
	v_lshlrev_b32_e32 v34, 2, v34
	ds_bpermute_b32 v71, v34, v35
	global_store_dwordx4 v[106:107], v[78:81], off offset:2048
	s_nop 0
	v_cvt_pk_bf16_f32 v38, v78, v79
	s_nop 0
	v_cvt_pk_bf16_f32 v39, v80, v81
	v_lshl_add_u64 v[66:67], s[2:3], 0, v[66:67]
	global_store_dwordx2 v[66:67], v[38:39], off
	global_store_dwordx4 v[106:107], v[46:49], off offset:3072
	s_waitcnt lgkmcnt(0)
	v_add_f32_e32 v38, v35, v71
	v_xor_b32_e32 v35, 32, v195
	v_cmp_lt_i32_e32 vcc, v35, v70
	v_or_b32_e32 v42, 0x120, v42
	v_lshl_add_u64 v[42:43], s[2:3], 0, v[42:43]
	v_cndmask_b32_e32 v35, v195, v35, vcc
	v_lshlrev_b32_e32 v35, 2, v35
	ds_bpermute_b32 v39, v35, v38
	s_nop 0
	v_cvt_pk_bf16_f32 v66, v46, v47
	s_nop 0
	v_cvt_pk_bf16_f32 v67, v48, v49
	global_store_dwordx2 v[42:43], v[66:67], off
	s_and_saveexec_b64 s[2:3], s[6:7]
	s_cbranch_execz .LBB0_2133
	v_lshl_add_u64 v[42:43], v[108:109], 2, s[10:11]
	s_waitcnt lgkmcnt(0)
	v_add_f32_e32 v38, v38, v39
	global_atomic_add_f32 v[42:43], v38, off

; __device__ __forceinline__ unsigned cvt_pk_bf16(float lo, float hi) { unsigned r; asm volatile("s_nop 0\n\tv_cvt_pk_bf16_f32 %0, %1, %2" : "=v"(r) : "v"(lo), "v"(hi)); return r; }
; __device__ __forceinline__ f32x4 sig4(const f32x4 v) { return (f32x4){sigmoidf_(v[0]), sigmoidf_(v[1]), sigmoidf_(v[2]), sigmoidf_(v[3])}; }
;     __device__ __forceinline__ void operator()(const typename AccT<I8>::type (&acc)[2][2][4][2], const Unit& u, int wr, int wc, int fr, int fq) const {
;     ...
;         for (int s = 0; s < 8; ++s) { const int ai = s >> 2, m = s & 3; const int r = row0 + ai * HALF + m * 16; const size_t off = (size_t)r * 4096 + col0;
;                 if (s + 1 < 8) load_row(nxt, (size_t)(row0 + ((s + 1) >> 2) * HALF + ((s + 1) & 3) * 16) * 4096 + col0);
;                 const float rs = rsv[s];
;                 float ss = 0.f, mx = 0.f;
; #pragma unroll
;                 for (int bj = 0; bj < 2; ++bj)
; #pragma unroll
;                     for (int n = 0; n < 2; ++n) { const size_t o = off + bj * HALF + n * 16; const f32x4 b = cur.b[bj][n]; f32x4 v;
;                         if constexpr (I8) v = __builtin_convertvector(acc[ai][bj][m][n], f32x4) * rs * sv[bj][n]; else v = acc[ai][bj][m][n];
;                         if (MODE == 1) { const u32x2 pw = cur.pw[bj][n]; const f32x4 pp = (f32x4){bf_lo(pw.x), bf_hi(pw.x), bf_lo(pw.y), bf_hi(pw.y)}; v = sig4(I8 ? v : v * rs) * pp; }
;                         const f32x4 x = b + v; *(f32x4*)(out + o) = x;
;                         if (MODE == 0 && XB) { u32x2 w; w.x = cvt_pk_bf16(x[0], x[1]); w.y = cvt_pk_bf16(x[2], x[3]); *(u32x2*)(XB + o) = w; ss += (x[0] * x[0] + x[1] * x[1]) + (x[2] * x[2] + x[3] * x[3]);
;                             if (RM) mx = fmaxf(fmaxf(mx, fmaxf(fabsf(x[0]), fabsf(x[1]))), fmaxf(fabsf(x[2]), fabsf(x[3]))); } }
;                 if (MODE == 0 && XB) { ss += __shfl_xor(ss, 16); ss += __shfl_xor(ss, 32); if (fq == 0) unsafeAtomicAdd(SS + r, ss);
;                     if (RM) { mx = fmaxf(mx, __shfl_xor(mx, 16)); mx = fmaxf(mx, __shfl_xor(mx, 32)); if (fq == 0) atomicMax(RM + r, __builtin_bit_cast(unsigned, mx)); } }
.LBB0_2137:
	v_or_b32_e32 v76, 48, v122
	v_ashrrev_i32_e32 v77, 31, v76
	v_readlane_b32 s52, v254, 8
	s_waitcnt lgkmcnt(0)
	v_lshlrev_b64 v[34:35], 14, v[76:77]
	v_readlane_b32 s58, v254, 14
	v_readlane_b32 s59, v254, 15
	s_waitcnt vmcnt(4)
	v_pk_add_f32 v[72:73], v[32:33], v[64:65]
	v_pk_add_f32 v[70:71], v[30:31], v[62:63]
	v_lshl_add_u64 v[34:35], s[58:59], 0, v[34:35]
	s_mov_b64 s[98:99], 0x38000
	v_lshl_add_u64 v[74:75], v[250:251], 0, s[98:99]
	s_mov_b64 s[98:99], 0x38000
	v_lshl_add_u64 v[252:253], v[250:251], 0, s[98:99]
	global_load_dwordx4 v[46:49], v[252:253], off
	global_load_dwordx4 v[42:45], v[252:253], off offset:1024
	global_load_dwordx4 v[38:41], v[252:253], off offset:2048
	global_load_dwordx4 v[34:37], v[252:253], off offset:3072
	s_and_b64 vcc, exec, s[8:9]
	s_waitcnt vmcnt(7)
	v_pk_add_f32 v[66:67], v[26:27], v[58:59]
	s_waitcnt vmcnt(6)
	v_pk_add_f32 v[62:63], v[18:19], v[54:55]
	s_waitcnt vmcnt(5)
	v_pk_add_f32 v[30:31], v[14:15], v[50:51]
	v_readlane_b32 s53, v254, 9
	v_readlane_b32 s54, v254, 10
	v_readlane_b32 s55, v254, 11
	v_readlane_b32 s56, v254, 12
	v_readlane_b32 s57, v254, 13
	global_store_dwordx4 v[90:91], v[70:73], off
	s_cbranch_vccnz .LBB0_2160
	v_lshlrev_b64 v[14:15], 12, v[92:93]
	v_lshl_add_u64 v[14:15], v[14:15], 0, v[182:183]
	v_readlane_b32 s2, v254, 40
	v_lshlrev_b64 v[26:27], 1, v[14:15]
	v_readlane_b32 s3, v254, 41
	s_nop 0
	v_cvt_pk_bf16_f32 v18, v70, v71
	s_nop 0
	v_cvt_pk_bf16_f32 v19, v72, v73
	v_pk_add_f32 v[68:69], v[28:29], v[60:61]
	v_pk_add_f32 v[64:65], v[20:21], v[56:57]
	v_lshl_add_u64 v[14:15], s[2:3], 0, v[26:27]
	global_store_dwordx2 v[14:15], v[18:19], off
	v_mul_f32_e32 v14, v71, v71
	v_mul_f32_e32 v15, v73, v73
	v_fmac_f32_e32 v14, v70, v70
	v_fmac_f32_e32 v15, v72, v72
	v_or_b32_e32 v18, 32, v26
	v_mov_b32_e32 v19, v27
	v_add_f32_e32 v32, v14, v15
	global_store_dwordx4 v[90:91], v[66:69], off offset:1024
	s_nop 0
	v_cvt_pk_bf16_f32 v14, v66, v67
	s_nop 0
	v_cvt_pk_bf16_f32 v15, v68, v69
	v_lshl_add_u64 v[18:19], s[2:3], 0, v[18:19]
	global_store_dwordx2 v[18:19], v[14:15], off
	v_mul_f32_e32 v14, v67, v67
	v_mul_f32_e32 v15, v69, v69
	v_fmac_f32_e32 v14, v66, v66
	v_fmac_f32_e32 v15, v68, v68
	v_add_f32_e32 v14, v14, v15
	v_add_f32_e32 v14, v32, v14
	v_mul_f32_e32 v15, v63, v63
	v_mul_f32_e32 v32, v65, v65
	v_fmac_f32_e32 v15, v62, v62
	v_fmac_f32_e32 v32, v64, v64
	v_add_f32_e32 v15, v15, v32
	v_pk_add_f32 v[32:33], v[16:17], v[52:53]
	v_add_f32_e32 v14, v14, v15
	v_mul_f32_e32 v15, v31, v31
	v_mul_f32_e32 v54, v33, v33
	v_fmac_f32_e32 v15, v30, v30
	v_fmac_f32_e32 v54, v32, v32
	v_add_f32_e32 v15, v15, v54
	v_and_b32_e32 v54, 64, v195
	v_add_f32_e32 v15, v14, v15
	v_xor_b32_e32 v14, 16, v195
	v_add_u32_e32 v54, 64, v54
	v_cmp_lt_i32_e32 vcc, v14, v54
	v_or_b32_e32 v50, 0x100, v26
	v_mov_b32_e32 v51, v27
	v_cndmask_b32_e32 v14, v195, v14, vcc
	v_lshlrev_b32_e32 v14, 2, v14
	ds_bpermute_b32 v55, v14, v15
	global_store_dwordx4 v[90:91], v[62:65], off offset:2048
	s_nop 0
	v_cvt_pk_bf16_f32 v18, v62, v63
	s_nop 0
	v_cvt_pk_bf16_f32 v19, v64, v65
	v_lshl_add_u64 v[50:51], s[2:3], 0, v[50:51]
	global_store_dwordx2 v[50:51], v[18:19], off
	global_store_dwordx4 v[90:91], v[30:33], off offset:3072
	s_waitcnt lgkmcnt(0)
	v_add_f32_e32 v18, v15, v55
	v_xor_b32_e32 v15, 32, v195
	v_cmp_lt_i32_e32 vcc, v15, v54
	v_or_b32_e32 v26, 0x120, v26
	v_lshl_add_u64 v[26:27], s[2:3], 0, v[26:27]
	v_cndmask_b32_e32 v15, v195, v15, vcc
	v_lshlrev_b32_e32 v15, 2, v15
	ds_bpermute_b32 v19, v15, v18
	s_nop 0
	v_cvt_pk_bf16_f32 v50, v30, v31
	s_nop 0
	v_cvt_pk_bf16_f32 v51, v32, v33
	global_store_dwordx2 v[26:27], v[50:51], off
	s_and_saveexec_b64 s[2:3], s[6:7]
	s_cbranch_execz .LBB0_2140
	v_lshl_add_u64 v[26:27], v[92:93], 2, s[10:11]
	s_waitcnt lgkmcnt(0)
	v_add_f32_e32 v18, v18, v19
	global_atomic_add_f32 v[26:27], v18, off

; __device__ __forceinline__ u32x4 pack8(const f32x4 v0, const f32x4 v1) { u32x4 w; w.x = cvt_pk_bf16(v0[0], v0[1]); w.y = cvt_pk_bf16(v0[2], v0[3]); w.z = cvt_pk_bf16(v1[0], v1[1]); w.w = cvt_pk_bf16(v1[2], v1[3]); return w; }
; __device__ __forceinline__ void unpack8(const u32x4 w, f32x4& v0, f32x4& v1) { v0 = (f32x4){bf_lo(w.x), bf_hi(w.x), bf_lo(w.y), bf_hi(w.y)}; v1 = (f32x4){bf_lo(w.z), bf_hi(w.z), bf_lo(w.w), bf_hi(w.w)}; }
;     __device__ __forceinline__ void operator()(AccRef acc, const Unit& u, int wr, int wc, int fr, int fq) const {
;         const int row0 = u.pm * BM + wr * 64 + fr, col0 = u.pn * BM + wc * 32 + 8 * fq;
;         RowIn cur, nxt;
;         if (MODE >= 2) load_row(cur, row0, col0);
; #pragma unroll
;         for (int s = 0; s < 8; ++s) { const int ai = s >> 2, m = s & 3; const int r = row0 + ai * HALF + m * 16; bf16_t* rowp = O + (size_t)r * ldc + col0;
;                 if (MODE >= 2 && s + 1 < 8) load_row(nxt, row0 + ((s + 1) >> 2) * HALF + ((s + 1) & 3) * 16, col0);
;                 float rs = 1.f; if (MODE == 1) rs = __builtin_amdgcn_rsqf(rstd[r] * (1.0f / 4096.0f) + 1e-6f);
;                 float mx = 0.f;
; #pragma unroll
;                 for (int bj = 0; bj < 2; ++bj) { f32x4 v0 = acc[ai][bj][m][0], v1 = acc[ai][bj][m][1];
;                     if (MODE == 1) { v0 = v0 * rs; v1 = v1 * rs;
; #pragma unroll
;                         for (int j = 0; j < 4; ++j) { const float a = v0[j] > 0.f ? v0[j] : 0.f, b = v1[j] > 0.f ? v1[j] : 0.f; v0[j] = a * a; v1[j] = b * b; } }
;                     if (MODE == 2) { f32x4 g0, g1; unpack8(cur.g[bj], g0, g1); v0 = v0 * g0; v1 = v1 * g1; }
;                     if (MODE == 3) { f32x4 g0, g1, a0, a1; unpack8(cur.g[bj], g0, g1); unpack8(cur.a[bj], a0, a1);
;                         v0 = a0 + v0 * g0; v1 = a1 + v1 * g1;
; #pragma unroll
;                         for (int j = 0; j < 4; ++j) mx = fmaxf(mx, fmaxf(fabsf(v0[j]), fabsf(v1[j]))); }
;                     *(u32x4*)(rowp + bj * HALF) = pack8(v0, v1); }
.LBB0_2246:
	v_mov_b32_e32 v138, v0
	s_nop 0
	v_cvt_pk_bf16_f32 v122, v122, v123
	s_nop 0
	v_cvt_pk_bf16_f32 v123, v124, v125
	s_nop 0
	v_cvt_pk_bf16_f32 v124, v114, v115
	s_nop 0
	v_cvt_pk_bf16_f32 v125, v116, v117
	s_nop 0
	v_lshrrev_b32_e32 v139, 6, v138
	v_and_b32_e32 v138, 63, v138
	v_lshlrev_b32_e32 v138, 4, v138
	v_lshl_add_u32 v138, v139, 11, v138
	s_lshl_b32 s98, s26, 4
	s_add_i32 s98, s98, s51
	s_lshl_b32 s98, s98, 17
	v_add_u32_e32 v138, s98, v138
	v_mov_b32_e32 v139, 0
	v_lshl_add_u64 v[138:139], s[2:3], 0, v[138:139]
	global_store_dwordx4 v[138:139], v[122:125], off
	s_nop 0
	v_cvt_pk_bf16_f32 v114, v126, v127
	s_nop 0
	v_cvt_pk_bf16_f32 v115, v128, v129
	s_nop 0
	v_cvt_pk_bf16_f32 v116, v118, v119
	s_nop 0
	v_cvt_pk_bf16_f32 v117, v120, v121
	global_store_dwordx4 v[138:139], v[114:117], off offset:1024
	s_nop 0
	v_cvt_pk_bf16_f32 v106, v106, v107
	s_nop 0
	v_cvt_pk_bf16_f32 v107, v108, v109
	s_nop 0
	v_cvt_pk_bf16_f32 v108, v98, v99
	s_nop 0
	v_cvt_pk_bf16_f32 v109, v100, v101
	s_nop 1
	s_mov_b64 s[98:99], 0x4000
	v_lshl_add_u64 v[114:115], v[138:139], 0, s[98:99]
	global_store_dwordx4 v[114:115], v[106:109], off
	s_nop 0
	v_cvt_pk_bf16_f32 v98, v110, v111
	s_nop 0
	v_cvt_pk_bf16_f32 v99, v112, v113
	s_nop 0
	v_cvt_pk_bf16_f32 v100, v102, v103
	s_nop 0
	v_cvt_pk_bf16_f32 v101, v104, v105
	global_store_dwordx4 v[114:115], v[98:101], off offset:1024
	s_nop 0
	v_cvt_pk_bf16_f32 v90, v90, v91
	s_nop 0
	v_cvt_pk_bf16_f32 v91, v92, v93
	s_nop 0
	v_cvt_pk_bf16_f32 v92, v82, v83
	s_nop 0
	v_cvt_pk_bf16_f32 v93, v84, v85
	s_nop 1
	s_mov_b64 s[98:99], 0x8000
	v_lshl_add_u64 v[98:99], v[138:139], 0, s[98:99]
	global_store_dwordx4 v[98:99], v[90:93], off
	s_nop 0
	v_cvt_pk_bf16_f32 v82, v94, v95
	s_nop 0
	v_cvt_pk_bf16_f32 v83, v96, v97
	s_nop 0
	v_cvt_pk_bf16_f32 v84, v86, v87
	s_nop 0
	v_cvt_pk_bf16_f32 v85, v88, v89
	global_store_dwordx4 v[98:99], v[82:85], off offset:1024
	s_nop 0
	v_cvt_pk_bf16_f32 v58, v58, v59
	s_nop 0
	v_cvt_pk_bf16_f32 v59, v60, v61
	s_nop 0
	v_cvt_pk_bf16_f32 v60, v50, v51
	s_nop 0
	v_cvt_pk_bf16_f32 v61, v52, v53
	s_nop 1
	s_mov_b64 s[98:99], 0xc000
	v_lshl_add_u64 v[82:83], v[138:139], 0, s[98:99]
	global_store_dwordx4 v[82:83], v[58:61], off
	s_nop 0
	v_cvt_pk_bf16_f32 v50, v62, v63
	s_nop 0
	v_cvt_pk_bf16_f32 v51, v64, v65
	s_nop 0
	v_cvt_pk_bf16_f32 v52, v54, v55
	s_nop 0
	v_cvt_pk_bf16_f32 v53, v56, v57
	s_mov_b64 s[98:99], 0x10000
	global_store_dwordx4 v[82:83], v[50:53], off offset:1024
	s_nop 0
	v_lshl_add_u64 v[56:57], v[138:139], 0, s[98:99]
	s_nop 0
	v_cvt_pk_bf16_f32 v50, v78, v79
	v_lshl_add_u64 v[54:55], v[138:139], 0, s[98:99]
	s_nop 0
	v_cvt_pk_bf16_f32 v51, v80, v81
	s_nop 0
	v_cvt_pk_bf16_f32 v52, v70, v71
	s_nop 0
	v_cvt_pk_bf16_f32 v53, v72, v73
	global_store_dwordx4 v[56:57], v[50:53], off
	s_andn2_b64 vcc, exec, s[4:5]
	s_mov_b64 s[4:5], -1
	s_nop 0
	v_cvt_pk_bf16_f32 v50, v74, v75
	s_nop 0
	v_cvt_pk_bf16_f32 v51, v76, v77
	s_nop 0
	v_cvt_pk_bf16_f32 v52, v66, v67
	s_nop 0
	v_cvt_pk_bf16_f32 v53, v68, v69
	global_store_dwordx4 v[54:55], v[50:53], off offset:1024
	s_nop 0
	v_cvt_pk_bf16_f32 v42, v42, v43
	s_nop 0
	v_cvt_pk_bf16_f32 v43, v44, v45
	s_nop 0
	v_cvt_pk_bf16_f32 v44, v34, v35
	s_nop 0
	v_cvt_pk_bf16_f32 v45, v36, v37
	s_nop 1
	s_mov_b64 s[98:99], 0x14000
	v_lshl_add_u64 v[50:51], v[138:139], 0, s[98:99]
	global_store_dwordx4 v[50:51], v[42:45], off
	s_nop 0
	v_cvt_pk_bf16_f32 v34, v46, v47
	s_nop 0
	v_cvt_pk_bf16_f32 v35, v48, v49
	s_nop 0
	v_cvt_pk_bf16_f32 v36, v38, v39
	s_nop 0
	v_cvt_pk_bf16_f32 v37, v40, v41
	global_store_dwordx4 v[50:51], v[34:37], off offset:1024
	s_nop 0
	v_cvt_pk_bf16_f32 v26, v26, v27
	s_nop 0
	v_cvt_pk_bf16_f32 v27, v28, v29
	s_nop 0
	v_cvt_pk_bf16_f32 v28, v18, v19
	s_nop 0
	v_cvt_pk_bf16_f32 v29, v20, v21
	s_nop 1
	s_mov_b64 s[98:99], 0x18000
	v_lshl_add_u64 v[34:35], v[138:139], 0, s[98:99]
	global_store_dwordx4 v[34:35], v[26:29], off
	s_nop 0
	v_cvt_pk_bf16_f32 v18, v30, v31
	s_nop 0
	v_cvt_pk_bf16_f32 v19, v32, v33
	s_nop 0
	v_cvt_pk_bf16_f32 v20, v22, v23
	s_nop 0
	v_cvt_pk_bf16_f32 v21, v24, v25
	global_store_dwordx4 v[34:35], v[18:21], off offset:1024
	s_nop 0
	v_cvt_pk_bf16_f32 v10, v10, v11
	s_nop 0
	v_cvt_pk_bf16_f32 v11, v12, v13
	s_nop 0
	v_cvt_pk_bf16_f32 v12, v2, v3
	s_nop 0
	v_cvt_pk_bf16_f32 v13, v4, v5
	s_nop 1
	s_mov_b64 s[98:99], 0x1c000
	v_lshl_add_u64 v[18:19], v[138:139], 0, s[98:99]
	global_store_dwordx4 v[18:19], v[10:13], off
	s_nop 0
	v_cvt_pk_bf16_f32 v2, v14, v15
	s_nop 0
	v_cvt_pk_bf16_f32 v3, v16, v17
	s_nop 0
	v_cvt_pk_bf16_f32 v4, v6, v7
	s_nop 0
	v_cvt_pk_bf16_f32 v5, v8, v9
	global_store_dwordx4 v[18:19], v[2:5], off offset:1024
	s_cbranch_vccnz .LBB0_2237
	s_andn2_b64 vcc, exec, s[0:1]
	s_cbranch_vccnz .LBB0_2236
	s_barrier
	s_branch .LBB0_2236

;     __device__ __forceinline__ void operator()(const typename AccT<I8>::type (&acc)[2][2][4][2], const Unit& u, int wr, int wc, int fr, int fq) const {
;         const int row0 = u.pm * BM + wr * 64 + fr, col0 = u.pn * BM + wc * 32 + 4 * fq;
;         f32x4 sv[2][2];
;         if (I8) {
; #pragma unroll
;             for (int bj = 0; bj < 2; ++bj)
; #pragma unroll
;                 for (int n = 0; n < 2; ++n) sv[bj][n] = *(const f32x4*)(swc + col0 + bj * HALF + n * 16);
;         }
;         float rsv[8];
; #pragma unroll
;         for (int s = 0; s < 8; ++s) { const int r = row0 + (s >> 2) * HALF + (s & 3) * 16; float rs = 1.f; if (MODE == 1) rs = __builtin_amdgcn_rsqf(rstd[r] * (1.0f / 4096.0f) + 1e-6f); if (I8) rs *= sxr[r]; rsv[s] = rs; }
;         RowIn cur, nxt;
;         load_row(cur, (size_t)row0 * 4096 + col0);
; #pragma unroll
;         for (int s = 0; s < 8; ++s) { const int ai = s >> 2, m = s & 3; const int r = row0 + ai * HALF + m * 16; const size_t off = (size_t)r * 4096 + col0;
;                 if (s + 1 < 8) load_row(nxt, (size_t)(row0 + ((s + 1) >> 2) * HALF + ((s + 1) & 3) * 16) * 4096 + col0);
.LBB0_2325:
	s_lshl_b32 s49, s2, 4
	s_add_i32 s49, s49, s48
	s_lshl_b32 s50, s49, 17
	s_add_u32 s50, s8, s50
	s_addc_u32 s51, s9, 0
	s_sub_i32 s53, s49, 888
	s_cmp_lt_u32 s49, 888
	s_cselect_b32 s52, s49, s53
	s_mov_b32 s53, 0x4200000
	s_cselect_b32 s53, 0x3f600000, s53
	s_lshl_b32 s52, s52, 18
	s_add_u32 s52, s52, s53
	s_add_u32 s52, s96, s52
	s_addc_u32 s53, s97, 0
	v_readlane_b32 s54, v254, 14
	v_readlane_b32 s55, v254, 15
	v_lshrrev_b32_e32 v194, 2, v0
	v_and_b32_e32 v194, 64, v194
	v_and_b32_e32 v195, 15, v0
	v_lshl_add_u32 v194, s2, 8, v194
	v_add_u32_e32 v194, v194, v195
	s_lshl_b32 s2, s48, 8
	v_lshrrev_b32_e32 v195, 1, v0
	v_and_b32_e32 v195, 0x60, v195
	v_lshrrev_b32_e32 v255, 2, v0
	v_and_b32_e32 v255, 12, v255
	v_or3_b32 v195, v195, s2, v255
	v_lshlrev_b32_e32 v190, 14, v194
	v_lshl_add_u32 v190, v195, 2, v190
	v_and_b32_e32 v191, 63, v0
	v_lshlrev_b32_e32 v191, 4, v191
	v_lshrrev_b32_e32 v255, 6, v0
	v_lshl_add_u32 v191, v255, 11, v191
	v_lshlrev_b32_e32 v194, 2, v194
	v_lshlrev_b32_e32 v195, 2, v195
	global_load_dword v242, v194, s[6:7] offset:0
	global_load_dword v243, v194, s[6:7] offset:64
	global_load_dword v244, v194, s[6:7] offset:128
	global_load_dword v245, v194, s[6:7] offset:192
	global_load_dword v246, v194, s[6:7] offset:512
	global_load_dword v247, v194, s[6:7] offset:576
	global_load_dword v248, v194, s[6:7] offset:640
	global_load_dword v249, v194, s[6:7] offset:704
	global_load_dword v250, v194, s[10:11] offset:0
	global_load_dword v251, v194, s[10:11] offset:64
	global_load_dword v252, v194, s[10:11] offset:128
	global_load_dword v253, v194, s[10:11] offset:192
	global_load_dword v182, v194, s[10:11] offset:512
	global_load_dword v188, v194, s[10:11] offset:576
	global_load_dword v192, v194, s[10:11] offset:640
	global_load_dword v196, v194, s[10:11] offset:704
	global_load_dwordx4 v[58:61], v195, s[12:13] offset:0
	global_load_dwordx4 v[66:69], v195, s[12:13] offset:64
	global_load_dwordx4 v[74:77], v195, s[12:13] offset:512
	global_load_dwordx4 v[78:81], v195, s[12:13] offset:576
	v_and_b32_e32 v195, 63, v0
	v_lshlrev_b32_e32 v195, 4, v195
	v_lshlrev_b32_e32 v194, 1, v191
	v_sub_u32_e32 v194, v194, v195
	global_load_dwordx4 v[146:149], v194, s[52:53] offset:0
	global_load_dwordx4 v[150:153], v194, s[52:53] offset:1024
	global_load_dwordx4 v[154:157], v194, s[52:53] offset:2048
	global_load_dwordx4 v[158:161], v194, s[52:53] offset:3072
	global_load_dwordx4 v[162:165], v191, s[50:51] offset:0
	global_load_dwordx4 v[178:181], v191, s[50:51] offset:1024
	v_and_b32_e32 v195, 63, v0
	v_lshlrev_b32_e32 v195, 4, v195
	v_lshlrev_b32_e32 v194, 1, v191
	v_sub_u32_e32 v194, v194, v195
	v_add_u32_e32 v194, 0x8000, v194
	v_add_u32_e32 v195, 0x4000, v191
	global_load_dwordx4 v[198:201], v194, s[52:53] offset:0
	global_load_dwordx4 v[202:205], v194, s[52:53] offset:1024
	global_load_dwordx4 v[206:209], v194, s[52:53] offset:2048
	global_load_dwordx4 v[210:213], v194, s[52:53] offset:3072
	global_load_dwordx4 v[184:187], v195, s[50:51] offset:0
	global_load_dwordx4 v[214:217], v195, s[50:51] offset:1024
	v_and_b32_e32 v195, 63, v0
	v_lshlrev_b32_e32 v195, 4, v195
	v_lshlrev_b32_e32 v194, 1, v191
	v_sub_u32_e32 v194, v194, v195
	v_add_u32_e32 v194, 0x10000, v194
	v_add_u32_e32 v195, 0x8000, v191
	global_load_dwordx4 v[218:221], v194, s[52:53] offset:0
	global_load_dwordx4 v[222:225], v194, s[52:53] offset:1024
	global_load_dwordx4 v[226:229], v194, s[52:53] offset:2048
	global_load_dwordx4 v[230:233], v194, s[52:53] offset:3072
	global_load_dwordx4 v[234:237], v195, s[50:51] offset:0
	global_load_dwordx4 v[238:241], v195, s[50:51] offset:1024
	v_mov_b32_e32 v255, 0xbfb8aa3b
	v_cvt_f32_i32_e32 v142, v142
	v_cvt_f32_i32_e32 v143, v143
	v_cvt_f32_i32_e32 v144, v144
	v_cvt_f32_i32_e32 v145, v145
	v_cvt_f32_i32_e32 v138, v138
	v_cvt_f32_i32_e32 v139, v139
	v_cvt_f32_i32_e32 v140, v140
	v_cvt_f32_i32_e32 v141, v141
	v_cvt_f32_i32_e32 v134, v134
	v_cvt_f32_i32_e32 v135, v135
	v_cvt_f32_i32_e32 v136, v136
	v_cvt_f32_i32_e32 v137, v137
	v_cvt_f32_i32_e32 v130, v130
	v_cvt_f32_i32_e32 v131, v131
	v_cvt_f32_i32_e32 v132, v132
	v_cvt_f32_i32_e32 v133, v133
	v_cvt_f32_i32_e32 v126, v126
	v_cvt_f32_i32_e32 v127, v127
	v_cvt_f32_i32_e32 v128, v128
	v_cvt_f32_i32_e32 v129, v129
	v_cvt_f32_i32_e32 v122, v122
	v_cvt_f32_i32_e32 v123, v123
	v_cvt_f32_i32_e32 v124, v124
	v_cvt_f32_i32_e32 v125, v125
	v_cvt_f32_i32_e32 v118, v118
	v_cvt_f32_i32_e32 v119, v119
	v_cvt_f32_i32_e32 v120, v120
	v_cvt_f32_i32_e32 v121, v121
	v_cvt_f32_i32_e32 v114, v114
	v_cvt_f32_i32_e32 v115, v115
	v_cvt_f32_i32_e32 v116, v116
	v_cvt_f32_i32_e32 v117, v117
	v_cvt_f32_i32_e32 v110, v110
	v_cvt_f32_i32_e32 v111, v111
	v_cvt_f32_i32_e32 v112, v112
	v_cvt_f32_i32_e32 v113, v113
	v_cvt_f32_i32_e32 v106, v106
	v_cvt_f32_i32_e32 v107, v107
	v_cvt_f32_i32_e32 v108, v108
	v_cvt_f32_i32_e32 v109, v109
	v_cvt_f32_i32_e32 v102, v102
	v_cvt_f32_i32_e32 v103, v103
	v_cvt_f32_i32_e32 v104, v104
	v_cvt_f32_i32_e32 v105, v105
	v_cvt_f32_i32_e32 v98, v98
	v_cvt_f32_i32_e32 v99, v99
	v_cvt_f32_i32_e32 v100, v100
	v_cvt_f32_i32_e32 v101, v101
	v_cvt_f32_i32_e32 v94, v94
	v_cvt_f32_i32_e32 v95, v95
	v_cvt_f32_i32_e32 v96, v96
	v_cvt_f32_i32_e32 v97, v97
	v_cvt_f32_i32_e32 v90, v90
	v_cvt_f32_i32_e32 v91, v91
	v_cvt_f32_i32_e32 v92, v92
	v_cvt_f32_i32_e32 v93, v93
	v_cvt_f32_i32_e32 v86, v86
	v_cvt_f32_i32_e32 v87, v87
	v_cvt_f32_i32_e32 v88, v88
	v_cvt_f32_i32_e32 v89, v89
	v_cvt_f32_i32_e32 v82, v82
	v_cvt_f32_i32_e32 v83, v83
	v_cvt_f32_i32_e32 v84, v84
	v_cvt_f32_i32_e32 v85, v85
	v_cvt_f32_i32_e32 v70, v70
	v_cvt_f32_i32_e32 v71, v71
	v_cvt_f32_i32_e32 v72, v72
	v_cvt_f32_i32_e32 v73, v73
; __device__ __forceinline__ f32x4 sig4(const f32x4 v) { return (f32x4){sigmoidf_(v[0]), sigmoidf_(v[1]), sigmoidf_(v[2]), sigmoidf_(v[3])}; }
;     __device__ __forceinline__ void operator()(const typename AccT<I8>::type (&acc)[2][2][4][2], const Unit& u, int wr, int wc, int fr, int fq) const {
;     ...
;         for (int s = 0; s < 8; ++s) { const int r = row0 + (s >> 2) * HALF + (s & 3) * 16; float rs = 1.f; if (MODE == 1) rs = __builtin_amdgcn_rsqf(rstd[r] * (1.0f / 4096.0f) + 1e-6f); if (I8) rs *= sxr[r]; rsv[s] = rs; }
;     ...
;                 const float rs = rsv[s];
;                 float ss = 0.f, mx = 0.f;
; #pragma unroll
;                 for (int bj = 0; bj < 2; ++bj)
; #pragma unroll
;                     for (int n = 0; n < 2; ++n) { const size_t o = off + bj * HALF + n * 16; const f32x4 b = cur.b[bj][n]; f32x4 v;
;                         if constexpr (I8) v = __builtin_convertvector(acc[ai][bj][m][n], f32x4) * rs * sv[bj][n]; else v = acc[ai][bj][m][n];
;                         if (MODE == 1) { const u32x2 pw = cur.pw[bj][n]; const f32x4 pp = (f32x4){bf_lo(pw.x), bf_hi(pw.x), bf_lo(pw.y), bf_hi(pw.y)}; v = sig4(I8 ? v : v * rs) * pp; }
;                         const f32x4 x = b + v; *(f32x4*)(out + o) = x;
	v_cvt_f32_i32_e32 v62, v62
	v_cvt_f32_i32_e32 v63, v63
	v_cvt_f32_i32_e32 v64, v64
	v_cvt_f32_i32_e32 v65, v65
	v_cvt_f32_i32_e32 v54, v54
	v_cvt_f32_i32_e32 v55, v55
	v_cvt_f32_i32_e32 v56, v56
	v_cvt_f32_i32_e32 v57, v57
	v_cvt_f32_i32_e32 v50, v50
	v_cvt_f32_i32_e32 v51, v51
	v_cvt_f32_i32_e32 v52, v52
	v_cvt_f32_i32_e32 v53, v53
	v_cvt_f32_i32_e32 v46, v46
	v_cvt_f32_i32_e32 v47, v47
	v_cvt_f32_i32_e32 v48, v48
	v_cvt_f32_i32_e32 v49, v49
	v_cvt_f32_i32_e32 v42, v42
	v_cvt_f32_i32_e32 v43, v43
	v_cvt_f32_i32_e32 v44, v44
	v_cvt_f32_i32_e32 v45, v45
	v_cvt_f32_i32_e32 v38, v38
	v_cvt_f32_i32_e32 v39, v39
	v_cvt_f32_i32_e32 v40, v40
	v_cvt_f32_i32_e32 v41, v41
	v_cvt_f32_i32_e32 v34, v34
	v_cvt_f32_i32_e32 v35, v35
	v_cvt_f32_i32_e32 v36, v36
	v_cvt_f32_i32_e32 v37, v37
	v_cvt_f32_i32_e32 v30, v30
	v_cvt_f32_i32_e32 v31, v31
	v_cvt_f32_i32_e32 v32, v32
	v_cvt_f32_i32_e32 v33, v33
	v_cvt_f32_i32_e32 v26, v26
	v_cvt_f32_i32_e32 v27, v27
	v_cvt_f32_i32_e32 v28, v28
	v_cvt_f32_i32_e32 v29, v29
	v_cvt_f32_i32_e32 v22, v22
	v_cvt_f32_i32_e32 v23, v23
	v_cvt_f32_i32_e32 v24, v24
	v_cvt_f32_i32_e32 v25, v25
	v_cvt_f32_i32_e32 v18, v18
	v_cvt_f32_i32_e32 v19, v19
	v_cvt_f32_i32_e32 v20, v20
	v_cvt_f32_i32_e32 v21, v21
	v_cvt_f32_i32_e32 v14, v14
	v_cvt_f32_i32_e32 v15, v15
	v_cvt_f32_i32_e32 v16, v16
	v_cvt_f32_i32_e32 v17, v17
	v_cvt_f32_i32_e32 v10, v10
	v_cvt_f32_i32_e32 v11, v11
	v_cvt_f32_i32_e32 v12, v12
	v_cvt_f32_i32_e32 v13, v13
	v_cvt_f32_i32_e32 v6, v6
	v_cvt_f32_i32_e32 v7, v7
	v_cvt_f32_i32_e32 v8, v8
	v_cvt_f32_i32_e32 v9, v9
	v_cvt_f32_i32_e32 v2, v2
	v_cvt_f32_i32_e32 v3, v3
	v_cvt_f32_i32_e32 v4, v4
	v_cvt_f32_i32_e32 v5, v5
	s_waitcnt vmcnt(22)
	v_fmamk_f32 v242, v242, 0x39800000, v197
	v_fmamk_f32 v243, v243, 0x39800000, v197
	v_fmamk_f32 v244, v244, 0x39800000, v197
	v_fmamk_f32 v245, v245, 0x39800000, v197
	v_fmamk_f32 v246, v246, 0x39800000, v197
	v_fmamk_f32 v247, v247, 0x39800000, v197
	v_fmamk_f32 v248, v248, 0x39800000, v197
	v_fmamk_f32 v249, v249, 0x39800000, v197
	v_rsq_f32_e32 v242, v242
	v_rsq_f32_e32 v243, v243
	v_rsq_f32_e32 v244, v244
	v_rsq_f32_e32 v245, v245
	v_rsq_f32_e32 v246, v246
	v_rsq_f32_e32 v247, v247
	v_rsq_f32_e32 v248, v248
	v_rsq_f32_e32 v249, v249
	v_mul_f32_e32 v242, v250, v242
	v_mul_f32_e32 v243, v251, v243
	v_mul_f32_e32 v244, v252, v244
	v_mul_f32_e32 v245, v253, v245
	v_mul_f32_e32 v246, v182, v246
	v_mul_f32_e32 v247, v188, v247
	v_mul_f32_e32 v248, v192, v248
	v_mul_f32_e32 v249, v196, v249
	s_waitcnt vmcnt(18)
	v_pk_mul_f32 v[142:143], v[242:243], v[142:143] op_sel:[0,0] op_sel_hi:[0,1]
	v_pk_mul_f32 v[144:145], v[242:243], v[144:145] op_sel:[0,0] op_sel_hi:[0,1]
	v_pk_mul_f32 v[142:143], v[58:59], v[142:143]
	v_pk_mul_f32 v[144:145], v[60:61], v[144:145]
	v_mul_f32_e32 v142, v255, v142
	v_mul_f32_e32 v143, v255, v143
	v_mul_f32_e32 v144, v255, v144
	v_mul_f32_e32 v145, v255, v145
	v_exp_f32_e32 v142, v142
	v_exp_f32_e32 v143, v143
	v_exp_f32_e32 v144, v144
	v_exp_f32_e32 v145, v145
	v_add_f32_e32 v142, 1.0, v142
	v_add_f32_e32 v143, 1.0, v143
	v_add_f32_e32 v144, 1.0, v144
	v_add_f32_e32 v145, 1.0, v145
	v_rcp_f32_e32 v142, v142
	v_rcp_f32_e32 v143, v143
	v_rcp_f32_e32 v144, v144
	v_rcp_f32_e32 v145, v145
	s_waitcnt vmcnt(13)
	v_lshlrev_b32_e32 v250, 16, v162
	v_and_b32_e32 v251, 0xffff0000, v162
	v_lshlrev_b32_e32 v252, 16, v163
	v_and_b32_e32 v253, 0xffff0000, v163
	v_pk_fma_f32 v[146:147], v[142:143], v[250:251], v[146:147]
	v_pk_fma_f32 v[148:149], v[144:145], v[252:253], v[148:149]
	global_store_dwordx4 v190, v[146:149], s[54:55] offset:0
	v_pk_mul_f32 v[138:139], v[242:243], v[138:139] op_sel:[0,0] op_sel_hi:[0,1]
	v_pk_mul_f32 v[140:141], v[242:243], v[140:141] op_sel:[0,0] op_sel_hi:[0,1]
	v_pk_mul_f32 v[138:139], v[66:67], v[138:139]
	v_pk_mul_f32 v[140:141], v[68:69], v[140:141]
	v_mul_f32_e32 v138, v255, v138
	v_mul_f32_e32 v139, v255, v139
	v_mul_f32_e32 v140, v255, v140
	v_mul_f32_e32 v141, v255, v141
	v_exp_f32_e32 v138, v138
	v_exp_f32_e32 v139, v139
	v_exp_f32_e32 v140, v140
	v_exp_f32_e32 v141, v141
	v_add_f32_e32 v138, 1.0, v138
	v_add_f32_e32 v139, 1.0, v139
	v_add_f32_e32 v140, 1.0, v140
	v_add_f32_e32 v141, 1.0, v141
	v_rcp_f32_e32 v138, v138
	v_rcp_f32_e32 v139, v139
	v_rcp_f32_e32 v140, v140
	v_rcp_f32_e32 v141, v141
	v_lshlrev_b32_e32 v250, 16, v164
	v_and_b32_e32 v251, 0xffff0000, v164
	v_lshlrev_b32_e32 v252, 16, v165
	v_and_b32_e32 v253, 0xffff0000, v165
	v_pk_fma_f32 v[150:151], v[138:139], v[250:251], v[150:151]
	v_pk_fma_f32 v[152:153], v[140:141], v[252:253], v[152:153]
	global_store_dwordx4 v190, v[150:153], s[54:55] offset:64
	v_pk_mul_f32 v[134:135], v[242:243], v[134:135] op_sel:[0,0] op_sel_hi:[0,1]
	v_pk_mul_f32 v[136:137], v[242:243], v[136:137] op_sel:[0,0] op_sel_hi:[0,1]
	v_pk_mul_f32 v[134:135], v[74:75], v[134:135]
	v_pk_mul_f32 v[136:137], v[76:77], v[136:137]
	v_mul_f32_e32 v134, v255, v134
	v_mul_f32_e32 v135, v255, v135
	v_mul_f32_e32 v136, v255, v136
	v_mul_f32_e32 v137, v255, v137
	v_exp_f32_e32 v134, v134
	v_exp_f32_e32 v135, v135
	v_exp_f32_e32 v136, v136
	v_exp_f32_e32 v137, v137
	v_add_f32_e32 v134, 1.0, v134
	v_add_f32_e32 v135, 1.0, v135
	v_add_f32_e32 v136, 1.0, v136
	v_add_f32_e32 v137, 1.0, v137
	v_rcp_f32_e32 v134, v134
	v_rcp_f32_e32 v135, v135
	v_rcp_f32_e32 v136, v136
	v_rcp_f32_e32 v137, v137
	s_waitcnt vmcnt(14)
; __device__ __forceinline__ f32x4 sig4(const f32x4 v) { return (f32x4){sigmoidf_(v[0]), sigmoidf_(v[1]), sigmoidf_(v[2]), sigmoidf_(v[3])}; }
;     __device__ __forceinline__ void operator()(const typename AccT<I8>::type (&acc)[2][2][4][2], const Unit& u, int wr, int wc, int fr, int fq) const {
;     ...
;         for (int s = 0; s < 8; ++s) { const int ai = s >> 2, m = s & 3; const int r = row0 + ai * HALF + m * 16; const size_t off = (size_t)r * 4096 + col0;
;                 if (s + 1 < 8) load_row(nxt, (size_t)(row0 + ((s + 1) >> 2) * HALF + ((s + 1) & 3) * 16) * 4096 + col0);
;                 const float rs = rsv[s];
;                 float ss = 0.f, mx = 0.f;
; #pragma unroll
;                 for (int bj = 0; bj < 2; ++bj)
; #pragma unroll
;                     for (int n = 0; n < 2; ++n) { const size_t o = off + bj * HALF + n * 16; const f32x4 b = cur.b[bj][n]; f32x4 v;
;                         if constexpr (I8) v = __builtin_convertvector(acc[ai][bj][m][n], f32x4) * rs * sv[bj][n]; else v = acc[ai][bj][m][n];
;                         if (MODE == 1) { const u32x2 pw = cur.pw[bj][n]; const f32x4 pp = (f32x4){bf_lo(pw.x), bf_hi(pw.x), bf_lo(pw.y), bf_hi(pw.y)}; v = sig4(I8 ? v : v * rs) * pp; }
;                         const f32x4 x = b + v; *(f32x4*)(out + o) = x;
	v_lshlrev_b32_e32 v250, 16, v178
	v_and_b32_e32 v251, 0xffff0000, v178
	v_lshlrev_b32_e32 v252, 16, v179
	v_and_b32_e32 v253, 0xffff0000, v179
	v_pk_fma_f32 v[154:155], v[134:135], v[250:251], v[154:155]
	v_pk_fma_f32 v[156:157], v[136:137], v[252:253], v[156:157]
	global_store_dwordx4 v190, v[154:157], s[54:55] offset:512
	v_pk_mul_f32 v[130:131], v[242:243], v[130:131] op_sel:[0,0] op_sel_hi:[0,1]
	v_pk_mul_f32 v[132:133], v[242:243], v[132:133] op_sel:[0,0] op_sel_hi:[0,1]
	v_pk_mul_f32 v[130:131], v[78:79], v[130:131]
	v_pk_mul_f32 v[132:133], v[80:81], v[132:133]
	v_mul_f32_e32 v130, v255, v130
	v_mul_f32_e32 v131, v255, v131
	v_mul_f32_e32 v132, v255, v132
	v_mul_f32_e32 v133, v255, v133
	v_exp_f32_e32 v130, v130
	v_exp_f32_e32 v131, v131
	v_exp_f32_e32 v132, v132
	v_exp_f32_e32 v133, v133
	v_add_f32_e32 v130, 1.0, v130
	v_add_f32_e32 v131, 1.0, v131
	v_add_f32_e32 v132, 1.0, v132
	v_add_f32_e32 v133, 1.0, v133
	v_rcp_f32_e32 v130, v130
	v_rcp_f32_e32 v131, v131
	v_rcp_f32_e32 v132, v132
	v_rcp_f32_e32 v133, v133
	v_lshlrev_b32_e32 v250, 16, v180
	v_and_b32_e32 v251, 0xffff0000, v180
	v_lshlrev_b32_e32 v252, 16, v181
	v_and_b32_e32 v253, 0xffff0000, v181
	v_pk_fma_f32 v[158:159], v[130:131], v[250:251], v[158:159]
	v_pk_fma_f32 v[160:161], v[132:133], v[252:253], v[160:161]
	global_store_dwordx4 v190, v[158:161], s[54:55] offset:576
	v_and_b32_e32 v195, 63, v0
	v_lshlrev_b32_e32 v195, 4, v195
	v_lshlrev_b32_e32 v194, 1, v191
	v_sub_u32_e32 v194, v194, v195
	v_add_u32_e32 v194, 0x18000, v194
	v_add_u32_e32 v195, 0xc000, v191
	global_load_dwordx4 v[146:149], v194, s[52:53] offset:0
	global_load_dwordx4 v[150:153], v194, s[52:53] offset:1024
	global_load_dwordx4 v[154:157], v194, s[52:53] offset:2048
	global_load_dwordx4 v[158:161], v194, s[52:53] offset:3072
	global_load_dwordx4 v[162:165], v195, s[50:51] offset:0
	global_load_dwordx4 v[178:181], v195, s[50:51] offset:1024
	v_add_u32_e32 v194, 0x40000, v190
	v_pk_mul_f32 v[126:127], v[242:243], v[126:127] op_sel:[1,0] op_sel_hi:[1,1]
	v_pk_mul_f32 v[128:129], v[242:243], v[128:129] op_sel:[1,0] op_sel_hi:[1,1]
	v_pk_mul_f32 v[126:127], v[58:59], v[126:127]
	v_pk_mul_f32 v[128:129], v[60:61], v[128:129]
	v_mul_f32_e32 v126, v255, v126
	v_mul_f32_e32 v127, v255, v127
	v_mul_f32_e32 v128, v255, v128
	v_mul_f32_e32 v129, v255, v129
	v_exp_f32_e32 v126, v126
	v_exp_f32_e32 v127, v127
	v_exp_f32_e32 v128, v128
	v_exp_f32_e32 v129, v129
	v_add_f32_e32 v126, 1.0, v126
	v_add_f32_e32 v127, 1.0, v127
	v_add_f32_e32 v128, 1.0, v128
	v_add_f32_e32 v129, 1.0, v129
	v_rcp_f32_e32 v126, v126
	v_rcp_f32_e32 v127, v127
	v_rcp_f32_e32 v128, v128
	v_rcp_f32_e32 v129, v129
	s_waitcnt vmcnt(17)
	v_lshlrev_b32_e32 v250, 16, v184
	v_and_b32_e32 v251, 0xffff0000, v184
	v_lshlrev_b32_e32 v252, 16, v185
	v_and_b32_e32 v253, 0xffff0000, v185
	v_pk_fma_f32 v[198:199], v[126:127], v[250:251], v[198:199]
	v_pk_fma_f32 v[200:201], v[128:129], v[252:253], v[200:201]
	global_store_dwordx4 v194, v[198:201], s[54:55] offset:0
	v_pk_mul_f32 v[122:123], v[242:243], v[122:123] op_sel:[1,0] op_sel_hi:[1,1]
	v_pk_mul_f32 v[124:125], v[242:243], v[124:125] op_sel:[1,0] op_sel_hi:[1,1]
	v_pk_mul_f32 v[122:123], v[66:67], v[122:123]
	v_pk_mul_f32 v[124:125], v[68:69], v[124:125]
	v_mul_f32_e32 v122, v255, v122
	v_mul_f32_e32 v123, v255, v123
	v_mul_f32_e32 v124, v255, v124
	v_mul_f32_e32 v125, v255, v125
	v_exp_f32_e32 v122, v122
	v_exp_f32_e32 v123, v123
	v_exp_f32_e32 v124, v124
	v_exp_f32_e32 v125, v125
	v_add_f32_e32 v122, 1.0, v122
	v_add_f32_e32 v123, 1.0, v123
	v_add_f32_e32 v124, 1.0, v124
	v_add_f32_e32 v125, 1.0, v125
	v_rcp_f32_e32 v122, v122
	v_rcp_f32_e32 v123, v123
	v_rcp_f32_e32 v124, v124
	v_rcp_f32_e32 v125, v125
	v_lshlrev_b32_e32 v250, 16, v186
	v_and_b32_e32 v251, 0xffff0000, v186
	v_lshlrev_b32_e32 v252, 16, v187
	v_and_b32_e32 v253, 0xffff0000, v187
	v_pk_fma_f32 v[202:203], v[122:123], v[250:251], v[202:203]
	v_pk_fma_f32 v[204:205], v[124:125], v[252:253], v[204:205]
	global_store_dwordx4 v194, v[202:205], s[54:55] offset:64
	v_pk_mul_f32 v[118:119], v[242:243], v[118:119] op_sel:[1,0] op_sel_hi:[1,1]
	v_pk_mul_f32 v[120:121], v[242:243], v[120:121] op_sel:[1,0] op_sel_hi:[1,1]
	v_pk_mul_f32 v[118:119], v[74:75], v[118:119]
	v_pk_mul_f32 v[120:121], v[76:77], v[120:121]
	v_mul_f32_e32 v118, v255, v118
	v_mul_f32_e32 v119, v255, v119
	v_mul_f32_e32 v120, v255, v120
	v_mul_f32_e32 v121, v255, v121
	v_exp_f32_e32 v118, v118
	v_exp_f32_e32 v119, v119
	v_exp_f32_e32 v120, v120
	v_exp_f32_e32 v121, v121
	v_add_f32_e32 v118, 1.0, v118
	v_add_f32_e32 v119, 1.0, v119
	v_add_f32_e32 v120, 1.0, v120
	v_add_f32_e32 v121, 1.0, v121
	v_rcp_f32_e32 v118, v118
	v_rcp_f32_e32 v119, v119
	v_rcp_f32_e32 v120, v120
	v_rcp_f32_e32 v121, v121
	s_waitcnt vmcnt(18)
; __device__ __forceinline__ f32x4 sig4(const f32x4 v) { return (f32x4){sigmoidf_(v[0]), sigmoidf_(v[1]), sigmoidf_(v[2]), sigmoidf_(v[3])}; }
;     __device__ __forceinline__ void operator()(const typename AccT<I8>::type (&acc)[2][2][4][2], const Unit& u, int wr, int wc, int fr, int fq) const {
;     ...
;         for (int s = 0; s < 8; ++s) { const int ai = s >> 2, m = s & 3; const int r = row0 + ai * HALF + m * 16; const size_t off = (size_t)r * 4096 + col0;
;                 if (s + 1 < 8) load_row(nxt, (size_t)(row0 + ((s + 1) >> 2) * HALF + ((s + 1) & 3) * 16) * 4096 + col0);
;                 const float rs = rsv[s];
;                 float ss = 0.f, mx = 0.f;
; #pragma unroll
;                 for (int bj = 0; bj < 2; ++bj)
; #pragma unroll
;                     for (int n = 0; n < 2; ++n) { const size_t o = off + bj * HALF + n * 16; const f32x4 b = cur.b[bj][n]; f32x4 v;
;                         if constexpr (I8) v = __builtin_convertvector(acc[ai][bj][m][n], f32x4) * rs * sv[bj][n]; else v = acc[ai][bj][m][n];
;                         if (MODE == 1) { const u32x2 pw = cur.pw[bj][n]; const f32x4 pp = (f32x4){bf_lo(pw.x), bf_hi(pw.x), bf_lo(pw.y), bf_hi(pw.y)}; v = sig4(I8 ? v : v * rs) * pp; }
;                         const f32x4 x = b + v; *(f32x4*)(out + o) = x;
	v_lshlrev_b32_e32 v250, 16, v214
	v_and_b32_e32 v251, 0xffff0000, v214
	v_lshlrev_b32_e32 v252, 16, v215
	v_and_b32_e32 v253, 0xffff0000, v215
	v_pk_fma_f32 v[206:207], v[118:119], v[250:251], v[206:207]
	v_pk_fma_f32 v[208:209], v[120:121], v[252:253], v[208:209]
	global_store_dwordx4 v194, v[206:209], s[54:55] offset:512
	v_pk_mul_f32 v[114:115], v[242:243], v[114:115] op_sel:[1,0] op_sel_hi:[1,1]
	v_pk_mul_f32 v[116:117], v[242:243], v[116:117] op_sel:[1,0] op_sel_hi:[1,1]
	v_pk_mul_f32 v[114:115], v[78:79], v[114:115]
	v_pk_mul_f32 v[116:117], v[80:81], v[116:117]
	v_mul_f32_e32 v114, v255, v114
	v_mul_f32_e32 v115, v255, v115
	v_mul_f32_e32 v116, v255, v116
	v_mul_f32_e32 v117, v255, v117
	v_exp_f32_e32 v114, v114
	v_exp_f32_e32 v115, v115
	v_exp_f32_e32 v116, v116
	v_exp_f32_e32 v117, v117
	v_add_f32_e32 v114, 1.0, v114
	v_add_f32_e32 v115, 1.0, v115
	v_add_f32_e32 v116, 1.0, v116
	v_add_f32_e32 v117, 1.0, v117
	v_rcp_f32_e32 v114, v114
	v_rcp_f32_e32 v115, v115
	v_rcp_f32_e32 v116, v116
	v_rcp_f32_e32 v117, v117
	v_lshlrev_b32_e32 v250, 16, v216
	v_and_b32_e32 v251, 0xffff0000, v216
	v_lshlrev_b32_e32 v252, 16, v217
	v_and_b32_e32 v253, 0xffff0000, v217
	v_pk_fma_f32 v[210:211], v[114:115], v[250:251], v[210:211]
	v_pk_fma_f32 v[212:213], v[116:117], v[252:253], v[212:213]
	global_store_dwordx4 v194, v[210:213], s[54:55] offset:576
	v_and_b32_e32 v195, 63, v0
	v_lshlrev_b32_e32 v195, 4, v195
	v_lshlrev_b32_e32 v194, 1, v191
	v_sub_u32_e32 v194, v194, v195
	v_add_u32_e32 v194, 0x20000, v194
	v_add_u32_e32 v195, 0x10000, v191
	global_load_dwordx4 v[198:201], v194, s[52:53] offset:0
	global_load_dwordx4 v[202:205], v194, s[52:53] offset:1024
	global_load_dwordx4 v[206:209], v194, s[52:53] offset:2048
	global_load_dwordx4 v[210:213], v194, s[52:53] offset:3072
	global_load_dwordx4 v[184:187], v195, s[50:51] offset:0
	global_load_dwordx4 v[214:217], v195, s[50:51] offset:1024
	v_and_b32_e32 v195, 63, v0
	v_lshlrev_b32_e32 v195, 4, v195
	v_lshlrev_b32_e32 v194, 1, v191
	v_sub_u32_e32 v194, v194, v195
	v_add_u32_e32 v194, 0x28000, v194
	v_add_u32_e32 v195, 0x14000, v191
	global_load_dwordx4 v[142:145], v194, s[52:53] offset:0
	global_load_dwordx4 v[138:141], v194, s[52:53] offset:1024
	global_load_dwordx4 v[134:137], v194, s[52:53] offset:2048
	global_load_dwordx4 v[130:133], v194, s[52:53] offset:3072
	global_load_dwordx4 v[126:129], v195, s[50:51] offset:0
	global_load_dwordx4 v[122:125], v195, s[50:51] offset:1024
	v_add_u32_e32 v194, 0x80000, v190
	v_pk_mul_f32 v[110:111], v[244:245], v[110:111] op_sel:[0,0] op_sel_hi:[0,1]
	v_pk_mul_f32 v[112:113], v[244:245], v[112:113] op_sel:[0,0] op_sel_hi:[0,1]
	v_pk_mul_f32 v[110:111], v[58:59], v[110:111]
	v_pk_mul_f32 v[112:113], v[60:61], v[112:113]
	v_mul_f32_e32 v110, v255, v110
	v_mul_f32_e32 v111, v255, v111
	v_mul_f32_e32 v112, v255, v112
	v_mul_f32_e32 v113, v255, v113
	v_exp_f32_e32 v110, v110
	v_exp_f32_e32 v111, v111
	v_exp_f32_e32 v112, v112
	v_exp_f32_e32 v113, v113
	v_add_f32_e32 v110, 1.0, v110
	v_add_f32_e32 v111, 1.0, v111
	v_add_f32_e32 v112, 1.0, v112
	v_add_f32_e32 v113, 1.0, v113
	v_rcp_f32_e32 v110, v110
	v_rcp_f32_e32 v111, v111
	v_rcp_f32_e32 v112, v112
	v_rcp_f32_e32 v113, v113
	s_waitcnt vmcnt(27)
	v_lshlrev_b32_e32 v250, 16, v234
	v_and_b32_e32 v251, 0xffff0000, v234
	v_lshlrev_b32_e32 v252, 16, v235
	v_and_b32_e32 v253, 0xffff0000, v235
	v_pk_fma_f32 v[218:219], v[110:111], v[250:251], v[218:219]
	v_pk_fma_f32 v[220:221], v[112:113], v[252:253], v[220:221]
	global_store_dwordx4 v194, v[218:221], s[54:55] offset:0
	v_pk_mul_f32 v[106:107], v[244:245], v[106:107] op_sel:[0,0] op_sel_hi:[0,1]
	v_pk_mul_f32 v[108:109], v[244:245], v[108:109] op_sel:[0,0] op_sel_hi:[0,1]
	v_pk_mul_f32 v[106:107], v[66:67], v[106:107]
	v_pk_mul_f32 v[108:109], v[68:69], v[108:109]
	v_mul_f32_e32 v106, v255, v106
	v_mul_f32_e32 v107, v255, v107
	v_mul_f32_e32 v108, v255, v108
	v_mul_f32_e32 v109, v255, v109
	v_exp_f32_e32 v106, v106
	v_exp_f32_e32 v107, v107
	v_exp_f32_e32 v108, v108
	v_exp_f32_e32 v109, v109
	v_add_f32_e32 v106, 1.0, v106
	v_add_f32_e32 v107, 1.0, v107
	v_add_f32_e32 v108, 1.0, v108
	v_add_f32_e32 v109, 1.0, v109
	v_rcp_f32_e32 v106, v106
	v_rcp_f32_e32 v107, v107
	v_rcp_f32_e32 v108, v108
	v_rcp_f32_e32 v109, v109
	v_lshlrev_b32_e32 v250, 16, v236
	v_and_b32_e32 v251, 0xffff0000, v236
	v_lshlrev_b32_e32 v252, 16, v237
	v_and_b32_e32 v253, 0xffff0000, v237
	v_pk_fma_f32 v[222:223], v[106:107], v[250:251], v[222:223]
	v_pk_fma_f32 v[224:225], v[108:109], v[252:253], v[224:225]
	global_store_dwordx4 v194, v[222:225], s[54:55] offset:64
	v_pk_mul_f32 v[102:103], v[244:245], v[102:103] op_sel:[0,0] op_sel_hi:[0,1]
	v_pk_mul_f32 v[104:105], v[244:245], v[104:105] op_sel:[0,0] op_sel_hi:[0,1]
	v_pk_mul_f32 v[102:103], v[74:75], v[102:103]
	v_pk_mul_f32 v[104:105], v[76:77], v[104:105]
	v_mul_f32_e32 v102, v255, v102
	v_mul_f32_e32 v103, v255, v103
	v_mul_f32_e32 v104, v255, v104
	v_mul_f32_e32 v105, v255, v105
	v_exp_f32_e32 v102, v102
	v_exp_f32_e32 v103, v103
	v_exp_f32_e32 v104, v104
	v_exp_f32_e32 v105, v105
	v_add_f32_e32 v102, 1.0, v102
	v_add_f32_e32 v103, 1.0, v103
	v_add_f32_e32 v104, 1.0, v104
	v_add_f32_e32 v105, 1.0, v105
	v_rcp_f32_e32 v102, v102
	v_rcp_f32_e32 v103, v103
	v_rcp_f32_e32 v104, v104
	v_rcp_f32_e32 v105, v105
	s_waitcnt vmcnt(28)
; __device__ __forceinline__ f32x4 sig4(const f32x4 v) { return (f32x4){sigmoidf_(v[0]), sigmoidf_(v[1]), sigmoidf_(v[2]), sigmoidf_(v[3])}; }
;     __device__ __forceinline__ void operator()(const typename AccT<I8>::type (&acc)[2][2][4][2], const Unit& u, int wr, int wc, int fr, int fq) const {
;     ...
;         for (int s = 0; s < 8; ++s) { const int ai = s >> 2, m = s & 3; const int r = row0 + ai * HALF + m * 16; const size_t off = (size_t)r * 4096 + col0;
;                 if (s + 1 < 8) load_row(nxt, (size_t)(row0 + ((s + 1) >> 2) * HALF + ((s + 1) & 3) * 16) * 4096 + col0);
;                 const float rs = rsv[s];
;                 float ss = 0.f, mx = 0.f;
; #pragma unroll
;                 for (int bj = 0; bj < 2; ++bj)
; #pragma unroll
;                     for (int n = 0; n < 2; ++n) { const size_t o = off + bj * HALF + n * 16; const f32x4 b = cur.b[bj][n]; f32x4 v;
;                         if constexpr (I8) v = __builtin_convertvector(acc[ai][bj][m][n], f32x4) * rs * sv[bj][n]; else v = acc[ai][bj][m][n];
;                         if (MODE == 1) { const u32x2 pw = cur.pw[bj][n]; const f32x4 pp = (f32x4){bf_lo(pw.x), bf_hi(pw.x), bf_lo(pw.y), bf_hi(pw.y)}; v = sig4(I8 ? v : v * rs) * pp; }
;                         const f32x4 x = b + v; *(f32x4*)(out + o) = x;
	v_lshlrev_b32_e32 v250, 16, v238
	v_and_b32_e32 v251, 0xffff0000, v238
	v_lshlrev_b32_e32 v252, 16, v239
	v_and_b32_e32 v253, 0xffff0000, v239
	v_pk_fma_f32 v[226:227], v[102:103], v[250:251], v[226:227]
	v_pk_fma_f32 v[228:229], v[104:105], v[252:253], v[228:229]
	global_store_dwordx4 v194, v[226:229], s[54:55] offset:512
	v_pk_mul_f32 v[98:99], v[244:245], v[98:99] op_sel:[0,0] op_sel_hi:[0,1]
	v_pk_mul_f32 v[100:101], v[244:245], v[100:101] op_sel:[0,0] op_sel_hi:[0,1]
	v_pk_mul_f32 v[98:99], v[78:79], v[98:99]
	v_pk_mul_f32 v[100:101], v[80:81], v[100:101]
	v_mul_f32_e32 v98, v255, v98
	v_mul_f32_e32 v99, v255, v99
	v_mul_f32_e32 v100, v255, v100
	v_mul_f32_e32 v101, v255, v101
	v_exp_f32_e32 v98, v98
	v_exp_f32_e32 v99, v99
	v_exp_f32_e32 v100, v100
	v_exp_f32_e32 v101, v101
	v_add_f32_e32 v98, 1.0, v98
	v_add_f32_e32 v99, 1.0, v99
	v_add_f32_e32 v100, 1.0, v100
	v_add_f32_e32 v101, 1.0, v101
	v_rcp_f32_e32 v98, v98
	v_rcp_f32_e32 v99, v99
	v_rcp_f32_e32 v100, v100
	v_rcp_f32_e32 v101, v101
	v_lshlrev_b32_e32 v250, 16, v240
	v_and_b32_e32 v251, 0xffff0000, v240
	v_lshlrev_b32_e32 v252, 16, v241
	v_and_b32_e32 v253, 0xffff0000, v241
	v_pk_fma_f32 v[230:231], v[98:99], v[250:251], v[230:231]
	v_pk_fma_f32 v[232:233], v[100:101], v[252:253], v[232:233]
	global_store_dwordx4 v194, v[230:233], s[54:55] offset:576
	v_and_b32_e32 v195, 63, v0
	v_lshlrev_b32_e32 v195, 4, v195
	v_lshlrev_b32_e32 v194, 1, v191
	v_sub_u32_e32 v194, v194, v195
	v_add_u32_e32 v194, 0x30000, v194
	v_add_u32_e32 v195, 0x18000, v191
	global_load_dwordx4 v[218:221], v194, s[52:53] offset:0
	global_load_dwordx4 v[222:225], v194, s[52:53] offset:1024
	global_load_dwordx4 v[226:229], v194, s[52:53] offset:2048
	global_load_dwordx4 v[230:233], v194, s[52:53] offset:3072
	global_load_dwordx4 v[234:237], v195, s[50:51] offset:0
	global_load_dwordx4 v[238:241], v195, s[50:51] offset:1024
	v_and_b32_e32 v195, 63, v0
	v_lshlrev_b32_e32 v195, 4, v195
	v_lshlrev_b32_e32 v194, 1, v191
	v_sub_u32_e32 v194, v194, v195
	v_add_u32_e32 v194, 0x38000, v194
	v_add_u32_e32 v195, 0x1c000, v191
	global_load_dwordx4 v[110:113], v194, s[52:53] offset:0
	global_load_dwordx4 v[106:109], v194, s[52:53] offset:1024
	global_load_dwordx4 v[102:105], v194, s[52:53] offset:2048
	global_load_dwordx4 v[98:101], v194, s[52:53] offset:3072
	global_load_dwordx4 v[118:121], v195, s[50:51] offset:0
	global_load_dwordx4 v[114:117], v195, s[50:51] offset:1024
	v_add_u32_e32 v194, 0xc0000, v190
	v_pk_mul_f32 v[94:95], v[244:245], v[94:95] op_sel:[1,0] op_sel_hi:[1,1]
	v_pk_mul_f32 v[96:97], v[244:245], v[96:97] op_sel:[1,0] op_sel_hi:[1,1]
	v_pk_mul_f32 v[94:95], v[58:59], v[94:95]
	v_pk_mul_f32 v[96:97], v[60:61], v[96:97]
	v_mul_f32_e32 v94, v255, v94
	v_mul_f32_e32 v95, v255, v95
	v_mul_f32_e32 v96, v255, v96
	v_mul_f32_e32 v97, v255, v97
	v_exp_f32_e32 v94, v94
	v_exp_f32_e32 v95, v95
	v_exp_f32_e32 v96, v96
	v_exp_f32_e32 v97, v97
	v_add_f32_e32 v94, 1.0, v94
	v_add_f32_e32 v95, 1.0, v95
	v_add_f32_e32 v96, 1.0, v96
	v_add_f32_e32 v97, 1.0, v97
	v_rcp_f32_e32 v94, v94
	v_rcp_f32_e32 v95, v95
	v_rcp_f32_e32 v96, v96
	v_rcp_f32_e32 v97, v97
	s_waitcnt vmcnt(33)
	v_lshlrev_b32_e32 v250, 16, v162
	v_and_b32_e32 v251, 0xffff0000, v162
	v_lshlrev_b32_e32 v252, 16, v163
	v_and_b32_e32 v253, 0xffff0000, v163
	v_pk_fma_f32 v[146:147], v[94:95], v[250:251], v[146:147]
	v_pk_fma_f32 v[148:149], v[96:97], v[252:253], v[148:149]
	global_store_dwordx4 v194, v[146:149], s[54:55] offset:0
	v_pk_mul_f32 v[90:91], v[244:245], v[90:91] op_sel:[1,0] op_sel_hi:[1,1]
	v_pk_mul_f32 v[92:93], v[244:245], v[92:93] op_sel:[1,0] op_sel_hi:[1,1]
	v_pk_mul_f32 v[90:91], v[66:67], v[90:91]
	v_pk_mul_f32 v[92:93], v[68:69], v[92:93]
	v_mul_f32_e32 v90, v255, v90
	v_mul_f32_e32 v91, v255, v91
	v_mul_f32_e32 v92, v255, v92
	v_mul_f32_e32 v93, v255, v93
	v_exp_f32_e32 v90, v90
	v_exp_f32_e32 v91, v91
	v_exp_f32_e32 v92, v92
	v_exp_f32_e32 v93, v93
	v_add_f32_e32 v90, 1.0, v90
	v_add_f32_e32 v91, 1.0, v91
	v_add_f32_e32 v92, 1.0, v92
	v_add_f32_e32 v93, 1.0, v93
	v_rcp_f32_e32 v90, v90
	v_rcp_f32_e32 v91, v91
	v_rcp_f32_e32 v92, v92
	v_rcp_f32_e32 v93, v93
	v_lshlrev_b32_e32 v250, 16, v164
	v_and_b32_e32 v251, 0xffff0000, v164
	v_lshlrev_b32_e32 v252, 16, v165
	v_and_b32_e32 v253, 0xffff0000, v165
	v_pk_fma_f32 v[150:151], v[90:91], v[250:251], v[150:151]
	v_pk_fma_f32 v[152:153], v[92:93], v[252:253], v[152:153]
	global_store_dwordx4 v194, v[150:153], s[54:55] offset:64
	v_pk_mul_f32 v[86:87], v[244:245], v[86:87] op_sel:[1,0] op_sel_hi:[1,1]
	v_pk_mul_f32 v[88:89], v[244:245], v[88:89] op_sel:[1,0] op_sel_hi:[1,1]
	v_pk_mul_f32 v[86:87], v[74:75], v[86:87]
	v_pk_mul_f32 v[88:89], v[76:77], v[88:89]
	v_mul_f32_e32 v86, v255, v86
	v_mul_f32_e32 v87, v255, v87
	v_mul_f32_e32 v88, v255, v88
	v_mul_f32_e32 v89, v255, v89
	v_exp_f32_e32 v86, v86
	v_exp_f32_e32 v87, v87
	v_exp_f32_e32 v88, v88
	v_exp_f32_e32 v89, v89
	v_add_f32_e32 v86, 1.0, v86
	v_add_f32_e32 v87, 1.0, v87
	v_add_f32_e32 v88, 1.0, v88
	v_add_f32_e32 v89, 1.0, v89
	v_rcp_f32_e32 v86, v86
	v_rcp_f32_e32 v87, v87
	v_rcp_f32_e32 v88, v88
	v_rcp_f32_e32 v89, v89
	s_waitcnt vmcnt(34)
; __device__ __forceinline__ f32x4 sig4(const f32x4 v) { return (f32x4){sigmoidf_(v[0]), sigmoidf_(v[1]), sigmoidf_(v[2]), sigmoidf_(v[3])}; }
;     __device__ __forceinline__ void operator()(const typename AccT<I8>::type (&acc)[2][2][4][2], const Unit& u, int wr, int wc, int fr, int fq) const {
;     ...
;         for (int s = 0; s < 8; ++s) { const int ai = s >> 2, m = s & 3; const int r = row0 + ai * HALF + m * 16; const size_t off = (size_t)r * 4096 + col0;
;                 if (s + 1 < 8) load_row(nxt, (size_t)(row0 + ((s + 1) >> 2) * HALF + ((s + 1) & 3) * 16) * 4096 + col0);
;                 const float rs = rsv[s];
;                 float ss = 0.f, mx = 0.f;
; #pragma unroll
;                 for (int bj = 0; bj < 2; ++bj)
; #pragma unroll
;                     for (int n = 0; n < 2; ++n) { const size_t o = off + bj * HALF + n * 16; const f32x4 b = cur.b[bj][n]; f32x4 v;
;                         if constexpr (I8) v = __builtin_convertvector(acc[ai][bj][m][n], f32x4) * rs * sv[bj][n]; else v = acc[ai][bj][m][n];
;                         if (MODE == 1) { const u32x2 pw = cur.pw[bj][n]; const f32x4 pp = (f32x4){bf_lo(pw.x), bf_hi(pw.x), bf_lo(pw.y), bf_hi(pw.y)}; v = sig4(I8 ? v : v * rs) * pp; }
;                         const f32x4 x = b + v; *(f32x4*)(out + o) = x;
	v_lshlrev_b32_e32 v250, 16, v178
	v_and_b32_e32 v251, 0xffff0000, v178
	v_lshlrev_b32_e32 v252, 16, v179
	v_and_b32_e32 v253, 0xffff0000, v179
	v_pk_fma_f32 v[154:155], v[86:87], v[250:251], v[154:155]
	v_pk_fma_f32 v[156:157], v[88:89], v[252:253], v[156:157]
	global_store_dwordx4 v194, v[154:157], s[54:55] offset:512
	v_pk_mul_f32 v[82:83], v[244:245], v[82:83] op_sel:[1,0] op_sel_hi:[1,1]
	v_pk_mul_f32 v[84:85], v[244:245], v[84:85] op_sel:[1,0] op_sel_hi:[1,1]
	v_pk_mul_f32 v[82:83], v[78:79], v[82:83]
	v_pk_mul_f32 v[84:85], v[80:81], v[84:85]
	v_mul_f32_e32 v82, v255, v82
	v_mul_f32_e32 v83, v255, v83
	v_mul_f32_e32 v84, v255, v84
	v_mul_f32_e32 v85, v255, v85
	v_exp_f32_e32 v82, v82
	v_exp_f32_e32 v83, v83
	v_exp_f32_e32 v84, v84
	v_exp_f32_e32 v85, v85
	v_add_f32_e32 v82, 1.0, v82
	v_add_f32_e32 v83, 1.0, v83
	v_add_f32_e32 v84, 1.0, v84
	v_add_f32_e32 v85, 1.0, v85
	v_rcp_f32_e32 v82, v82
	v_rcp_f32_e32 v83, v83
	v_rcp_f32_e32 v84, v84
	v_rcp_f32_e32 v85, v85
	v_lshlrev_b32_e32 v250, 16, v180
	v_and_b32_e32 v251, 0xffff0000, v180
	v_lshlrev_b32_e32 v252, 16, v181
	v_and_b32_e32 v253, 0xffff0000, v181
	v_pk_fma_f32 v[158:159], v[82:83], v[250:251], v[158:159]
	v_pk_fma_f32 v[160:161], v[84:85], v[252:253], v[160:161]
	global_store_dwordx4 v194, v[158:161], s[54:55] offset:576
	v_add_u32_e32 v194, 0x200000, v190
	v_pk_mul_f32 v[70:71], v[246:247], v[70:71] op_sel:[0,0] op_sel_hi:[0,1]
	v_pk_mul_f32 v[72:73], v[246:247], v[72:73] op_sel:[0,0] op_sel_hi:[0,1]
	v_pk_mul_f32 v[70:71], v[58:59], v[70:71]
	v_pk_mul_f32 v[72:73], v[60:61], v[72:73]
	v_mul_f32_e32 v70, v255, v70
	v_mul_f32_e32 v71, v255, v71
	v_mul_f32_e32 v72, v255, v72
	v_mul_f32_e32 v73, v255, v73
	v_exp_f32_e32 v70, v70
	v_exp_f32_e32 v71, v71
	v_exp_f32_e32 v72, v72
	v_exp_f32_e32 v73, v73
	v_add_f32_e32 v70, 1.0, v70
	v_add_f32_e32 v71, 1.0, v71
	v_add_f32_e32 v72, 1.0, v72
	v_add_f32_e32 v73, 1.0, v73
	v_rcp_f32_e32 v70, v70
	v_rcp_f32_e32 v71, v71
	v_rcp_f32_e32 v72, v72
	v_rcp_f32_e32 v73, v73
	s_waitcnt vmcnt(27)
	v_lshlrev_b32_e32 v250, 16, v184
	v_and_b32_e32 v251, 0xffff0000, v184
	v_lshlrev_b32_e32 v252, 16, v185
	v_and_b32_e32 v253, 0xffff0000, v185
	v_pk_fma_f32 v[198:199], v[70:71], v[250:251], v[198:199]
	v_pk_fma_f32 v[200:201], v[72:73], v[252:253], v[200:201]
	global_store_dwordx4 v194, v[198:201], s[54:55] offset:0
	v_pk_mul_f32 v[62:63], v[246:247], v[62:63] op_sel:[0,0] op_sel_hi:[0,1]
	v_pk_mul_f32 v[64:65], v[246:247], v[64:65] op_sel:[0,0] op_sel_hi:[0,1]
	v_pk_mul_f32 v[62:63], v[66:67], v[62:63]
	v_pk_mul_f32 v[64:65], v[68:69], v[64:65]
	v_mul_f32_e32 v62, v255, v62
	v_mul_f32_e32 v63, v255, v63
	v_mul_f32_e32 v64, v255, v64
	v_mul_f32_e32 v65, v255, v65
	v_exp_f32_e32 v62, v62
	v_exp_f32_e32 v63, v63
	v_exp_f32_e32 v64, v64
	v_exp_f32_e32 v65, v65
	v_add_f32_e32 v62, 1.0, v62
	v_add_f32_e32 v63, 1.0, v63
	v_add_f32_e32 v64, 1.0, v64
	v_add_f32_e32 v65, 1.0, v65
	v_rcp_f32_e32 v62, v62
	v_rcp_f32_e32 v63, v63
	v_rcp_f32_e32 v64, v64
	v_rcp_f32_e32 v65, v65
	v_lshlrev_b32_e32 v250, 16, v186
	v_and_b32_e32 v251, 0xffff0000, v186
	v_lshlrev_b32_e32 v252, 16, v187
	v_and_b32_e32 v253, 0xffff0000, v187
	v_pk_fma_f32 v[202:203], v[62:63], v[250:251], v[202:203]
	v_pk_fma_f32 v[204:205], v[64:65], v[252:253], v[204:205]
	global_store_dwordx4 v194, v[202:205], s[54:55] offset:64
	v_pk_mul_f32 v[54:55], v[246:247], v[54:55] op_sel:[0,0] op_sel_hi:[0,1]
	v_pk_mul_f32 v[56:57], v[246:247], v[56:57] op_sel:[0,0] op_sel_hi:[0,1]
	v_pk_mul_f32 v[54:55], v[74:75], v[54:55]
	v_pk_mul_f32 v[56:57], v[76:77], v[56:57]
	v_mul_f32_e32 v54, v255, v54
	v_mul_f32_e32 v55, v255, v55
	v_mul_f32_e32 v56, v255, v56
	v_mul_f32_e32 v57, v255, v57
	v_exp_f32_e32 v54, v54
	v_exp_f32_e32 v55, v55
	v_exp_f32_e32 v56, v56
	v_exp_f32_e32 v57, v57
	v_add_f32_e32 v54, 1.0, v54
	v_add_f32_e32 v55, 1.0, v55
	v_add_f32_e32 v56, 1.0, v56
	v_add_f32_e32 v57, 1.0, v57
	v_rcp_f32_e32 v54, v54
	v_rcp_f32_e32 v55, v55
	v_rcp_f32_e32 v56, v56
	v_rcp_f32_e32 v57, v57
	s_waitcnt vmcnt(28)
	v_lshlrev_b32_e32 v250, 16, v214
	v_and_b32_e32 v251, 0xffff0000, v214
	v_lshlrev_b32_e32 v252, 16, v215
	v_and_b32_e32 v253, 0xffff0000, v215
	v_pk_fma_f32 v[206:207], v[54:55], v[250:251], v[206:207]
	v_pk_fma_f32 v[208:209], v[56:57], v[252:253], v[208:209]
	global_store_dwordx4 v194, v[206:209], s[54:55] offset:512
	v_pk_mul_f32 v[50:51], v[246:247], v[50:51] op_sel:[0,0] op_sel_hi:[0,1]
	v_pk_mul_f32 v[52:53], v[246:247], v[52:53] op_sel:[0,0] op_sel_hi:[0,1]
	v_pk_mul_f32 v[50:51], v[78:79], v[50:51]
	v_pk_mul_f32 v[52:53], v[80:81], v[52:53]
	v_mul_f32_e32 v50, v255, v50
	v_mul_f32_e32 v51, v255, v51
	v_mul_f32_e32 v52, v255, v52
	v_mul_f32_e32 v53, v255, v53
	v_exp_f32_e32 v50, v50
	v_exp_f32_e32 v51, v51
	v_exp_f32_e32 v52, v52
	v_exp_f32_e32 v53, v53
	v_add_f32_e32 v50, 1.0, v50
	v_add_f32_e32 v51, 1.0, v51
	v_add_f32_e32 v52, 1.0, v52
	v_add_f32_e32 v53, 1.0, v53
	v_rcp_f32_e32 v50, v50
	v_rcp_f32_e32 v51, v51
	v_rcp_f32_e32 v52, v52
	v_rcp_f32_e32 v53, v53
	v_lshlrev_b32_e32 v250, 16, v216
	v_and_b32_e32 v251, 0xffff0000, v216
	v_lshlrev_b32_e32 v252, 16, v217
	v_and_b32_e32 v253, 0xffff0000, v217
	v_pk_fma_f32 v[210:211], v[50:51], v[250:251], v[210:211]
	v_pk_fma_f32 v[212:213], v[52:53], v[252:253], v[212:213]
	global_store_dwordx4 v194, v[210:213], s[54:55] offset:576
	v_add_u32_e32 v194, 0x240000, v190
	v_pk_mul_f32 v[46:47], v[246:247], v[46:47] op_sel:[1,0] op_sel_hi:[1,1]
	v_pk_mul_f32 v[48:49], v[246:247], v[48:49] op_sel:[1,0] op_sel_hi:[1,1]
	v_pk_mul_f32 v[46:47], v[58:59], v[46:47]
	v_pk_mul_f32 v[48:49], v[60:61], v[48:49]
	v_mul_f32_e32 v46, v255, v46
	v_mul_f32_e32 v47, v255, v47
	v_mul_f32_e32 v48, v255, v48
	v_mul_f32_e32 v49, v255, v49
	v_exp_f32_e32 v46, v46
	v_exp_f32_e32 v47, v47
	v_exp_f32_e32 v48, v48
	v_exp_f32_e32 v49, v49
	v_add_f32_e32 v46, 1.0, v46
	v_add_f32_e32 v47, 1.0, v47
	v_add_f32_e32 v48, 1.0, v48
	v_add_f32_e32 v49, 1.0, v49
	v_rcp_f32_e32 v46, v46
	v_rcp_f32_e32 v47, v47
	v_rcp_f32_e32 v48, v48
	v_rcp_f32_e32 v49, v49
	s_waitcnt vmcnt(25)
; __device__ __forceinline__ f32x4 sig4(const f32x4 v) { return (f32x4){sigmoidf_(v[0]), sigmoidf_(v[1]), sigmoidf_(v[2]), sigmoidf_(v[3])}; }
;     __device__ __forceinline__ void operator()(const typename AccT<I8>::type (&acc)[2][2][4][2], const Unit& u, int wr, int wc, int fr, int fq) const {
;     ...
;         for (int s = 0; s < 8; ++s) { const int ai = s >> 2, m = s & 3; const int r = row0 + ai * HALF + m * 16; const size_t off = (size_t)r * 4096 + col0;
;                 if (s + 1 < 8) load_row(nxt, (size_t)(row0 + ((s + 1) >> 2) * HALF + ((s + 1) & 3) * 16) * 4096 + col0);
;                 const float rs = rsv[s];
;                 float ss = 0.f, mx = 0.f;
; #pragma unroll
;                 for (int bj = 0; bj < 2; ++bj)
; #pragma unroll
;                     for (int n = 0; n < 2; ++n) { const size_t o = off + bj * HALF + n * 16; const f32x4 b = cur.b[bj][n]; f32x4 v;
;                         if constexpr (I8) v = __builtin_convertvector(acc[ai][bj][m][n], f32x4) * rs * sv[bj][n]; else v = acc[ai][bj][m][n];
;                         if (MODE == 1) { const u32x2 pw = cur.pw[bj][n]; const f32x4 pp = (f32x4){bf_lo(pw.x), bf_hi(pw.x), bf_lo(pw.y), bf_hi(pw.y)}; v = sig4(I8 ? v : v * rs) * pp; }
;                         const f32x4 x = b + v; *(f32x4*)(out + o) = x;
	v_lshlrev_b32_e32 v250, 16, v126
	v_and_b32_e32 v251, 0xffff0000, v126
	v_lshlrev_b32_e32 v252, 16, v127
	v_and_b32_e32 v253, 0xffff0000, v127
	v_pk_fma_f32 v[142:143], v[46:47], v[250:251], v[142:143]
	v_pk_fma_f32 v[144:145], v[48:49], v[252:253], v[144:145]
	global_store_dwordx4 v194, v[142:145], s[54:55] offset:0
	v_pk_mul_f32 v[42:43], v[246:247], v[42:43] op_sel:[1,0] op_sel_hi:[1,1]
	v_pk_mul_f32 v[44:45], v[246:247], v[44:45] op_sel:[1,0] op_sel_hi:[1,1]
	v_pk_mul_f32 v[42:43], v[66:67], v[42:43]
	v_pk_mul_f32 v[44:45], v[68:69], v[44:45]
	v_mul_f32_e32 v42, v255, v42
	v_mul_f32_e32 v43, v255, v43
	v_mul_f32_e32 v44, v255, v44
	v_mul_f32_e32 v45, v255, v45
	v_exp_f32_e32 v42, v42
	v_exp_f32_e32 v43, v43
	v_exp_f32_e32 v44, v44
	v_exp_f32_e32 v45, v45
	v_add_f32_e32 v42, 1.0, v42
	v_add_f32_e32 v43, 1.0, v43
	v_add_f32_e32 v44, 1.0, v44
	v_add_f32_e32 v45, 1.0, v45
	v_rcp_f32_e32 v42, v42
	v_rcp_f32_e32 v43, v43
	v_rcp_f32_e32 v44, v44
	v_rcp_f32_e32 v45, v45
	v_lshlrev_b32_e32 v250, 16, v128
	v_and_b32_e32 v251, 0xffff0000, v128
	v_lshlrev_b32_e32 v252, 16, v129
	v_and_b32_e32 v253, 0xffff0000, v129
	v_pk_fma_f32 v[138:139], v[42:43], v[250:251], v[138:139]
	v_pk_fma_f32 v[140:141], v[44:45], v[252:253], v[140:141]
	global_store_dwordx4 v194, v[138:141], s[54:55] offset:64
	v_pk_mul_f32 v[38:39], v[246:247], v[38:39] op_sel:[1,0] op_sel_hi:[1,1]
	v_pk_mul_f32 v[40:41], v[246:247], v[40:41] op_sel:[1,0] op_sel_hi:[1,1]
	v_pk_mul_f32 v[38:39], v[74:75], v[38:39]
	v_pk_mul_f32 v[40:41], v[76:77], v[40:41]
	v_mul_f32_e32 v38, v255, v38
	v_mul_f32_e32 v39, v255, v39
	v_mul_f32_e32 v40, v255, v40
	v_mul_f32_e32 v41, v255, v41
	v_exp_f32_e32 v38, v38
	v_exp_f32_e32 v39, v39
	v_exp_f32_e32 v40, v40
	v_exp_f32_e32 v41, v41
	v_add_f32_e32 v38, 1.0, v38
	v_add_f32_e32 v39, 1.0, v39
	v_add_f32_e32 v40, 1.0, v40
	v_add_f32_e32 v41, 1.0, v41
	v_rcp_f32_e32 v38, v38
	v_rcp_f32_e32 v39, v39
	v_rcp_f32_e32 v40, v40
	v_rcp_f32_e32 v41, v41
	s_waitcnt vmcnt(26)
	v_lshlrev_b32_e32 v250, 16, v122
	v_and_b32_e32 v251, 0xffff0000, v122
	v_lshlrev_b32_e32 v252, 16, v123
	v_and_b32_e32 v253, 0xffff0000, v123
	v_pk_fma_f32 v[134:135], v[38:39], v[250:251], v[134:135]
	v_pk_fma_f32 v[136:137], v[40:41], v[252:253], v[136:137]
	global_store_dwordx4 v194, v[134:137], s[54:55] offset:512
	v_pk_mul_f32 v[34:35], v[246:247], v[34:35] op_sel:[1,0] op_sel_hi:[1,1]
	v_pk_mul_f32 v[36:37], v[246:247], v[36:37] op_sel:[1,0] op_sel_hi:[1,1]
	v_pk_mul_f32 v[34:35], v[78:79], v[34:35]
	v_pk_mul_f32 v[36:37], v[80:81], v[36:37]
	v_mul_f32_e32 v34, v255, v34
	v_mul_f32_e32 v35, v255, v35
	v_mul_f32_e32 v36, v255, v36
	v_mul_f32_e32 v37, v255, v37
	v_exp_f32_e32 v34, v34
	v_exp_f32_e32 v35, v35
	v_exp_f32_e32 v36, v36
	v_exp_f32_e32 v37, v37
	v_add_f32_e32 v34, 1.0, v34
	v_add_f32_e32 v35, 1.0, v35
	v_add_f32_e32 v36, 1.0, v36
	v_add_f32_e32 v37, 1.0, v37
	v_rcp_f32_e32 v34, v34
	v_rcp_f32_e32 v35, v35
	v_rcp_f32_e32 v36, v36
	v_rcp_f32_e32 v37, v37
	v_lshlrev_b32_e32 v250, 16, v124
	v_and_b32_e32 v251, 0xffff0000, v124
	v_lshlrev_b32_e32 v252, 16, v125
	v_and_b32_e32 v253, 0xffff0000, v125
	v_pk_fma_f32 v[130:131], v[34:35], v[250:251], v[130:131]
	v_pk_fma_f32 v[132:133], v[36:37], v[252:253], v[132:133]
	global_store_dwordx4 v194, v[130:133], s[54:55] offset:576
	v_add_u32_e32 v194, 0x280000, v190
	v_pk_mul_f32 v[30:31], v[248:249], v[30:31] op_sel:[0,0] op_sel_hi:[0,1]
	v_pk_mul_f32 v[32:33], v[248:249], v[32:33] op_sel:[0,0] op_sel_hi:[0,1]
	v_pk_mul_f32 v[30:31], v[58:59], v[30:31]
	v_pk_mul_f32 v[32:33], v[60:61], v[32:33]
	v_mul_f32_e32 v30, v255, v30
	v_mul_f32_e32 v31, v255, v31
	v_mul_f32_e32 v32, v255, v32
	v_mul_f32_e32 v33, v255, v33
	v_exp_f32_e32 v30, v30
	v_exp_f32_e32 v31, v31
	v_exp_f32_e32 v32, v32
	v_exp_f32_e32 v33, v33
	v_add_f32_e32 v30, 1.0, v30
	v_add_f32_e32 v31, 1.0, v31
	v_add_f32_e32 v32, 1.0, v32
	v_add_f32_e32 v33, 1.0, v33
	v_rcp_f32_e32 v30, v30
	v_rcp_f32_e32 v31, v31
	v_rcp_f32_e32 v32, v32
	v_rcp_f32_e32 v33, v33
	s_waitcnt vmcnt(19)
	v_lshlrev_b32_e32 v250, 16, v234
	v_and_b32_e32 v251, 0xffff0000, v234
	v_lshlrev_b32_e32 v252, 16, v235
	v_and_b32_e32 v253, 0xffff0000, v235
	v_pk_fma_f32 v[218:219], v[30:31], v[250:251], v[218:219]
	v_pk_fma_f32 v[220:221], v[32:33], v[252:253], v[220:221]
	global_store_dwordx4 v194, v[218:221], s[54:55] offset:0
	v_pk_mul_f32 v[26:27], v[248:249], v[26:27] op_sel:[0,0] op_sel_hi:[0,1]
	v_pk_mul_f32 v[28:29], v[248:249], v[28:29] op_sel:[0,0] op_sel_hi:[0,1]
	v_pk_mul_f32 v[26:27], v[66:67], v[26:27]
	v_pk_mul_f32 v[28:29], v[68:69], v[28:29]
	v_mul_f32_e32 v26, v255, v26
	v_mul_f32_e32 v27, v255, v27
	v_mul_f32_e32 v28, v255, v28
	v_mul_f32_e32 v29, v255, v29
	v_exp_f32_e32 v26, v26
	v_exp_f32_e32 v27, v27
	v_exp_f32_e32 v28, v28
	v_exp_f32_e32 v29, v29
	v_add_f32_e32 v26, 1.0, v26
	v_add_f32_e32 v27, 1.0, v27
	v_add_f32_e32 v28, 1.0, v28
	v_add_f32_e32 v29, 1.0, v29
	v_rcp_f32_e32 v26, v26
	v_rcp_f32_e32 v27, v27
	v_rcp_f32_e32 v28, v28
	v_rcp_f32_e32 v29, v29
	v_lshlrev_b32_e32 v250, 16, v236
	v_and_b32_e32 v251, 0xffff0000, v236
	v_lshlrev_b32_e32 v252, 16, v237
	v_and_b32_e32 v253, 0xffff0000, v237
	v_pk_fma_f32 v[222:223], v[26:27], v[250:251], v[222:223]
	v_pk_fma_f32 v[224:225], v[28:29], v[252:253], v[224:225]
	global_store_dwordx4 v194, v[222:225], s[54:55] offset:64
	v_pk_mul_f32 v[22:23], v[248:249], v[22:23] op_sel:[0,0] op_sel_hi:[0,1]
	v_pk_mul_f32 v[24:25], v[248:249], v[24:25] op_sel:[0,0] op_sel_hi:[0,1]
	v_pk_mul_f32 v[22:23], v[74:75], v[22:23]
	v_pk_mul_f32 v[24:25], v[76:77], v[24:25]
	v_mul_f32_e32 v22, v255, v22
	v_mul_f32_e32 v23, v255, v23
	v_mul_f32_e32 v24, v255, v24
	v_mul_f32_e32 v25, v255, v25
	v_exp_f32_e32 v22, v22
	v_exp_f32_e32 v23, v23
	v_exp_f32_e32 v24, v24
	v_exp_f32_e32 v25, v25
	v_add_f32_e32 v22, 1.0, v22
	v_add_f32_e32 v23, 1.0, v23
	v_add_f32_e32 v24, 1.0, v24
	v_add_f32_e32 v25, 1.0, v25
	v_rcp_f32_e32 v22, v22
	v_rcp_f32_e32 v23, v23
	v_rcp_f32_e32 v24, v24
	v_rcp_f32_e32 v25, v25
	s_waitcnt vmcnt(20)
; __device__ __forceinline__ unsigned cvt_pk_bf16(float lo, float hi) { unsigned r; asm volatile("s_nop 0\n\tv_cvt_pk_bf16_f32 %0, %1, %2" : "=v"(r) : "v"(lo), "v"(hi)); return r; }
; __device__ __forceinline__ f32x4 sig4(const f32x4 v) { return (f32x4){sigmoidf_(v[0]), sigmoidf_(v[1]), sigmoidf_(v[2]), sigmoidf_(v[3])}; }
;     __device__ __forceinline__ void operator()(const typename AccT<I8>::type (&acc)[2][2][4][2], const Unit& u, int wr, int wc, int fr, int fq) const {
;     ...
;         for (int s = 0; s < 8; ++s) { const int ai = s >> 2, m = s & 3; const int r = row0 + ai * HALF + m * 16; const size_t off = (size_t)r * 4096 + col0;
;                 if (s + 1 < 8) load_row(nxt, (size_t)(row0 + ((s + 1) >> 2) * HALF + ((s + 1) & 3) * 16) * 4096 + col0);
;                 const float rs = rsv[s];
;                 float ss = 0.f, mx = 0.f;
; #pragma unroll
;                 for (int bj = 0; bj < 2; ++bj)
; #pragma unroll
;                     for (int n = 0; n < 2; ++n) { const size_t o = off + bj * HALF + n * 16; const f32x4 b = cur.b[bj][n]; f32x4 v;
;                         if constexpr (I8) v = __builtin_convertvector(acc[ai][bj][m][n], f32x4) * rs * sv[bj][n]; else v = acc[ai][bj][m][n];
;                         if (MODE == 1) { const u32x2 pw = cur.pw[bj][n]; const f32x4 pp = (f32x4){bf_lo(pw.x), bf_hi(pw.x), bf_lo(pw.y), bf_hi(pw.y)}; v = sig4(I8 ? v : v * rs) * pp; }
;                         const f32x4 x = b + v; *(f32x4*)(out + o) = x;
;                         if (MODE == 0 && XB) { u32x2 w; w.x = cvt_pk_bf16(x[0], x[1]); w.y = cvt_pk_bf16(x[2], x[3]); *(u32x2*)(XB + o) = w; ss += (x[0] * x[0] + x[1] * x[1]) + (x[2] * x[2] + x[3] * x[3]);
;                             if (RM) mx = fmaxf(fmaxf(mx, fmaxf(fabsf(x[0]), fabsf(x[1]))), fmaxf(fabsf(x[2]), fabsf(x[3]))); } }
;                 if (MODE == 0 && XB) { ss += __shfl_xor(ss, 16); ss += __shfl_xor(ss, 32); if (fq == 0) unsafeAtomicAdd(SS + r, ss);
;                     if (RM) { mx = fmaxf(mx, __shfl_xor(mx, 16)); mx = fmaxf(mx, __shfl_xor(mx, 32)); if (fq == 0) atomicMax(RM + r, __builtin_bit_cast(unsigned, mx)); } }
;                 cur = nxt; }
	v_lshlrev_b32_e32 v250, 16, v238
	v_and_b32_e32 v251, 0xffff0000, v238
	v_lshlrev_b32_e32 v252, 16, v239
	v_and_b32_e32 v253, 0xffff0000, v239
	v_pk_fma_f32 v[226:227], v[22:23], v[250:251], v[226:227]
	v_pk_fma_f32 v[228:229], v[24:25], v[252:253], v[228:229]
	global_store_dwordx4 v194, v[226:229], s[54:55] offset:512
	v_pk_mul_f32 v[18:19], v[248:249], v[18:19] op_sel:[0,0] op_sel_hi:[0,1]
	v_pk_mul_f32 v[20:21], v[248:249], v[20:21] op_sel:[0,0] op_sel_hi:[0,1]
	v_pk_mul_f32 v[18:19], v[78:79], v[18:19]
	v_pk_mul_f32 v[20:21], v[80:81], v[20:21]
	v_mul_f32_e32 v18, v255, v18
	v_mul_f32_e32 v19, v255, v19
	v_mul_f32_e32 v20, v255, v20
	v_mul_f32_e32 v21, v255, v21
	v_exp_f32_e32 v18, v18
	v_exp_f32_e32 v19, v19
	v_exp_f32_e32 v20, v20
	v_exp_f32_e32 v21, v21
	v_add_f32_e32 v18, 1.0, v18
	v_add_f32_e32 v19, 1.0, v19
	v_add_f32_e32 v20, 1.0, v20
	v_add_f32_e32 v21, 1.0, v21
	v_rcp_f32_e32 v18, v18
	v_rcp_f32_e32 v19, v19
	v_rcp_f32_e32 v20, v20
	v_rcp_f32_e32 v21, v21
	v_lshlrev_b32_e32 v250, 16, v240
	v_and_b32_e32 v251, 0xffff0000, v240
	v_lshlrev_b32_e32 v252, 16, v241
	v_and_b32_e32 v253, 0xffff0000, v241
	v_pk_fma_f32 v[230:231], v[18:19], v[250:251], v[230:231]
	v_pk_fma_f32 v[232:233], v[20:21], v[252:253], v[232:233]
	global_store_dwordx4 v194, v[230:233], s[54:55] offset:576
	v_add_u32_e32 v194, 0x2c0000, v190
	v_pk_mul_f32 v[14:15], v[248:249], v[14:15] op_sel:[1,0] op_sel_hi:[1,1]
	v_pk_mul_f32 v[16:17], v[248:249], v[16:17] op_sel:[1,0] op_sel_hi:[1,1]
	v_pk_mul_f32 v[14:15], v[58:59], v[14:15]
	v_pk_mul_f32 v[16:17], v[60:61], v[16:17]
	v_mul_f32_e32 v14, v255, v14
	v_mul_f32_e32 v15, v255, v15
	v_mul_f32_e32 v16, v255, v16
	v_mul_f32_e32 v17, v255, v17
	v_exp_f32_e32 v14, v14
	v_exp_f32_e32 v15, v15
	v_exp_f32_e32 v16, v16
	v_exp_f32_e32 v17, v17
	v_add_f32_e32 v14, 1.0, v14
	v_add_f32_e32 v15, 1.0, v15
	v_add_f32_e32 v16, 1.0, v16
	v_add_f32_e32 v17, 1.0, v17
	v_rcp_f32_e32 v14, v14
	v_rcp_f32_e32 v15, v15
	v_rcp_f32_e32 v16, v16
	v_rcp_f32_e32 v17, v17
	s_waitcnt vmcnt(17)
	v_lshlrev_b32_e32 v250, 16, v118
	v_and_b32_e32 v251, 0xffff0000, v118
	v_lshlrev_b32_e32 v252, 16, v119
	v_and_b32_e32 v253, 0xffff0000, v119
	v_pk_fma_f32 v[110:111], v[14:15], v[250:251], v[110:111]
	v_pk_fma_f32 v[112:113], v[16:17], v[252:253], v[112:113]
	global_store_dwordx4 v194, v[110:113], s[54:55] offset:0
	v_pk_mul_f32 v[10:11], v[248:249], v[10:11] op_sel:[1,0] op_sel_hi:[1,1]
	v_pk_mul_f32 v[12:13], v[248:249], v[12:13] op_sel:[1,0] op_sel_hi:[1,1]
	v_pk_mul_f32 v[10:11], v[66:67], v[10:11]
	v_pk_mul_f32 v[12:13], v[68:69], v[12:13]
	v_mul_f32_e32 v10, v255, v10
	v_mul_f32_e32 v11, v255, v11
	v_mul_f32_e32 v12, v255, v12
	v_mul_f32_e32 v13, v255, v13
	v_exp_f32_e32 v10, v10
	v_exp_f32_e32 v11, v11
	v_exp_f32_e32 v12, v12
	v_exp_f32_e32 v13, v13
	v_add_f32_e32 v10, 1.0, v10
	v_add_f32_e32 v11, 1.0, v11
	v_add_f32_e32 v12, 1.0, v12
	v_add_f32_e32 v13, 1.0, v13
	v_rcp_f32_e32 v10, v10
	v_rcp_f32_e32 v11, v11
	v_rcp_f32_e32 v12, v12
	v_rcp_f32_e32 v13, v13
	v_lshlrev_b32_e32 v250, 16, v120
	v_and_b32_e32 v251, 0xffff0000, v120
	v_lshlrev_b32_e32 v252, 16, v121
	v_and_b32_e32 v253, 0xffff0000, v121
	v_pk_fma_f32 v[106:107], v[10:11], v[250:251], v[106:107]
	v_pk_fma_f32 v[108:109], v[12:13], v[252:253], v[108:109]
	global_store_dwordx4 v194, v[106:109], s[54:55] offset:64
	v_pk_mul_f32 v[6:7], v[248:249], v[6:7] op_sel:[1,0] op_sel_hi:[1,1]
	v_pk_mul_f32 v[8:9], v[248:249], v[8:9] op_sel:[1,0] op_sel_hi:[1,1]
	v_pk_mul_f32 v[6:7], v[74:75], v[6:7]
	v_pk_mul_f32 v[8:9], v[76:77], v[8:9]
	v_mul_f32_e32 v6, v255, v6
	v_mul_f32_e32 v7, v255, v7
	v_mul_f32_e32 v8, v255, v8
	v_mul_f32_e32 v9, v255, v9
	v_exp_f32_e32 v6, v6
	v_exp_f32_e32 v7, v7
	v_exp_f32_e32 v8, v8
	v_exp_f32_e32 v9, v9
	v_add_f32_e32 v6, 1.0, v6
	v_add_f32_e32 v7, 1.0, v7
	v_add_f32_e32 v8, 1.0, v8
	v_add_f32_e32 v9, 1.0, v9
	v_rcp_f32_e32 v6, v6
	v_rcp_f32_e32 v7, v7
	v_rcp_f32_e32 v8, v8
	v_rcp_f32_e32 v9, v9
	s_waitcnt vmcnt(18)
	v_lshlrev_b32_e32 v250, 16, v114
	v_and_b32_e32 v251, 0xffff0000, v114
	v_lshlrev_b32_e32 v252, 16, v115
	v_and_b32_e32 v253, 0xffff0000, v115
	v_pk_fma_f32 v[102:103], v[6:7], v[250:251], v[102:103]
	v_pk_fma_f32 v[104:105], v[8:9], v[252:253], v[104:105]
	global_store_dwordx4 v194, v[102:105], s[54:55] offset:512
	v_pk_mul_f32 v[2:3], v[248:249], v[2:3] op_sel:[1,0] op_sel_hi:[1,1]
	v_pk_mul_f32 v[4:5], v[248:249], v[4:5] op_sel:[1,0] op_sel_hi:[1,1]
	v_pk_mul_f32 v[2:3], v[78:79], v[2:3]
	v_pk_mul_f32 v[4:5], v[80:81], v[4:5]
	v_mul_f32_e32 v2, v255, v2
	v_mul_f32_e32 v3, v255, v3
	v_mul_f32_e32 v4, v255, v4
	v_mul_f32_e32 v5, v255, v5
	v_exp_f32_e32 v2, v2
	v_exp_f32_e32 v3, v3
	v_exp_f32_e32 v4, v4
	v_exp_f32_e32 v5, v5
	v_add_f32_e32 v2, 1.0, v2
	v_add_f32_e32 v3, 1.0, v3
	v_add_f32_e32 v4, 1.0, v4
	v_add_f32_e32 v5, 1.0, v5
	v_rcp_f32_e32 v2, v2
	v_rcp_f32_e32 v3, v3
	v_rcp_f32_e32 v4, v4
	v_rcp_f32_e32 v5, v5
	v_lshlrev_b32_e32 v250, 16, v116
	v_and_b32_e32 v251, 0xffff0000, v116
	v_lshlrev_b32_e32 v252, 16, v117
	v_and_b32_e32 v253, 0xffff0000, v117
	v_pk_fma_f32 v[98:99], v[2:3], v[250:251], v[98:99]
	v_pk_fma_f32 v[100:101], v[4:5], v[252:253], v[100:101]
	global_store_dwordx4 v194, v[98:101], s[54:55] offset:576
	v_readlane_b32 s48, v254, 8
	s_mov_b64 s[26:27], s[54:55]
	s_andn2_b64 vcc, exec, s[0:1]
	s_mov_b64 s[0:1], -1
	v_readlane_b32 s49, v254, 9
	v_readlane_b32 s50, v254, 10
	v_readlane_b32 s51, v254, 11
	v_readlane_b32 s52, v254, 12
	v_readlane_b32 s53, v254, 13
	s_cbranch_vccnz .LBB0_2314
	s_andn2_b64 vcc, exec, s[4:5]
	s_cbranch_vccnz .LBB0_2313
	s_barrier
	s_branch .LBB0_2313
